# K-loops of all six GEMMs: LDS-DMA loads use SGPR-base saddr addressing, 16 v_lshl_add_u64 per iteration removed
# speedup vs baseline: 1.0038x; 1.0038x over previous
; #define PG8_STAGE(bufoff, gbase, voff) do { _Pragma("unroll") for (int _i = 0; _i < 2; ++_i) \
;         __builtin_amdgcn_global_load_lds((const unsigned*)((const char*)(gbase) + (voff)[_i]), (PG8_LAS unsigned*)(lds + (bufoff) + ldsw + _i * 8192), 16, 0, 0); } while (0)
; #define PG8_LDA(dst, b, h) do { _Pragma("unroll") for (int m = 0; m < 4; ++m) _Pragma("unroll") for (int k = 0; k < 2; ++k) dst[m][k] = *(const PG8_LAS bf16x8*)(lds + PG8_SA(b, h) + aoff + m * 2048 + k * 1024); } while (0)
; #define PG8_LDB(dst, b, h) do { _Pragma("unroll") for (int n = 0; n < 2; ++n) _Pragma("unroll") for (int k = 0; k < 2; ++k) dst[n][k] = *(const PG8_LAS bf16x8*)(lds + PG8_SB(b, h) + boff + n * 2048 + k * 1024); } while (0)
; #define PG8_WAIT_V(n) asm volatile("s_waitcnt vmcnt(" #n ")" ::: "memory")
; #define PG8_WAIT_L(n) asm volatile("s_waitcnt lgkmcnt(" #n ")" ::: "memory")
; #define PG8_BAR __builtin_amdgcn_s_barrier()
; #define PG8_SCHED __builtin_amdgcn_sched_barrier(0)
; template <class Epi, class Sched, bool ALIGN_EPI = false, bool SP2 = false>
; __device__ __forceinline__ void gemm_phase(PG8_LAS unsigned char* lds, const Gemm g, const Sched& S, const Epi& E, int tid_in) {
;     ...
;             PG8_LDB(B0, 0, 0); PG8_LDB(B1, 0, 1); PG8_SCHED; PG8_LDA(At, 0, 0); PG8_STAGE(PG8_SA(1, 1), a1 + hstepA, voffA);
;             PG8_WAIT_V(8); PG8_WAIT_L(0); PG8_BAR; PG8_MMA(0, 0, At, B0); PG8_MMA(0, 1, At, B1); PG8_BAR; PG8_SCHED;
;             PG8_LDA(At, 0, 1); PG8_STAGE(PG8_SB(0, 0), b2, voffB); PG8_STAGE(PG8_SB(0, 1), b2 + hstep, voffB); PG8_STAGE(PG8_SA(0, 0), a2, voffA);
;             PG8_WAIT_V(8); PG8_WAIT_L(0); PG8_BAR; PG8_MMA(1, 0, At, B0); PG8_MMA(1, 1, At, B1); PG8_BAR; PG8_SCHED;
.LBB0_158:
	ds_read_b128 v[112:115], v200
	ds_read_b128 v[116:119], v200 offset:1024
	ds_read_b128 v[136:139], v200 offset:2048
	ds_read_b128 v[140:143], v200 offset:3072
	ds_read_b128 v[172:175], v201
	ds_read_b128 v[176:179], v201 offset:1024
	ds_read_b128 v[180:183], v201 offset:2048
	ds_read_b128 v[184:187], v201 offset:3072
	s_add_u32 s42, s4, 0x100
	s_addc_u32 s43, s5, 0
	s_cmp_eq_u32 s48, 60
	s_cselect_b32 s47, s1, s43
	s_cselect_b32 s46, s19, s42
	s_cselect_b32 s45, s31, s41
	s_cselect_b32 s44, s33, s35
	s_add_i32 m0, s71, 0xc000
	ds_read_b128 v[188:191], v202
	ds_read_b128 v[192:195], v202 offset:1024
	ds_read_b128 v[208:211], v202 offset:2048
	ds_read_b128 v[212:215], v202 offset:3072
	ds_read_b128 v[216:219], v202 offset:4096
	ds_read_b128 v[220:223], v202 offset:5120
	ds_read_b128 v[224:227], v202 offset:6144
	ds_read_b128 v[228:231], v202 offset:7168
	global_load_lds_dwordx4 v160, s[4:5]
	s_add_i32 m0, s71, 0xe000
	s_nop 0
	global_load_lds_dwordx4 v162, s[4:5]
	s_waitcnt vmcnt(8)
	s_waitcnt lgkmcnt(0)
	s_barrier
	s_setprio 1
	s_waitcnt lgkmcnt(0)
	v_mfma_f32_16x16x32_bf16 v[132:135], v[112:115], v[188:191], v[132:135]
	v_mfma_f32_16x16x32_bf16 v[132:135], v[116:119], v[192:195], v[132:135]
	v_mfma_f32_16x16x32_bf16 v[124:127], v[116:119], v[212:215], v[124:127]
	v_mfma_f32_16x16x32_bf16 v[124:127], v[112:115], v[208:211], v[124:127]
	v_mfma_f32_16x16x32_bf16 v[108:111], v[112:115], v[216:219], v[108:111]
	v_mfma_f32_16x16x32_bf16 v[108:111], v[116:119], v[220:223], v[108:111]
	v_mfma_f32_16x16x32_bf16 v[100:103], v[116:119], v[228:231], v[100:103]
	v_mfma_f32_16x16x32_bf16 v[100:103], v[112:115], v[224:227], v[100:103]
	v_mfma_f32_16x16x32_bf16 v[128:131], v[136:139], v[188:191], v[128:131]
	v_mfma_f32_16x16x32_bf16 v[128:131], v[140:143], v[192:195], v[128:131]
	v_mfma_f32_16x16x32_bf16 v[120:123], v[140:143], v[212:215], v[120:123]
	v_mfma_f32_16x16x32_bf16 v[120:123], v[136:139], v[208:211], v[120:123]
	v_mfma_f32_16x16x32_bf16 v[104:107], v[136:139], v[216:219], v[104:107]
	v_mfma_f32_16x16x32_bf16 v[104:107], v[140:143], v[220:223], v[104:107]
	v_mfma_f32_16x16x32_bf16 v[96:99], v[140:143], v[228:231], v[96:99]
	v_mfma_f32_16x16x32_bf16 v[96:99], v[136:139], v[224:227], v[96:99]
	s_setprio 0
	s_setprio 1
	v_mfma_f32_16x16x32_bf16 v[60:63], v[172:175], v[188:191], v[60:63]
	v_mfma_f32_16x16x32_bf16 v[60:63], v[176:179], v[192:195], v[60:63]
	v_mfma_f32_16x16x32_bf16 v[52:55], v[176:179], v[212:215], v[52:55]
	v_mfma_f32_16x16x32_bf16 v[52:55], v[172:175], v[208:211], v[52:55]
	v_mfma_f32_16x16x32_bf16 v[44:47], v[172:175], v[216:219], v[44:47]
	v_mfma_f32_16x16x32_bf16 v[44:47], v[176:179], v[220:223], v[44:47]
	v_mfma_f32_16x16x32_bf16 v[36:39], v[176:179], v[228:231], v[36:39]
	v_mfma_f32_16x16x32_bf16 v[36:39], v[172:175], v[224:227], v[36:39]
	v_mfma_f32_16x16x32_bf16 v[56:59], v[180:183], v[188:191], v[56:59]
	v_mfma_f32_16x16x32_bf16 v[56:59], v[184:187], v[192:195], v[56:59]
	v_mfma_f32_16x16x32_bf16 v[48:51], v[184:187], v[212:215], v[48:51]
	v_mfma_f32_16x16x32_bf16 v[48:51], v[180:183], v[208:211], v[48:51]
	v_mfma_f32_16x16x32_bf16 v[40:43], v[180:183], v[216:219], v[40:43]
	v_mfma_f32_16x16x32_bf16 v[40:43], v[184:187], v[220:223], v[40:43]
	v_mfma_f32_16x16x32_bf16 v[32:35], v[184:187], v[228:231], v[32:35]
	v_mfma_f32_16x16x32_bf16 v[32:35], v[180:183], v[224:227], v[32:35]
	s_setprio 0
	s_barrier
	s_add_u32 s98, s44, 0x80
	s_addc_u32 s99, s45, 0
	s_add_u32 s100, s46, 0x80
	s_addc_u32 s101, s47, 0
	s_add_i32 s4, s91, s70
	s_mov_b32 m0, s4
	ds_read_b128 v[188:191], v202 offset:16384
	ds_read_b128 v[192:195], v202 offset:17408
	ds_read_b128 v[208:211], v202 offset:18432
	ds_read_b128 v[212:215], v202 offset:19456
	ds_read_b128 v[216:219], v202 offset:20480
	ds_read_b128 v[220:223], v202 offset:21504
	ds_read_b128 v[224:227], v202 offset:22528
	ds_read_b128 v[228:231], v202 offset:23552
	global_load_lds_dwordx4 v146, s[44:45]
	s_add_i32 m0, s4, 0x2000
	s_add_u32 s4, s44, 0x100000
	s_addc_u32 s5, s45, 0
	s_add_i32 s49, s92, s70
	global_load_lds_dwordx4 v150, s[44:45]
	s_mov_b32 m0, s49
	s_nop 0
	global_load_lds_dwordx4 v146, s[4:5]
	s_add_i32 m0, s49, 0x2000
	s_nop 0
	global_load_lds_dwordx4 v150, s[4:5]
	s_mov_b32 m0, s71
	s_nop 0
	global_load_lds_dwordx4 v144, s[46:47]
	s_mov_b32 m0, s72
	s_nop 0
	global_load_lds_dwordx4 v148, s[46:47]
	s_waitcnt vmcnt(8)
	s_waitcnt lgkmcnt(0)
	s_barrier
	s_setprio 1
	s_waitcnt lgkmcnt(0)
	v_mfma_f32_16x16x32_bf16 v[92:95], v[112:115], v[188:191], v[92:95]
	v_mfma_f32_16x16x32_bf16 v[92:95], v[116:119], v[192:195], v[92:95]
	v_mfma_f32_16x16x32_bf16 v[84:87], v[116:119], v[212:215], v[84:87]
	v_mfma_f32_16x16x32_bf16 v[84:87], v[112:115], v[208:211], v[84:87]
	v_mfma_f32_16x16x32_bf16 v[76:79], v[112:115], v[216:219], v[76:79]
	v_mfma_f32_16x16x32_bf16 v[76:79], v[116:119], v[220:223], v[76:79]
	v_mfma_f32_16x16x32_bf16 v[68:71], v[116:119], v[228:231], v[68:71]
	v_mfma_f32_16x16x32_bf16 v[68:71], v[112:115], v[224:227], v[68:71]
	v_mfma_f32_16x16x32_bf16 v[88:91], v[136:139], v[188:191], v[88:91]
	v_mfma_f32_16x16x32_bf16 v[88:91], v[140:143], v[192:195], v[88:91]
	v_mfma_f32_16x16x32_bf16 v[80:83], v[140:143], v[212:215], v[80:83]
	v_mfma_f32_16x16x32_bf16 v[80:83], v[136:139], v[208:211], v[80:83]
	v_mfma_f32_16x16x32_bf16 v[72:75], v[136:139], v[216:219], v[72:75]
	v_mfma_f32_16x16x32_bf16 v[72:75], v[140:143], v[220:223], v[72:75]
	v_mfma_f32_16x16x32_bf16 v[64:67], v[140:143], v[228:231], v[64:67]
	v_mfma_f32_16x16x32_bf16 v[64:67], v[136:139], v[224:227], v[64:67]
	s_setprio 0
	s_setprio 1
	v_mfma_f32_16x16x32_bf16 v[28:31], v[172:175], v[188:191], v[28:31]
	v_mfma_f32_16x16x32_bf16 v[28:31], v[176:179], v[192:195], v[28:31]
	v_mfma_f32_16x16x32_bf16 v[20:23], v[176:179], v[212:215], v[20:23]
	v_mfma_f32_16x16x32_bf16 v[20:23], v[172:175], v[208:211], v[20:23]
	v_mfma_f32_16x16x32_bf16 v[12:15], v[172:175], v[216:219], v[12:15]
	v_mfma_f32_16x16x32_bf16 v[12:15], v[176:179], v[220:223], v[12:15]
	v_mfma_f32_16x16x32_bf16 v[4:7], v[176:179], v[228:231], v[4:7]
	v_mfma_f32_16x16x32_bf16 v[4:7], v[172:175], v[224:227], v[4:7]
	v_mfma_f32_16x16x32_bf16 v[24:27], v[180:183], v[188:191], v[24:27]
	v_mfma_f32_16x16x32_bf16 v[24:27], v[184:187], v[192:195], v[24:27]
	v_mfma_f32_16x16x32_bf16 v[16:19], v[184:187], v[212:215], v[16:19]
	v_mfma_f32_16x16x32_bf16 v[16:19], v[180:183], v[208:211], v[16:19]
	v_mfma_f32_16x16x32_bf16 v[8:11], v[180:183], v[216:219], v[8:11]
	v_mfma_f32_16x16x32_bf16 v[8:11], v[184:187], v[220:223], v[8:11]
	v_mfma_f32_16x16x32_bf16 v[0:3], v[184:187], v[228:231], v[0:3]
	v_mfma_f32_16x16x32_bf16 v[0:3], v[180:183], v[224:227], v[0:3]
	s_setprio 0
	s_barrier
; #define PG8_STAGE(bufoff, gbase, voff) do { _Pragma("unroll") for (int _i = 0; _i < 2; ++_i) \
;         __builtin_amdgcn_global_load_lds((const unsigned*)((const char*)(gbase) + (voff)[_i]), (PG8_LAS unsigned*)(lds + (bufoff) + ldsw + _i * 8192), 16, 0, 0); } while (0)
; #define PG8_LDA(dst, b, h) do { _Pragma("unroll") for (int m = 0; m < 4; ++m) _Pragma("unroll") for (int k = 0; k < 2; ++k) dst[m][k] = *(const PG8_LAS bf16x8*)(lds + PG8_SA(b, h) + aoff + m * 2048 + k * 1024); } while (0)
; #define PG8_LDB(dst, b, h) do { _Pragma("unroll") for (int n = 0; n < 2; ++n) _Pragma("unroll") for (int k = 0; k < 2; ++k) dst[n][k] = *(const PG8_LAS bf16x8*)(lds + PG8_SB(b, h) + boff + n * 2048 + k * 1024); } while (0)
; #define PG8_WAIT_V(n) asm volatile("s_waitcnt vmcnt(" #n ")" ::: "memory")
; #define PG8_WAIT_L(n) asm volatile("s_waitcnt lgkmcnt(" #n ")" ::: "memory")
; #define PG8_BAR __builtin_amdgcn_s_barrier()
; #define PG8_SCHED __builtin_amdgcn_sched_barrier(0)
; template <class Epi, class Sched, bool ALIGN_EPI = false, bool SP2 = false>
; __device__ __forceinline__ void gemm_phase(PG8_LAS unsigned char* lds, const Gemm g, const Sched& S, const Epi& E, int tid_in) {
;     ...
;             PG8_LDB(B0, 1, 0); PG8_LDB(B1, 1, 1); PG8_SCHED; PG8_LDA(At, 1, 0); PG8_STAGE(PG8_SA(0, 1), a2 + hstepA, voffA);
;             PG8_WAIT_V(8); PG8_WAIT_L(0); PG8_BAR; PG8_MMA(0, 0, At, B0); PG8_MMA(0, 1, At, B1); PG8_BAR; PG8_SCHED;
;             PG8_LDA(At, 1, 1); PG8_STAGE(PG8_SB(1, 0), b3, voffB); PG8_STAGE(PG8_SB(1, 1), b3 + hstep, voffB); PG8_STAGE(PG8_SA(1, 0), a3, voffA);
;             PG8_WAIT_V(8); PG8_WAIT_L(0); PG8_BAR; PG8_MMA(1, 0, At, B0); PG8_MMA(1, 1, At, B1); PG8_BAR; PG8_SCHED;
	s_add_i32 s49, 0, 0x18000
	s_add_i32 s50, 0, 0x1c000
	v_add_u32_e32 v140, s49, v197
	v_add_u32_e32 v152, s50, v197
	ds_read_b128 v[112:115], v140
	ds_read_b128 v[116:119], v140 offset:1024
	ds_read_b128 v[136:139], v140 offset:2048
	ds_read_b128 v[140:143], v140 offset:3072
	ds_read_b128 v[172:175], v152
	ds_read_b128 v[176:179], v152 offset:1024
	ds_read_b128 v[180:183], v152 offset:2048
	ds_read_b128 v[184:187], v152 offset:3072
	s_add_u32 s4, s46, 0x8000
	s_addc_u32 s5, s47, 0
	s_mov_b32 m0, s73
	ds_read_b128 v[188:191], v202 offset:32768
	ds_read_b128 v[192:195], v202 offset:33792
	ds_read_b128 v[208:211], v202 offset:34816
	ds_read_b128 v[212:215], v202 offset:35840
	ds_read_b128 v[216:219], v202 offset:36864
	ds_read_b128 v[220:223], v202 offset:37888
	ds_read_b128 v[224:227], v202 offset:38912
	ds_read_b128 v[228:231], v202 offset:39936
	global_load_lds_dwordx4 v144, s[4:5]
	s_mov_b32 m0, s74
	s_nop 0
	global_load_lds_dwordx4 v148, s[4:5]
	s_waitcnt vmcnt(8)
	s_waitcnt lgkmcnt(0)
	s_barrier
	s_setprio 1
	s_waitcnt lgkmcnt(0)
	v_mfma_f32_16x16x32_bf16 v[132:135], v[112:115], v[188:191], v[132:135]
	v_mfma_f32_16x16x32_bf16 v[132:135], v[116:119], v[192:195], v[132:135]
	v_mfma_f32_16x16x32_bf16 v[124:127], v[116:119], v[212:215], v[124:127]
	v_mfma_f32_16x16x32_bf16 v[124:127], v[112:115], v[208:211], v[124:127]
	v_mfma_f32_16x16x32_bf16 v[108:111], v[112:115], v[216:219], v[108:111]
	v_mfma_f32_16x16x32_bf16 v[108:111], v[116:119], v[220:223], v[108:111]
	v_mfma_f32_16x16x32_bf16 v[100:103], v[116:119], v[228:231], v[100:103]
	v_mfma_f32_16x16x32_bf16 v[100:103], v[112:115], v[224:227], v[100:103]
	v_mfma_f32_16x16x32_bf16 v[128:131], v[136:139], v[188:191], v[128:131]
	v_mfma_f32_16x16x32_bf16 v[128:131], v[140:143], v[192:195], v[128:131]
	v_mfma_f32_16x16x32_bf16 v[120:123], v[140:143], v[212:215], v[120:123]
	v_mfma_f32_16x16x32_bf16 v[120:123], v[136:139], v[208:211], v[120:123]
	v_mfma_f32_16x16x32_bf16 v[104:107], v[136:139], v[216:219], v[104:107]
	v_mfma_f32_16x16x32_bf16 v[104:107], v[140:143], v[220:223], v[104:107]
	v_mfma_f32_16x16x32_bf16 v[96:99], v[140:143], v[228:231], v[96:99]
	v_mfma_f32_16x16x32_bf16 v[96:99], v[136:139], v[224:227], v[96:99]
	s_setprio 0
	s_setprio 1
	v_mfma_f32_16x16x32_bf16 v[60:63], v[172:175], v[188:191], v[60:63]
	v_mfma_f32_16x16x32_bf16 v[60:63], v[176:179], v[192:195], v[60:63]
	v_mfma_f32_16x16x32_bf16 v[52:55], v[176:179], v[212:215], v[52:55]
	v_mfma_f32_16x16x32_bf16 v[52:55], v[172:175], v[208:211], v[52:55]
	v_mfma_f32_16x16x32_bf16 v[44:47], v[172:175], v[216:219], v[44:47]
	v_mfma_f32_16x16x32_bf16 v[44:47], v[176:179], v[220:223], v[44:47]
	v_mfma_f32_16x16x32_bf16 v[36:39], v[176:179], v[228:231], v[36:39]
	v_mfma_f32_16x16x32_bf16 v[36:39], v[172:175], v[224:227], v[36:39]
	v_mfma_f32_16x16x32_bf16 v[56:59], v[180:183], v[188:191], v[56:59]
	v_mfma_f32_16x16x32_bf16 v[56:59], v[184:187], v[192:195], v[56:59]
	v_mfma_f32_16x16x32_bf16 v[48:51], v[184:187], v[212:215], v[48:51]
	v_mfma_f32_16x16x32_bf16 v[48:51], v[180:183], v[208:211], v[48:51]
	v_mfma_f32_16x16x32_bf16 v[40:43], v[180:183], v[216:219], v[40:43]
	v_mfma_f32_16x16x32_bf16 v[40:43], v[184:187], v[220:223], v[40:43]
	v_mfma_f32_16x16x32_bf16 v[32:35], v[184:187], v[228:231], v[32:35]
	v_mfma_f32_16x16x32_bf16 v[32:35], v[180:183], v[224:227], v[32:35]
	s_setprio 0
	s_barrier
	s_add_i32 s4, s49, s70
	s_mov_b32 m0, s4
	ds_read_b128 v[188:191], v202 offset:49152
	ds_read_b128 v[192:195], v202 offset:50176
	ds_read_b128 v[208:211], v202 offset:51200
	ds_read_b128 v[212:215], v202 offset:52224
	ds_read_b128 v[216:219], v202 offset:53248
	ds_read_b128 v[220:223], v202 offset:54272
	ds_read_b128 v[224:227], v202 offset:55296
	ds_read_b128 v[228:231], v202 offset:56320
	global_load_lds_dwordx4 v146, s[98:99]
	s_add_i32 m0, s4, 0x2000
	s_add_u32 s4, s44, 0x100080
	s_addc_u32 s5, s45, 0
	s_add_i32 s44, s50, s70
	global_load_lds_dwordx4 v150, s[98:99]
	s_mov_b32 m0, s44
	s_nop 0
	global_load_lds_dwordx4 v146, s[4:5]
	s_add_i32 m0, s44, 0x2000
	s_nop 0
	global_load_lds_dwordx4 v150, s[4:5]
	s_mov_b32 m0, s79
	s_nop 0
	global_load_lds_dwordx4 v144, s[100:101]
	s_mov_b32 m0, s61
	s_nop 0
	global_load_lds_dwordx4 v148, s[100:101]
	s_waitcnt vmcnt(8)
	s_waitcnt lgkmcnt(0)
	s_barrier
	s_setprio 1
	s_waitcnt lgkmcnt(0)
	v_mfma_f32_16x16x32_bf16 v[92:95], v[112:115], v[188:191], v[92:95]
	v_mfma_f32_16x16x32_bf16 v[92:95], v[116:119], v[192:195], v[92:95]
	v_mfma_f32_16x16x32_bf16 v[84:87], v[116:119], v[212:215], v[84:87]
	v_mfma_f32_16x16x32_bf16 v[84:87], v[112:115], v[208:211], v[84:87]
	v_mfma_f32_16x16x32_bf16 v[76:79], v[112:115], v[216:219], v[76:79]
	v_mfma_f32_16x16x32_bf16 v[76:79], v[116:119], v[220:223], v[76:79]
	v_mfma_f32_16x16x32_bf16 v[68:71], v[116:119], v[228:231], v[68:71]
	v_mfma_f32_16x16x32_bf16 v[68:71], v[112:115], v[224:227], v[68:71]
	v_mfma_f32_16x16x32_bf16 v[88:91], v[136:139], v[188:191], v[88:91]
	v_mfma_f32_16x16x32_bf16 v[88:91], v[140:143], v[192:195], v[88:91]
	v_mfma_f32_16x16x32_bf16 v[80:83], v[140:143], v[212:215], v[80:83]
	v_mfma_f32_16x16x32_bf16 v[80:83], v[136:139], v[208:211], v[80:83]
	v_mfma_f32_16x16x32_bf16 v[72:75], v[136:139], v[216:219], v[72:75]
	v_mfma_f32_16x16x32_bf16 v[72:75], v[140:143], v[220:223], v[72:75]
	v_mfma_f32_16x16x32_bf16 v[64:67], v[140:143], v[228:231], v[64:67]
	v_mfma_f32_16x16x32_bf16 v[64:67], v[136:139], v[224:227], v[64:67]
	s_setprio 0
	s_setprio 1
	v_mfma_f32_16x16x32_bf16 v[28:31], v[172:175], v[188:191], v[28:31]
	v_mfma_f32_16x16x32_bf16 v[28:31], v[176:179], v[192:195], v[28:31]
	v_mfma_f32_16x16x32_bf16 v[20:23], v[176:179], v[212:215], v[20:23]
	v_mfma_f32_16x16x32_bf16 v[20:23], v[172:175], v[208:211], v[20:23]
	v_mfma_f32_16x16x32_bf16 v[12:15], v[172:175], v[216:219], v[12:15]
	v_mfma_f32_16x16x32_bf16 v[12:15], v[176:179], v[220:223], v[12:15]
	v_mfma_f32_16x16x32_bf16 v[4:7], v[176:179], v[228:231], v[4:7]
	v_mfma_f32_16x16x32_bf16 v[4:7], v[172:175], v[224:227], v[4:7]
	v_mfma_f32_16x16x32_bf16 v[24:27], v[180:183], v[188:191], v[24:27]
	v_mfma_f32_16x16x32_bf16 v[24:27], v[184:187], v[192:195], v[24:27]
	v_mfma_f32_16x16x32_bf16 v[16:19], v[184:187], v[212:215], v[16:19]
	v_mfma_f32_16x16x32_bf16 v[16:19], v[180:183], v[208:211], v[16:19]
	v_mfma_f32_16x16x32_bf16 v[8:11], v[180:183], v[216:219], v[8:11]
	v_mfma_f32_16x16x32_bf16 v[8:11], v[184:187], v[220:223], v[8:11]
	v_mfma_f32_16x16x32_bf16 v[0:3], v[184:187], v[228:231], v[0:3]
	v_mfma_f32_16x16x32_bf16 v[0:3], v[180:183], v[224:227], v[0:3]
	s_setprio 0
	s_barrier
	s_add_i32 s48, s48, 2
	s_add_u32 s35, s35, 0x100
	s_addc_u32 s41, s41, 0
	s_cmp_gt_u32 s48, 61
	s_mov_b64 s[4:5], s[42:43]
	s_cbranch_scc0 .LBB0_158
	s_and_b64 vcc, exec, s[24:25]
	s_cbranch_vccnz .LBB0_163
	v_lshl_add_u32 v172, s0, 8, v198
	s_cmpk_lg_i32 s40, 0x48
	s_mov_b64 s[4:5], -1
	s_cbranch_scc1 .LBB0_164

; #define PG8_STAGE(bufoff, gbase, voff) do { _Pragma("unroll") for (int _i = 0; _i < 2; ++_i) \
;         __builtin_amdgcn_global_load_lds((const unsigned*)((const char*)(gbase) + (voff)[_i]), (PG8_LAS unsigned*)(lds + (bufoff) + ldsw + _i * 8192), 16, 0, 0); } while (0)
; #define PG8_LDA(dst, b, h) do { _Pragma("unroll") for (int m = 0; m < 4; ++m) _Pragma("unroll") for (int k = 0; k < 2; ++k) dst[m][k] = *(const PG8_LAS bf16x8*)(lds + PG8_SA(b, h) + aoff + m * 2048 + k * 1024); } while (0)
; #define PG8_LDB(dst, b, h) do { _Pragma("unroll") for (int n = 0; n < 2; ++n) _Pragma("unroll") for (int k = 0; k < 2; ++k) dst[n][k] = *(const PG8_LAS bf16x8*)(lds + PG8_SB(b, h) + boff + n * 2048 + k * 1024); } while (0)
; #define PG8_WAIT_V(n) asm volatile("s_waitcnt vmcnt(" #n ")" ::: "memory")
; #define PG8_WAIT_L(n) asm volatile("s_waitcnt lgkmcnt(" #n ")" ::: "memory")
; #define PG8_BAR __builtin_amdgcn_s_barrier()
; #define PG8_SCHED __builtin_amdgcn_sched_barrier(0)
; template <class Epi, class Sched, bool ALIGN_EPI = false, bool SP2 = false>
; __device__ __forceinline__ void gemm_phase(PG8_LAS unsigned char* lds, const Gemm g, const Sched& S, const Epi& E, int tid_in) {
;     ...
;             PG8_LDB(B0, 0, 0); PG8_LDB(B1, 0, 1); PG8_SCHED; PG8_LDA(At, 0, 0); PG8_STAGE(PG8_SA(1, 1), a1 + hstepA, voffA);
;             PG8_WAIT_V(8); PG8_WAIT_L(0); PG8_BAR; PG8_MMA(0, 0, At, B0); PG8_MMA(0, 1, At, B1); PG8_BAR; PG8_SCHED;
;             PG8_LDA(At, 0, 1); PG8_STAGE(PG8_SB(0, 0), b2, voffB); PG8_STAGE(PG8_SB(0, 1), b2 + hstep, voffB); PG8_STAGE(PG8_SA(0, 0), a2, voffA);
;             PG8_WAIT_V(8); PG8_WAIT_L(0); PG8_BAR; PG8_MMA(1, 0, At, B0); PG8_MMA(1, 1, At, B1); PG8_BAR; PG8_SCHED;
.LBB0_927:
	ds_read_b128 v[144:147], v151
	ds_read_b128 v[154:157], v151 offset:1024
	ds_read_b128 v[158:161], v151 offset:2048
	ds_read_b128 v[162:165], v151 offset:3072
	ds_read_b128 v[166:169], v152
	ds_read_b128 v[170:173], v152 offset:1024
	ds_read_b128 v[174:177], v152 offset:2048
	ds_read_b128 v[178:181], v152 offset:3072
	s_add_u32 s24, s22, 0xffe00080
	s_addc_u32 s25, s23, -1
	s_cmpk_eq_i32 s50, 0x7c
	s_cselect_b32 s27, s15, s25
	s_cselect_b32 s26, s46, s24
	s_cselect_b32 s25, s13, s49
	s_cselect_b32 s24, s47, s48
	s_add_i32 m0, s21, 0xc000
	ds_read_b128 v[182:185], v153
	ds_read_b128 v[186:189], v153 offset:1024
	ds_read_b128 v[190:193], v153 offset:2048
	ds_read_b128 v[194:197], v153 offset:3072
	ds_read_b128 v[198:201], v153 offset:4096
	ds_read_b128 v[202:205], v153 offset:5120
	ds_read_b128 v[206:209], v153 offset:6144
	ds_read_b128 v[210:213], v153 offset:7168
	global_load_lds_dwordx4 v136, s[22:23]
	s_add_i32 m0, s21, 0xe000
	s_nop 0
	global_load_lds_dwordx4 v138, s[22:23]
	s_waitcnt vmcnt(8)
	s_waitcnt lgkmcnt(0)
	s_barrier
	s_setprio 1
	s_waitcnt lgkmcnt(0)
	v_mfma_f32_16x16x32_bf16 v[124:127], v[144:147], v[182:185], v[124:127]
	v_mfma_f32_16x16x32_bf16 v[124:127], v[154:157], v[186:189], v[124:127]
	v_mfma_f32_16x16x32_bf16 v[108:111], v[154:157], v[194:197], v[108:111]
	v_mfma_f32_16x16x32_bf16 v[108:111], v[144:147], v[190:193], v[108:111]
	v_mfma_f32_16x16x32_bf16 v[92:95], v[144:147], v[198:201], v[92:95]
	v_mfma_f32_16x16x32_bf16 v[92:95], v[154:157], v[202:205], v[92:95]
	v_mfma_f32_16x16x32_bf16 v[76:79], v[154:157], v[210:213], v[76:79]
	v_mfma_f32_16x16x32_bf16 v[76:79], v[144:147], v[206:209], v[76:79]
	v_mfma_f32_16x16x32_bf16 v[120:123], v[158:161], v[182:185], v[120:123]
	v_mfma_f32_16x16x32_bf16 v[120:123], v[162:165], v[186:189], v[120:123]
	v_mfma_f32_16x16x32_bf16 v[104:107], v[162:165], v[194:197], v[104:107]
	v_mfma_f32_16x16x32_bf16 v[104:107], v[158:161], v[190:193], v[104:107]
	v_mfma_f32_16x16x32_bf16 v[88:91], v[158:161], v[198:201], v[88:91]
	v_mfma_f32_16x16x32_bf16 v[88:91], v[162:165], v[202:205], v[88:91]
	v_mfma_f32_16x16x32_bf16 v[72:75], v[162:165], v[210:213], v[72:75]
	v_mfma_f32_16x16x32_bf16 v[72:75], v[158:161], v[206:209], v[72:75]
	s_setprio 0
	s_setprio 1
	v_mfma_f32_16x16x32_bf16 v[116:119], v[166:169], v[182:185], v[116:119]
	v_mfma_f32_16x16x32_bf16 v[116:119], v[170:173], v[186:189], v[116:119]
	v_mfma_f32_16x16x32_bf16 v[100:103], v[170:173], v[194:197], v[100:103]
	v_mfma_f32_16x16x32_bf16 v[100:103], v[166:169], v[190:193], v[100:103]
	v_mfma_f32_16x16x32_bf16 v[84:87], v[166:169], v[198:201], v[84:87]
	v_mfma_f32_16x16x32_bf16 v[84:87], v[170:173], v[202:205], v[84:87]
	v_mfma_f32_16x16x32_bf16 v[68:71], v[170:173], v[210:213], v[68:71]
	v_mfma_f32_16x16x32_bf16 v[68:71], v[166:169], v[206:209], v[68:71]
	v_mfma_f32_16x16x32_bf16 v[112:115], v[174:177], v[182:185], v[112:115]
	v_mfma_f32_16x16x32_bf16 v[112:115], v[178:181], v[186:189], v[112:115]
	v_mfma_f32_16x16x32_bf16 v[96:99], v[178:181], v[194:197], v[96:99]
	v_mfma_f32_16x16x32_bf16 v[96:99], v[174:177], v[190:193], v[96:99]
	v_mfma_f32_16x16x32_bf16 v[80:83], v[174:177], v[198:201], v[80:83]
	v_mfma_f32_16x16x32_bf16 v[80:83], v[178:181], v[202:205], v[80:83]
	v_mfma_f32_16x16x32_bf16 v[64:67], v[178:181], v[210:213], v[64:67]
	v_mfma_f32_16x16x32_bf16 v[64:67], v[174:177], v[206:209], v[64:67]
	s_setprio 0
	s_barrier
	s_add_u32 s98, s24, 0x80
	s_addc_u32 s99, s25, 0
	s_add_u32 s100, s26, 0x80
	s_addc_u32 s101, s27, 0
	s_add_i32 s51, s43, s34
	s_mov_b32 m0, s51
	ds_read_b128 v[182:185], v153 offset:16384
	ds_read_b128 v[186:189], v153 offset:17408
	ds_read_b128 v[190:193], v153 offset:18432
	ds_read_b128 v[194:197], v153 offset:19456
	ds_read_b128 v[198:201], v153 offset:20480
	ds_read_b128 v[202:205], v153 offset:21504
	ds_read_b128 v[206:209], v153 offset:22528
	ds_read_b128 v[210:213], v153 offset:23552
	global_load_lds_dwordx4 v130, s[24:25]
	s_add_i32 m0, s51, 0x2000
	s_add_u32 s52, s24, 0x200000
	s_addc_u32 s53, s25, 0
	s_add_i32 s51, s44, s34
	global_load_lds_dwordx4 v134, s[24:25]
	s_mov_b32 m0, s51
	s_nop 0
	global_load_lds_dwordx4 v130, s[52:53]
	s_add_i32 m0, s51, 0x2000
	s_nop 0
	global_load_lds_dwordx4 v134, s[52:53]
	s_mov_b32 m0, s21
	s_nop 0
	global_load_lds_dwordx4 v128, s[26:27]
	s_mov_b32 m0, s35
	s_nop 0
	global_load_lds_dwordx4 v132, s[26:27]
	s_waitcnt vmcnt(8)
	s_waitcnt lgkmcnt(0)
	s_barrier
	s_setprio 1
	s_waitcnt lgkmcnt(0)
	v_mfma_f32_16x16x32_bf16 v[60:63], v[144:147], v[182:185], v[60:63]
	v_mfma_f32_16x16x32_bf16 v[60:63], v[154:157], v[186:189], v[60:63]
	v_mfma_f32_16x16x32_bf16 v[44:47], v[154:157], v[194:197], v[44:47]
	v_mfma_f32_16x16x32_bf16 v[44:47], v[144:147], v[190:193], v[44:47]
	v_mfma_f32_16x16x32_bf16 v[28:31], v[144:147], v[198:201], v[28:31]
	v_mfma_f32_16x16x32_bf16 v[28:31], v[154:157], v[202:205], v[28:31]
	v_mfma_f32_16x16x32_bf16 v[12:15], v[154:157], v[210:213], v[12:15]
	v_mfma_f32_16x16x32_bf16 v[12:15], v[144:147], v[206:209], v[12:15]
	v_mfma_f32_16x16x32_bf16 v[56:59], v[158:161], v[182:185], v[56:59]
	v_mfma_f32_16x16x32_bf16 v[56:59], v[162:165], v[186:189], v[56:59]
	v_mfma_f32_16x16x32_bf16 v[40:43], v[162:165], v[194:197], v[40:43]
	v_mfma_f32_16x16x32_bf16 v[40:43], v[158:161], v[190:193], v[40:43]
	v_mfma_f32_16x16x32_bf16 v[24:27], v[158:161], v[198:201], v[24:27]
	v_mfma_f32_16x16x32_bf16 v[24:27], v[162:165], v[202:205], v[24:27]
	v_mfma_f32_16x16x32_bf16 v[8:11], v[162:165], v[210:213], v[8:11]
	v_mfma_f32_16x16x32_bf16 v[8:11], v[158:161], v[206:209], v[8:11]
	s_setprio 0
	s_setprio 1
	v_mfma_f32_16x16x32_bf16 v[52:55], v[166:169], v[182:185], v[52:55]
	v_mfma_f32_16x16x32_bf16 v[52:55], v[170:173], v[186:189], v[52:55]
	v_mfma_f32_16x16x32_bf16 v[36:39], v[170:173], v[194:197], v[36:39]
	v_mfma_f32_16x16x32_bf16 v[36:39], v[166:169], v[190:193], v[36:39]
	v_mfma_f32_16x16x32_bf16 v[20:23], v[166:169], v[198:201], v[20:23]
	v_mfma_f32_16x16x32_bf16 v[20:23], v[170:173], v[202:205], v[20:23]
	v_mfma_f32_16x16x32_bf16 v[4:7], v[170:173], v[210:213], v[4:7]
	v_mfma_f32_16x16x32_bf16 v[4:7], v[166:169], v[206:209], v[4:7]
	v_mfma_f32_16x16x32_bf16 v[48:51], v[174:177], v[182:185], v[48:51]
	v_mfma_f32_16x16x32_bf16 v[48:51], v[178:181], v[186:189], v[48:51]
	v_mfma_f32_16x16x32_bf16 v[32:35], v[178:181], v[194:197], v[32:35]
	v_mfma_f32_16x16x32_bf16 v[32:35], v[174:177], v[190:193], v[32:35]
	v_mfma_f32_16x16x32_bf16 v[16:19], v[174:177], v[198:201], v[16:19]
	v_mfma_f32_16x16x32_bf16 v[16:19], v[178:181], v[202:205], v[16:19]
	v_mfma_f32_16x16x32_bf16 v[0:3], v[178:181], v[210:213], v[0:3]
	v_mfma_f32_16x16x32_bf16 v[0:3], v[174:177], v[206:209], v[0:3]
	s_setprio 0
	s_barrier
; #define PG8_STAGE(bufoff, gbase, voff) do { _Pragma("unroll") for (int _i = 0; _i < 2; ++_i) \
;         __builtin_amdgcn_global_load_lds((const unsigned*)((const char*)(gbase) + (voff)[_i]), (PG8_LAS unsigned*)(lds + (bufoff) + ldsw + _i * 8192), 16, 0, 0); } while (0)
; #define PG8_LDA(dst, b, h) do { _Pragma("unroll") for (int m = 0; m < 4; ++m) _Pragma("unroll") for (int k = 0; k < 2; ++k) dst[m][k] = *(const PG8_LAS bf16x8*)(lds + PG8_SA(b, h) + aoff + m * 2048 + k * 1024); } while (0)
; #define PG8_LDB(dst, b, h) do { _Pragma("unroll") for (int n = 0; n < 2; ++n) _Pragma("unroll") for (int k = 0; k < 2; ++k) dst[n][k] = *(const PG8_LAS bf16x8*)(lds + PG8_SB(b, h) + boff + n * 2048 + k * 1024); } while (0)
; #define PG8_WAIT_V(n) asm volatile("s_waitcnt vmcnt(" #n ")" ::: "memory")
; #define PG8_WAIT_L(n) asm volatile("s_waitcnt lgkmcnt(" #n ")" ::: "memory")
; #define PG8_BAR __builtin_amdgcn_s_barrier()
; #define PG8_SCHED __builtin_amdgcn_sched_barrier(0)
; template <class Epi, class Sched, bool ALIGN_EPI = false, bool SP2 = false>
; __device__ __forceinline__ void gemm_phase(PG8_LAS unsigned char* lds, const Gemm g, const Sched& S, const Epi& E, int tid_in) {
;     ...
;             PG8_LDB(B0, 1, 0); PG8_LDB(B1, 1, 1); PG8_SCHED; PG8_LDA(At, 1, 0); PG8_STAGE(PG8_SA(0, 1), a2 + hstepA, voffA);
;             PG8_WAIT_V(8); PG8_WAIT_L(0); PG8_BAR; PG8_MMA(0, 0, At, B0); PG8_MMA(0, 1, At, B1); PG8_BAR; PG8_SCHED;
;             PG8_LDA(At, 1, 1); PG8_STAGE(PG8_SB(1, 0), b3, voffB); PG8_STAGE(PG8_SB(1, 1), b3 + hstep, voffB); PG8_STAGE(PG8_SA(1, 0), a3, voffA);
;             PG8_WAIT_V(8); PG8_WAIT_L(0); PG8_BAR; PG8_MMA(1, 0, At, B0); PG8_MMA(1, 1, At, B1); PG8_BAR; PG8_SCHED;
	s_add_i32 s51, 0, 0x18000
	s_add_i32 s52, 0, 0x1c000
	v_add_u32_e32 v162, s51, v149
	v_add_u32_e32 v178, s52, v149
	ds_read_b128 v[144:147], v162
	ds_read_b128 v[154:157], v162 offset:1024
	ds_read_b128 v[158:161], v162 offset:2048
	ds_read_b128 v[162:165], v162 offset:3072
	ds_read_b128 v[166:169], v178
	ds_read_b128 v[170:173], v178 offset:1024
	ds_read_b128 v[174:177], v178 offset:2048
	ds_read_b128 v[178:181], v178 offset:3072
	s_add_u32 s26, s26, 0x200000
	s_addc_u32 s27, s27, 0
	s_mov_b32 m0, s36
	ds_read_b128 v[182:185], v153 offset:32768
	ds_read_b128 v[186:189], v153 offset:33792
	ds_read_b128 v[190:193], v153 offset:34816
	ds_read_b128 v[194:197], v153 offset:35840
	ds_read_b128 v[198:201], v153 offset:36864
	ds_read_b128 v[202:205], v153 offset:37888
	ds_read_b128 v[206:209], v153 offset:38912
	ds_read_b128 v[210:213], v153 offset:39936
	global_load_lds_dwordx4 v128, s[26:27]
	s_mov_b32 m0, s37
	s_nop 0
	global_load_lds_dwordx4 v132, s[26:27]
	s_waitcnt vmcnt(8)
	s_waitcnt lgkmcnt(0)
	s_barrier
	s_setprio 1
	s_waitcnt lgkmcnt(0)
	v_mfma_f32_16x16x32_bf16 v[124:127], v[144:147], v[182:185], v[124:127]
	v_mfma_f32_16x16x32_bf16 v[124:127], v[154:157], v[186:189], v[124:127]
	v_mfma_f32_16x16x32_bf16 v[108:111], v[154:157], v[194:197], v[108:111]
	v_mfma_f32_16x16x32_bf16 v[108:111], v[144:147], v[190:193], v[108:111]
	v_mfma_f32_16x16x32_bf16 v[92:95], v[144:147], v[198:201], v[92:95]
	v_mfma_f32_16x16x32_bf16 v[92:95], v[154:157], v[202:205], v[92:95]
	v_mfma_f32_16x16x32_bf16 v[76:79], v[154:157], v[210:213], v[76:79]
	v_mfma_f32_16x16x32_bf16 v[76:79], v[144:147], v[206:209], v[76:79]
	v_mfma_f32_16x16x32_bf16 v[120:123], v[158:161], v[182:185], v[120:123]
	v_mfma_f32_16x16x32_bf16 v[120:123], v[162:165], v[186:189], v[120:123]
	v_mfma_f32_16x16x32_bf16 v[104:107], v[162:165], v[194:197], v[104:107]
	v_mfma_f32_16x16x32_bf16 v[104:107], v[158:161], v[190:193], v[104:107]
	v_mfma_f32_16x16x32_bf16 v[88:91], v[158:161], v[198:201], v[88:91]
	v_mfma_f32_16x16x32_bf16 v[88:91], v[162:165], v[202:205], v[88:91]
	v_mfma_f32_16x16x32_bf16 v[72:75], v[162:165], v[210:213], v[72:75]
	v_mfma_f32_16x16x32_bf16 v[72:75], v[158:161], v[206:209], v[72:75]
	s_setprio 0
	s_setprio 1
	v_mfma_f32_16x16x32_bf16 v[116:119], v[166:169], v[182:185], v[116:119]
	v_mfma_f32_16x16x32_bf16 v[116:119], v[170:173], v[186:189], v[116:119]
	v_mfma_f32_16x16x32_bf16 v[100:103], v[170:173], v[194:197], v[100:103]
	v_mfma_f32_16x16x32_bf16 v[100:103], v[166:169], v[190:193], v[100:103]
	v_mfma_f32_16x16x32_bf16 v[84:87], v[166:169], v[198:201], v[84:87]
	v_mfma_f32_16x16x32_bf16 v[84:87], v[170:173], v[202:205], v[84:87]
	v_mfma_f32_16x16x32_bf16 v[68:71], v[170:173], v[210:213], v[68:71]
	v_mfma_f32_16x16x32_bf16 v[68:71], v[166:169], v[206:209], v[68:71]
	v_mfma_f32_16x16x32_bf16 v[112:115], v[174:177], v[182:185], v[112:115]
	v_mfma_f32_16x16x32_bf16 v[112:115], v[178:181], v[186:189], v[112:115]
	v_mfma_f32_16x16x32_bf16 v[96:99], v[178:181], v[194:197], v[96:99]
	v_mfma_f32_16x16x32_bf16 v[96:99], v[174:177], v[190:193], v[96:99]
	v_mfma_f32_16x16x32_bf16 v[80:83], v[174:177], v[198:201], v[80:83]
	v_mfma_f32_16x16x32_bf16 v[80:83], v[178:181], v[202:205], v[80:83]
	v_mfma_f32_16x16x32_bf16 v[64:67], v[178:181], v[210:213], v[64:67]
	v_mfma_f32_16x16x32_bf16 v[64:67], v[174:177], v[206:209], v[64:67]
	s_setprio 0
	s_barrier
	s_add_i32 s26, s51, s34
	s_mov_b32 m0, s26
	ds_read_b128 v[182:185], v153 offset:49152
	ds_read_b128 v[186:189], v153 offset:50176
	ds_read_b128 v[190:193], v153 offset:51200
	ds_read_b128 v[194:197], v153 offset:52224
	ds_read_b128 v[198:201], v153 offset:53248
	ds_read_b128 v[202:205], v153 offset:54272
	ds_read_b128 v[206:209], v153 offset:55296
	ds_read_b128 v[210:213], v153 offset:56320
	global_load_lds_dwordx4 v130, s[98:99]
	s_add_i32 m0, s26, 0x2000
	s_add_u32 s24, s24, 0x200080
	s_addc_u32 s25, s25, 0
	s_add_i32 s26, s52, s34
	global_load_lds_dwordx4 v134, s[98:99]
	s_mov_b32 m0, s26
	s_nop 0
	global_load_lds_dwordx4 v130, s[24:25]
	s_add_i32 m0, s26, 0x2000
	s_nop 0
	global_load_lds_dwordx4 v134, s[24:25]
	s_mov_b32 m0, s40
	s_nop 0
	global_load_lds_dwordx4 v128, s[100:101]
	s_mov_b32 m0, s41
	s_nop 0
	global_load_lds_dwordx4 v132, s[100:101]
	s_waitcnt vmcnt(8)
	s_waitcnt lgkmcnt(0)
	s_barrier
	s_setprio 1
	s_waitcnt lgkmcnt(0)
	v_mfma_f32_16x16x32_bf16 v[60:63], v[144:147], v[182:185], v[60:63]
	v_mfma_f32_16x16x32_bf16 v[60:63], v[154:157], v[186:189], v[60:63]
	v_mfma_f32_16x16x32_bf16 v[44:47], v[154:157], v[194:197], v[44:47]
	v_mfma_f32_16x16x32_bf16 v[44:47], v[144:147], v[190:193], v[44:47]
	v_mfma_f32_16x16x32_bf16 v[28:31], v[144:147], v[198:201], v[28:31]
	v_mfma_f32_16x16x32_bf16 v[28:31], v[154:157], v[202:205], v[28:31]
	v_mfma_f32_16x16x32_bf16 v[12:15], v[154:157], v[210:213], v[12:15]
	v_mfma_f32_16x16x32_bf16 v[12:15], v[144:147], v[206:209], v[12:15]
	v_mfma_f32_16x16x32_bf16 v[56:59], v[158:161], v[182:185], v[56:59]
	v_mfma_f32_16x16x32_bf16 v[56:59], v[162:165], v[186:189], v[56:59]
	v_mfma_f32_16x16x32_bf16 v[40:43], v[162:165], v[194:197], v[40:43]
	v_mfma_f32_16x16x32_bf16 v[40:43], v[158:161], v[190:193], v[40:43]
	v_mfma_f32_16x16x32_bf16 v[24:27], v[158:161], v[198:201], v[24:27]
	v_mfma_f32_16x16x32_bf16 v[24:27], v[162:165], v[202:205], v[24:27]
	v_mfma_f32_16x16x32_bf16 v[8:11], v[162:165], v[210:213], v[8:11]
	v_mfma_f32_16x16x32_bf16 v[8:11], v[158:161], v[206:209], v[8:11]
	s_setprio 0
	s_setprio 1
	v_mfma_f32_16x16x32_bf16 v[52:55], v[166:169], v[182:185], v[52:55]
	v_mfma_f32_16x16x32_bf16 v[52:55], v[170:173], v[186:189], v[52:55]
	v_mfma_f32_16x16x32_bf16 v[36:39], v[170:173], v[194:197], v[36:39]
	v_mfma_f32_16x16x32_bf16 v[36:39], v[166:169], v[190:193], v[36:39]
	v_mfma_f32_16x16x32_bf16 v[20:23], v[166:169], v[198:201], v[20:23]
	v_mfma_f32_16x16x32_bf16 v[20:23], v[170:173], v[202:205], v[20:23]
	v_mfma_f32_16x16x32_bf16 v[4:7], v[170:173], v[210:213], v[4:7]
	v_mfma_f32_16x16x32_bf16 v[4:7], v[166:169], v[206:209], v[4:7]
	v_mfma_f32_16x16x32_bf16 v[48:51], v[174:177], v[182:185], v[48:51]
	v_mfma_f32_16x16x32_bf16 v[48:51], v[178:181], v[186:189], v[48:51]
	v_mfma_f32_16x16x32_bf16 v[32:35], v[178:181], v[194:197], v[32:35]
	v_mfma_f32_16x16x32_bf16 v[32:35], v[174:177], v[190:193], v[32:35]
	v_mfma_f32_16x16x32_bf16 v[16:19], v[174:177], v[198:201], v[16:19]
	v_mfma_f32_16x16x32_bf16 v[16:19], v[178:181], v[202:205], v[16:19]
	v_mfma_f32_16x16x32_bf16 v[0:3], v[178:181], v[210:213], v[0:3]
	v_mfma_f32_16x16x32_bf16 v[0:3], v[174:177], v[206:209], v[0:3]
	s_setprio 0
	s_barrier
	s_add_i32 s50, s50, 2
	s_add_u32 s22, s22, 0x100
	s_addc_u32 s23, s23, 0
	s_add_u32 s48, s48, 0x100
	s_addc_u32 s49, s49, 0
	s_cmpk_gt_u32 s50, 0x7d
	s_cbranch_scc0 .LBB0_927
	s_and_b64 vcc, exec, s[10:11]
	s_cbranch_vccz .LBB0_930
	s_barrier
; __device__ __forceinline__ float epi_sigmoid(float v) { return __builtin_amdgcn_rcpf(1.0f + __expf(-v)); }
;     __device__ __forceinline__ void operator()(const f32x4 (&acc)[2][2][4][2], const Unit& u, int wr, int wc, int fr, int fq) const {
;         const int row0 = u.pm * BM + wr * 64 + fr, col0 = u.pn * BM + wc * 32 + 8 * fq;
; #pragma unroll
;         for (int ai = 0; ai < 2; ++ai)
; #pragma unroll
;             for (int m = 0; m < 4; ++m) { const size_t row = (size_t)(row0 + ai * HALF + m * 16);
; #pragma unroll
;                 for (int bj = 0; bj < 2; ++bj) { const int col = col0 + bj * HALF; f32x4 g0, g1; ld8bf(gates + row * 8192 + second * 4096 + col, g0, g1);
; #pragma unroll
;                     for (int j = 0; j < 4; ++j) { g0[j] = epi_sigmoid(g0[j]); g1[j] = epi_sigmoid(g1[j]); }
;                     f32x4 v0 = acc[ai][bj][m][0] * g0, v1 = acc[ai][bj][m][1] * g1;
;                     if (second) { f32x4 p0, p1; ld8bf(pm + row * 4096 + col, p0, p1); v0 += p0; v1 += p1; }
;                     st8bf(pm + row * 4096 + col, v0, v1); } }
.LBB0_930:
	v_lshl_add_u32 v146, s20, 8, v148
	v_lshl_or_b32 v144, s45, 8, v150
	v_ashrrev_i32_e32 v147, 31, v146
	v_lshlrev_b64 v[154:155], 14, v[146:147]
	v_ashrrev_i32_e32 v145, 31, v144
	v_lshl_add_u64 v[154:155], s[4:5], 0, v[154:155]
	v_lshlrev_b64 v[144:145], 1, v[144:145]
	v_lshl_add_u64 v[158:159], v[154:155], 0, v[144:145]
	global_load_dwordx4 v[154:157], v[158:159], off
	s_andn2_b64 vcc, exec, s[2:3]
	s_mov_b64 s[2:3], -1
	s_waitcnt vmcnt(0)
	v_lshlrev_b32_e32 v160, 16, v154
	v_and_b32_e32 v154, 0xffff0000, v154
	v_lshlrev_b32_e32 v161, 16, v155
	v_and_b32_e32 v155, 0xffff0000, v155
	v_lshlrev_b32_e32 v162, 16, v156
	v_and_b32_e32 v156, 0xffff0000, v156
	v_lshlrev_b32_e32 v163, 16, v157
	v_and_b32_e32 v157, 0xffff0000, v157
	v_mul_f32_e32 v160, 0xbfb8aa3b, v160
	v_mul_f32_e32 v162, 0xbfb8aa3b, v162
	v_mul_f32_e32 v154, 0xbfb8aa3b, v154
	v_mul_f32_e32 v156, 0xbfb8aa3b, v156
	v_mul_f32_e32 v161, 0xbfb8aa3b, v161
	v_mul_f32_e32 v163, 0xbfb8aa3b, v163
	v_mul_f32_e32 v155, 0xbfb8aa3b, v155
	v_mul_f32_e32 v157, 0xbfb8aa3b, v157
	v_exp_f32_e32 v160, v160
	v_exp_f32_e32 v162, v162
	v_exp_f32_e32 v154, v154
	v_exp_f32_e32 v156, v156
	v_exp_f32_e32 v161, v161
	v_exp_f32_e32 v163, v163
	v_exp_f32_e32 v155, v155
	v_exp_f32_e32 v157, v157
	v_add_f32_e32 v160, 1.0, v160
	v_add_f32_e32 v162, 1.0, v162
	v_add_f32_e32 v164, 1.0, v154
	v_add_f32_e32 v165, 1.0, v156
	v_add_f32_e32 v161, 1.0, v161
	v_add_f32_e32 v163, 1.0, v163
	v_add_f32_e32 v166, 1.0, v155
	v_add_f32_e32 v157, 1.0, v157
	v_rcp_f32_e32 v154, v160
	v_rcp_f32_e32 v156, v162
	v_rcp_f32_e32 v155, v164
	v_rcp_f32_e32 v160, v161
	v_rcp_f32_e32 v161, v166
	v_rcp_f32_e32 v162, v163
	v_rcp_f32_e32 v163, v157
	v_rcp_f32_e32 v157, v165
	v_pk_mul_f32 v[126:127], v[126:127], v[160:161]
	v_pk_mul_f32 v[124:125], v[124:125], v[154:155]
	v_pk_mul_f32 v[154:155], v[122:123], v[162:163]
	v_pk_mul_f32 v[122:123], v[120:121], v[156:157]
	v_cvt_pk_bf16_f32 v120, v124, v125
	v_cvt_pk_bf16_f32 v121, v126, v127
	v_lshlrev_b64 v[156:157], 13, v[146:147]
	v_cvt_pk_bf16_f32 v122, v122, v123
	v_cvt_pk_bf16_f32 v123, v154, v155
	global_load_dwordx4 v[124:127], v[158:159], off offset:256
	v_lshl_add_u64 v[156:157], s[6:7], 0, v[156:157]
	v_lshl_add_u64 v[156:157], v[156:157], 0, v[144:145]
	global_store_dwordx4 v[156:157], v[120:123], off
	v_or_b32_e32 v154, 16, v146
	v_ashrrev_i32_e32 v155, 31, v154
	v_lshlrev_b64 v[158:159], 14, v[154:155]
	v_lshl_add_u64 v[158:159], s[4:5], 0, v[158:159]
	v_lshl_add_u64 v[158:159], v[158:159], 0, v[144:145]
	s_waitcnt vmcnt(1)
	v_lshlrev_b32_e32 v120, 16, v124
	v_and_b32_e32 v121, 0xffff0000, v124
	v_lshlrev_b32_e32 v122, 16, v125
	v_and_b32_e32 v123, 0xffff0000, v125
	v_lshlrev_b32_e32 v124, 16, v126
	v_and_b32_e32 v125, 0xffff0000, v126
	v_lshlrev_b32_e32 v126, 16, v127
	v_and_b32_e32 v127, 0xffff0000, v127
	v_mul_f32_e32 v120, 0xbfb8aa3b, v120
	v_mul_f32_e32 v124, 0xbfb8aa3b, v124
	v_mul_f32_e32 v121, 0xbfb8aa3b, v121
	v_mul_f32_e32 v125, 0xbfb8aa3b, v125
	v_mul_f32_e32 v122, 0xbfb8aa3b, v122
	v_mul_f32_e32 v126, 0xbfb8aa3b, v126
	v_mul_f32_e32 v123, 0xbfb8aa3b, v123
	v_mul_f32_e32 v127, 0xbfb8aa3b, v127
	v_exp_f32_e32 v120, v120
	v_exp_f32_e32 v124, v124
	v_exp_f32_e32 v121, v121
	v_exp_f32_e32 v125, v125
	v_exp_f32_e32 v122, v122
	v_exp_f32_e32 v126, v126
	v_exp_f32_e32 v123, v123
	v_exp_f32_e32 v127, v127
	v_add_f32_e32 v120, 1.0, v120
	v_add_f32_e32 v124, 1.0, v124
	v_add_f32_e32 v121, 1.0, v121
	v_add_f32_e32 v147, 1.0, v125
	v_add_f32_e32 v125, 1.0, v122
	v_add_f32_e32 v126, 1.0, v126
	v_add_f32_e32 v123, 1.0, v123
	v_add_f32_e32 v127, 1.0, v127
	v_rcp_f32_e32 v120, v120
	v_rcp_f32_e32 v122, v124
	v_rcp_f32_e32 v121, v121
	v_rcp_f32_e32 v124, v125
	v_rcp_f32_e32 v125, v123
	v_rcp_f32_e32 v126, v126
	v_rcp_f32_e32 v127, v127
	v_rcp_f32_e32 v123, v147
	v_pk_mul_f32 v[118:119], v[118:119], v[124:125]
	v_pk_mul_f32 v[116:117], v[116:117], v[120:121]
	v_pk_mul_f32 v[120:121], v[114:115], v[126:127]
	v_pk_mul_f32 v[114:115], v[112:113], v[122:123]
	v_cvt_pk_bf16_f32 v112, v116, v117
	v_cvt_pk_bf16_f32 v113, v118, v119
	s_nop 0
	v_cvt_pk_bf16_f32 v114, v114, v115
	v_cvt_pk_bf16_f32 v115, v120, v121
	global_load_dwordx4 v[116:119], v[158:159], off
	s_nop 0
	global_store_dwordx4 v[156:157], v[112:115], off offset:256
	s_waitcnt vmcnt(1)
	s_nop 0
	v_lshlrev_b32_e32 v112, 16, v116
	v_and_b32_e32 v113, 0xffff0000, v116
	v_lshlrev_b32_e32 v114, 16, v117
	v_and_b32_e32 v115, 0xffff0000, v117
	v_lshlrev_b32_e32 v116, 16, v118
	v_and_b32_e32 v117, 0xffff0000, v118
	v_lshlrev_b32_e32 v118, 16, v119
	v_and_b32_e32 v119, 0xffff0000, v119
	v_mul_f32_e32 v112, 0xbfb8aa3b, v112
	v_mul_f32_e32 v116, 0xbfb8aa3b, v116
	v_mul_f32_e32 v113, 0xbfb8aa3b, v113
	v_mul_f32_e32 v117, 0xbfb8aa3b, v117
	v_mul_f32_e32 v114, 0xbfb8aa3b, v114
	v_mul_f32_e32 v118, 0xbfb8aa3b, v118
	v_mul_f32_e32 v115, 0xbfb8aa3b, v115
	v_mul_f32_e32 v119, 0xbfb8aa3b, v119
	v_exp_f32_e32 v112, v112
	v_exp_f32_e32 v116, v116
	v_exp_f32_e32 v113, v113
	v_exp_f32_e32 v117, v117
	v_exp_f32_e32 v114, v114
	v_exp_f32_e32 v118, v118
	v_exp_f32_e32 v115, v115
	v_exp_f32_e32 v119, v119
	v_add_f32_e32 v112, 1.0, v112
	v_add_f32_e32 v116, 1.0, v116
	v_add_f32_e32 v113, 1.0, v113
	v_add_f32_e32 v120, 1.0, v117
	v_add_f32_e32 v117, 1.0, v114
	v_add_f32_e32 v118, 1.0, v118
	v_add_f32_e32 v115, 1.0, v115
	v_add_f32_e32 v119, 1.0, v119
	v_rcp_f32_e32 v112, v112
	v_rcp_f32_e32 v114, v116
	v_rcp_f32_e32 v113, v113
	v_rcp_f32_e32 v116, v117
	v_rcp_f32_e32 v117, v115
	v_rcp_f32_e32 v118, v118
	v_rcp_f32_e32 v119, v119
	v_rcp_f32_e32 v115, v120
	v_pk_mul_f32 v[110:111], v[110:111], v[116:117]
	v_pk_mul_f32 v[108:109], v[108:109], v[112:113]
	v_pk_mul_f32 v[112:113], v[106:107], v[118:119]
	v_pk_mul_f32 v[106:107], v[104:105], v[114:115]
	v_cvt_pk_bf16_f32 v104, v108, v109
	v_cvt_pk_bf16_f32 v105, v110, v111
	v_lshlrev_b64 v[114:115], 13, v[154:155]
	v_cvt_pk_bf16_f32 v106, v106, v107
	v_cvt_pk_bf16_f32 v107, v112, v113
	global_load_dwordx4 v[108:111], v[158:159], off offset:256
	v_lshl_add_u64 v[114:115], s[6:7], 0, v[114:115]
	v_lshl_add_u64 v[114:115], v[114:115], 0, v[144:145]
	global_store_dwordx4 v[114:115], v[104:107], off
	v_or_b32_e32 v112, 32, v146
	v_ashrrev_i32_e32 v113, 31, v112
	v_lshlrev_b64 v[116:117], 14, v[112:113]
	v_lshl_add_u64 v[116:117], s[4:5], 0, v[116:117]
	v_lshl_add_u64 v[116:117], v[116:117], 0, v[144:145]
	s_waitcnt vmcnt(1)
; __device__ __forceinline__ float epi_sigmoid(float v) { return __builtin_amdgcn_rcpf(1.0f + __expf(-v)); }
;     __device__ __forceinline__ void operator()(const f32x4 (&acc)[2][2][4][2], const Unit& u, int wr, int wc, int fr, int fq) const {
;         const int row0 = u.pm * BM + wr * 64 + fr, col0 = u.pn * BM + wc * 32 + 8 * fq;
; #pragma unroll
;         for (int ai = 0; ai < 2; ++ai)
; #pragma unroll
;             for (int m = 0; m < 4; ++m) { const size_t row = (size_t)(row0 + ai * HALF + m * 16);
; #pragma unroll
;                 for (int bj = 0; bj < 2; ++bj) { const int col = col0 + bj * HALF; f32x4 g0, g1; ld8bf(gates + row * 8192 + second * 4096 + col, g0, g1);
; #pragma unroll
;                     for (int j = 0; j < 4; ++j) { g0[j] = epi_sigmoid(g0[j]); g1[j] = epi_sigmoid(g1[j]); }
;                     f32x4 v0 = acc[ai][bj][m][0] * g0, v1 = acc[ai][bj][m][1] * g1;
;                     if (second) { f32x4 p0, p1; ld8bf(pm + row * 4096 + col, p0, p1); v0 += p0; v1 += p1; }
;                     st8bf(pm + row * 4096 + col, v0, v1); } }
	v_lshlrev_b32_e32 v104, 16, v108
	v_and_b32_e32 v105, 0xffff0000, v108
	v_lshlrev_b32_e32 v106, 16, v109
	v_and_b32_e32 v107, 0xffff0000, v109
	v_lshlrev_b32_e32 v108, 16, v110
	v_and_b32_e32 v109, 0xffff0000, v110
	v_lshlrev_b32_e32 v110, 16, v111
	v_and_b32_e32 v111, 0xffff0000, v111
	v_mul_f32_e32 v104, 0xbfb8aa3b, v104
	v_mul_f32_e32 v108, 0xbfb8aa3b, v108
	v_mul_f32_e32 v105, 0xbfb8aa3b, v105
	v_mul_f32_e32 v109, 0xbfb8aa3b, v109
	v_mul_f32_e32 v106, 0xbfb8aa3b, v106
	v_mul_f32_e32 v110, 0xbfb8aa3b, v110
	v_mul_f32_e32 v107, 0xbfb8aa3b, v107
	v_mul_f32_e32 v111, 0xbfb8aa3b, v111
	v_exp_f32_e32 v104, v104
	v_exp_f32_e32 v108, v108
	v_exp_f32_e32 v105, v105
	v_exp_f32_e32 v109, v109
	v_exp_f32_e32 v106, v106
	v_exp_f32_e32 v110, v110
	v_exp_f32_e32 v107, v107
	v_exp_f32_e32 v111, v111
	v_add_f32_e32 v104, 1.0, v104
	v_add_f32_e32 v108, 1.0, v108
	v_add_f32_e32 v105, 1.0, v105
	v_add_f32_e32 v118, 1.0, v109
	v_add_f32_e32 v109, 1.0, v106
	v_add_f32_e32 v110, 1.0, v110
	v_add_f32_e32 v107, 1.0, v107
	v_add_f32_e32 v111, 1.0, v111
	v_rcp_f32_e32 v104, v104
	v_rcp_f32_e32 v106, v108
	v_rcp_f32_e32 v105, v105
	v_rcp_f32_e32 v108, v109
	v_rcp_f32_e32 v109, v107
	v_rcp_f32_e32 v110, v110
	v_rcp_f32_e32 v111, v111
	v_rcp_f32_e32 v107, v118
	v_pk_mul_f32 v[102:103], v[102:103], v[108:109]
	v_pk_mul_f32 v[100:101], v[100:101], v[104:105]
	v_pk_mul_f32 v[104:105], v[98:99], v[110:111]
	v_pk_mul_f32 v[98:99], v[96:97], v[106:107]
	v_cvt_pk_bf16_f32 v96, v100, v101
	v_cvt_pk_bf16_f32 v97, v102, v103
	s_nop 0
	v_cvt_pk_bf16_f32 v98, v98, v99
	v_cvt_pk_bf16_f32 v99, v104, v105
	global_load_dwordx4 v[100:103], v[116:117], off
	s_nop 0
	global_store_dwordx4 v[114:115], v[96:99], off offset:256
	s_waitcnt vmcnt(1)
	s_nop 0
	v_lshlrev_b32_e32 v96, 16, v100
	v_and_b32_e32 v97, 0xffff0000, v100
	v_lshlrev_b32_e32 v98, 16, v101
	v_and_b32_e32 v99, 0xffff0000, v101
	v_lshlrev_b32_e32 v100, 16, v102
	v_and_b32_e32 v101, 0xffff0000, v102
	v_lshlrev_b32_e32 v102, 16, v103
	v_and_b32_e32 v103, 0xffff0000, v103
	v_mul_f32_e32 v96, 0xbfb8aa3b, v96
	v_mul_f32_e32 v100, 0xbfb8aa3b, v100
	v_mul_f32_e32 v97, 0xbfb8aa3b, v97
	v_mul_f32_e32 v101, 0xbfb8aa3b, v101
	v_mul_f32_e32 v98, 0xbfb8aa3b, v98
	v_mul_f32_e32 v102, 0xbfb8aa3b, v102
	v_mul_f32_e32 v99, 0xbfb8aa3b, v99
	v_mul_f32_e32 v103, 0xbfb8aa3b, v103
	v_exp_f32_e32 v96, v96
	v_exp_f32_e32 v100, v100
	v_exp_f32_e32 v97, v97
	v_exp_f32_e32 v101, v101
	v_exp_f32_e32 v98, v98
	v_exp_f32_e32 v102, v102
	v_exp_f32_e32 v99, v99
	v_exp_f32_e32 v103, v103
	v_add_f32_e32 v96, 1.0, v96
	v_add_f32_e32 v100, 1.0, v100
	v_add_f32_e32 v97, 1.0, v97
	v_add_f32_e32 v104, 1.0, v101
	v_add_f32_e32 v101, 1.0, v98
	v_add_f32_e32 v102, 1.0, v102
	v_add_f32_e32 v99, 1.0, v99
	v_add_f32_e32 v103, 1.0, v103
	v_rcp_f32_e32 v96, v96
	v_rcp_f32_e32 v98, v100
	v_rcp_f32_e32 v97, v97
	v_rcp_f32_e32 v100, v101
	v_rcp_f32_e32 v101, v99
	v_rcp_f32_e32 v102, v102
	v_rcp_f32_e32 v103, v103
	v_rcp_f32_e32 v99, v104
	v_pk_mul_f32 v[94:95], v[94:95], v[100:101]
	v_pk_mul_f32 v[92:93], v[92:93], v[96:97]
	v_pk_mul_f32 v[96:97], v[90:91], v[102:103]
	v_pk_mul_f32 v[90:91], v[88:89], v[98:99]
	v_cvt_pk_bf16_f32 v88, v92, v93
	v_cvt_pk_bf16_f32 v89, v94, v95
	v_lshlrev_b64 v[98:99], 13, v[112:113]
	v_cvt_pk_bf16_f32 v90, v90, v91
	v_cvt_pk_bf16_f32 v91, v96, v97
	global_load_dwordx4 v[92:95], v[116:117], off offset:256
	v_lshl_add_u64 v[98:99], s[6:7], 0, v[98:99]
	v_lshl_add_u64 v[98:99], v[98:99], 0, v[144:145]
	global_store_dwordx4 v[98:99], v[88:91], off
	v_or_b32_e32 v96, 48, v146
	v_ashrrev_i32_e32 v97, 31, v96
	v_lshlrev_b64 v[100:101], 14, v[96:97]
	v_lshl_add_u64 v[100:101], s[4:5], 0, v[100:101]
	v_lshl_add_u64 v[100:101], v[100:101], 0, v[144:145]
	s_waitcnt vmcnt(1)
	v_lshlrev_b32_e32 v88, 16, v92
	v_and_b32_e32 v89, 0xffff0000, v92
	v_lshlrev_b32_e32 v90, 16, v93
	v_and_b32_e32 v91, 0xffff0000, v93
	v_lshlrev_b32_e32 v92, 16, v94
	v_and_b32_e32 v93, 0xffff0000, v94
	v_lshlrev_b32_e32 v94, 16, v95
	v_and_b32_e32 v95, 0xffff0000, v95
	v_mul_f32_e32 v88, 0xbfb8aa3b, v88
	v_mul_f32_e32 v92, 0xbfb8aa3b, v92
	v_mul_f32_e32 v89, 0xbfb8aa3b, v89
	v_mul_f32_e32 v93, 0xbfb8aa3b, v93
	v_mul_f32_e32 v90, 0xbfb8aa3b, v90
	v_mul_f32_e32 v94, 0xbfb8aa3b, v94
	v_mul_f32_e32 v91, 0xbfb8aa3b, v91
	v_mul_f32_e32 v95, 0xbfb8aa3b, v95
	v_exp_f32_e32 v88, v88
	v_exp_f32_e32 v92, v92
	v_exp_f32_e32 v89, v89
	v_exp_f32_e32 v93, v93
	v_exp_f32_e32 v90, v90
	v_exp_f32_e32 v94, v94
	v_exp_f32_e32 v91, v91
	v_exp_f32_e32 v95, v95
	v_add_f32_e32 v88, 1.0, v88
	v_add_f32_e32 v92, 1.0, v92
	v_add_f32_e32 v89, 1.0, v89
	v_add_f32_e32 v102, 1.0, v93
	v_add_f32_e32 v93, 1.0, v90
	v_add_f32_e32 v94, 1.0, v94
	v_add_f32_e32 v91, 1.0, v91
	v_add_f32_e32 v95, 1.0, v95
	v_rcp_f32_e32 v88, v88
	v_rcp_f32_e32 v90, v92
	v_rcp_f32_e32 v89, v89
	v_rcp_f32_e32 v92, v93
	v_rcp_f32_e32 v93, v91
	v_rcp_f32_e32 v94, v94
	v_rcp_f32_e32 v95, v95
	v_rcp_f32_e32 v91, v102
	v_pk_mul_f32 v[86:87], v[86:87], v[92:93]
	v_pk_mul_f32 v[84:85], v[84:85], v[88:89]
	v_pk_mul_f32 v[88:89], v[82:83], v[94:95]
	v_pk_mul_f32 v[82:83], v[80:81], v[90:91]
	v_cvt_pk_bf16_f32 v80, v84, v85
	v_cvt_pk_bf16_f32 v81, v86, v87
	s_nop 0
	v_cvt_pk_bf16_f32 v82, v82, v83
	v_cvt_pk_bf16_f32 v83, v88, v89
	global_load_dwordx4 v[84:87], v[100:101], off
	s_nop 0
	global_store_dwordx4 v[98:99], v[80:83], off offset:256
	s_waitcnt vmcnt(1)
; __device__ __forceinline__ float epi_sigmoid(float v) { return __builtin_amdgcn_rcpf(1.0f + __expf(-v)); }
;     __device__ __forceinline__ void operator()(const f32x4 (&acc)[2][2][4][2], const Unit& u, int wr, int wc, int fr, int fq) const {
;         const int row0 = u.pm * BM + wr * 64 + fr, col0 = u.pn * BM + wc * 32 + 8 * fq;
; #pragma unroll
;         for (int ai = 0; ai < 2; ++ai)
; #pragma unroll
;             for (int m = 0; m < 4; ++m) { const size_t row = (size_t)(row0 + ai * HALF + m * 16);
; #pragma unroll
;                 for (int bj = 0; bj < 2; ++bj) { const int col = col0 + bj * HALF; f32x4 g0, g1; ld8bf(gates + row * 8192 + second * 4096 + col, g0, g1);
; #pragma unroll
;                     for (int j = 0; j < 4; ++j) { g0[j] = epi_sigmoid(g0[j]); g1[j] = epi_sigmoid(g1[j]); }
;                     f32x4 v0 = acc[ai][bj][m][0] * g0, v1 = acc[ai][bj][m][1] * g1;
;                     if (second) { f32x4 p0, p1; ld8bf(pm + row * 4096 + col, p0, p1); v0 += p0; v1 += p1; }
;                     st8bf(pm + row * 4096 + col, v0, v1); } }
	s_nop 0
	v_lshlrev_b32_e32 v80, 16, v84
	v_and_b32_e32 v81, 0xffff0000, v84
	v_lshlrev_b32_e32 v82, 16, v85
	v_and_b32_e32 v83, 0xffff0000, v85
	v_lshlrev_b32_e32 v84, 16, v86
	v_and_b32_e32 v85, 0xffff0000, v86
	v_lshlrev_b32_e32 v86, 16, v87
	v_and_b32_e32 v87, 0xffff0000, v87
	v_mul_f32_e32 v80, 0xbfb8aa3b, v80
	v_mul_f32_e32 v84, 0xbfb8aa3b, v84
	v_mul_f32_e32 v81, 0xbfb8aa3b, v81
	v_mul_f32_e32 v85, 0xbfb8aa3b, v85
	v_mul_f32_e32 v82, 0xbfb8aa3b, v82
	v_mul_f32_e32 v86, 0xbfb8aa3b, v86
	v_mul_f32_e32 v83, 0xbfb8aa3b, v83
	v_mul_f32_e32 v87, 0xbfb8aa3b, v87
	v_exp_f32_e32 v80, v80
	v_exp_f32_e32 v84, v84
	v_exp_f32_e32 v81, v81
	v_exp_f32_e32 v85, v85
	v_exp_f32_e32 v82, v82
	v_exp_f32_e32 v86, v86
	v_exp_f32_e32 v83, v83
	v_exp_f32_e32 v87, v87
	v_add_f32_e32 v80, 1.0, v80
	v_add_f32_e32 v84, 1.0, v84
	v_add_f32_e32 v81, 1.0, v81
	v_add_f32_e32 v88, 1.0, v85
	v_add_f32_e32 v85, 1.0, v82
	v_add_f32_e32 v86, 1.0, v86
	v_add_f32_e32 v83, 1.0, v83
	v_add_f32_e32 v87, 1.0, v87
	v_rcp_f32_e32 v80, v80
	v_rcp_f32_e32 v82, v84
	v_rcp_f32_e32 v81, v81
	v_rcp_f32_e32 v84, v85
	v_rcp_f32_e32 v85, v83
	v_rcp_f32_e32 v86, v86
	v_rcp_f32_e32 v87, v87
	v_rcp_f32_e32 v83, v88
	v_pk_mul_f32 v[78:79], v[78:79], v[84:85]
	v_pk_mul_f32 v[76:77], v[76:77], v[80:81]
	v_pk_mul_f32 v[80:81], v[74:75], v[86:87]
	v_pk_mul_f32 v[74:75], v[72:73], v[82:83]
	v_cvt_pk_bf16_f32 v72, v76, v77
	v_cvt_pk_bf16_f32 v73, v78, v79
	v_lshlrev_b64 v[82:83], 13, v[96:97]
	v_cvt_pk_bf16_f32 v74, v74, v75
	v_cvt_pk_bf16_f32 v75, v80, v81
	global_load_dwordx4 v[76:79], v[100:101], off offset:256
	v_lshl_add_u64 v[82:83], s[6:7], 0, v[82:83]
	v_lshl_add_u64 v[82:83], v[82:83], 0, v[144:145]
	global_store_dwordx4 v[82:83], v[72:75], off
	v_add_u32_e32 v80, 0x80, v146
	v_ashrrev_i32_e32 v81, 31, v80
	v_lshlrev_b64 v[84:85], 14, v[80:81]
	v_lshl_add_u64 v[84:85], s[4:5], 0, v[84:85]
	v_lshl_add_u64 v[84:85], v[84:85], 0, v[144:145]
	s_waitcnt vmcnt(1)
	v_lshlrev_b32_e32 v72, 16, v76
	v_and_b32_e32 v73, 0xffff0000, v76
	v_lshlrev_b32_e32 v74, 16, v77
	v_and_b32_e32 v75, 0xffff0000, v77
	v_lshlrev_b32_e32 v76, 16, v78
	v_and_b32_e32 v77, 0xffff0000, v78
	v_lshlrev_b32_e32 v78, 16, v79
	v_and_b32_e32 v79, 0xffff0000, v79
	v_mul_f32_e32 v72, 0xbfb8aa3b, v72
	v_mul_f32_e32 v76, 0xbfb8aa3b, v76
	v_mul_f32_e32 v73, 0xbfb8aa3b, v73
	v_mul_f32_e32 v77, 0xbfb8aa3b, v77
	v_mul_f32_e32 v74, 0xbfb8aa3b, v74
	v_mul_f32_e32 v78, 0xbfb8aa3b, v78
	v_mul_f32_e32 v75, 0xbfb8aa3b, v75
	v_mul_f32_e32 v79, 0xbfb8aa3b, v79
	v_exp_f32_e32 v72, v72
	v_exp_f32_e32 v76, v76
	v_exp_f32_e32 v73, v73
	v_exp_f32_e32 v77, v77
	v_exp_f32_e32 v74, v74
	v_exp_f32_e32 v78, v78
	v_exp_f32_e32 v75, v75
	v_exp_f32_e32 v79, v79
	v_add_f32_e32 v72, 1.0, v72
	v_add_f32_e32 v76, 1.0, v76
	v_add_f32_e32 v73, 1.0, v73
	v_add_f32_e32 v86, 1.0, v77
	v_add_f32_e32 v77, 1.0, v74
	v_add_f32_e32 v78, 1.0, v78
	v_add_f32_e32 v75, 1.0, v75
	v_add_f32_e32 v79, 1.0, v79
	v_rcp_f32_e32 v72, v72
	v_rcp_f32_e32 v74, v76
	v_rcp_f32_e32 v73, v73
	v_rcp_f32_e32 v76, v77
	v_rcp_f32_e32 v77, v75
	v_rcp_f32_e32 v78, v78
	v_rcp_f32_e32 v79, v79
	v_rcp_f32_e32 v75, v86
	v_pk_mul_f32 v[70:71], v[70:71], v[76:77]
	v_pk_mul_f32 v[68:69], v[68:69], v[72:73]
	v_pk_mul_f32 v[72:73], v[66:67], v[78:79]
	v_pk_mul_f32 v[66:67], v[64:65], v[74:75]
	v_cvt_pk_bf16_f32 v64, v68, v69
	v_cvt_pk_bf16_f32 v65, v70, v71
	s_nop 0
	v_cvt_pk_bf16_f32 v66, v66, v67
	v_cvt_pk_bf16_f32 v67, v72, v73
	global_load_dwordx4 v[68:71], v[84:85], off
	s_nop 0
	global_store_dwordx4 v[82:83], v[64:67], off offset:256
	s_waitcnt vmcnt(1)
	s_nop 0
	v_lshlrev_b32_e32 v64, 16, v68
	v_and_b32_e32 v65, 0xffff0000, v68
	v_lshlrev_b32_e32 v66, 16, v69
	v_and_b32_e32 v67, 0xffff0000, v69
	v_lshlrev_b32_e32 v68, 16, v70
	v_and_b32_e32 v69, 0xffff0000, v70
	v_lshlrev_b32_e32 v70, 16, v71
	v_and_b32_e32 v71, 0xffff0000, v71
	v_mul_f32_e32 v64, 0xbfb8aa3b, v64
	v_mul_f32_e32 v68, 0xbfb8aa3b, v68
	v_mul_f32_e32 v65, 0xbfb8aa3b, v65
	v_mul_f32_e32 v69, 0xbfb8aa3b, v69
	v_mul_f32_e32 v66, 0xbfb8aa3b, v66
	v_mul_f32_e32 v70, 0xbfb8aa3b, v70
	v_mul_f32_e32 v67, 0xbfb8aa3b, v67
	v_mul_f32_e32 v71, 0xbfb8aa3b, v71
	v_exp_f32_e32 v64, v64
	v_exp_f32_e32 v68, v68
	v_exp_f32_e32 v65, v65
	v_exp_f32_e32 v69, v69
	v_exp_f32_e32 v66, v66
	v_exp_f32_e32 v70, v70
	v_exp_f32_e32 v67, v67
	v_exp_f32_e32 v71, v71
	v_add_f32_e32 v64, 1.0, v64
	v_add_f32_e32 v68, 1.0, v68
	v_add_f32_e32 v65, 1.0, v65
	v_add_f32_e32 v72, 1.0, v69
	v_add_f32_e32 v69, 1.0, v66
	v_add_f32_e32 v70, 1.0, v70
	v_add_f32_e32 v67, 1.0, v67
	v_add_f32_e32 v71, 1.0, v71
	v_rcp_f32_e32 v64, v64
	v_rcp_f32_e32 v66, v68
	v_rcp_f32_e32 v65, v65
	v_rcp_f32_e32 v68, v69
	v_rcp_f32_e32 v69, v67
	v_rcp_f32_e32 v70, v70
	v_rcp_f32_e32 v71, v71
	v_rcp_f32_e32 v67, v72
	v_pk_mul_f32 v[62:63], v[62:63], v[68:69]
	v_pk_mul_f32 v[60:61], v[60:61], v[64:65]
	v_pk_mul_f32 v[64:65], v[58:59], v[70:71]
	v_pk_mul_f32 v[58:59], v[56:57], v[66:67]
	v_cvt_pk_bf16_f32 v56, v60, v61
	v_cvt_pk_bf16_f32 v57, v62, v63
	v_lshlrev_b64 v[66:67], 13, v[80:81]
	v_cvt_pk_bf16_f32 v58, v58, v59
	v_cvt_pk_bf16_f32 v59, v64, v65
	global_load_dwordx4 v[60:63], v[84:85], off offset:256
	v_lshl_add_u64 v[66:67], s[6:7], 0, v[66:67]
	v_lshl_add_u64 v[66:67], v[66:67], 0, v[144:145]
	global_store_dwordx4 v[66:67], v[56:59], off
	v_add_u32_e32 v64, 0x90, v146
	v_ashrrev_i32_e32 v65, 31, v64
	v_lshlrev_b64 v[68:69], 14, v[64:65]
	v_lshl_add_u64 v[68:69], s[4:5], 0, v[68:69]
	v_lshl_add_u64 v[68:69], v[68:69], 0, v[144:145]
	s_waitcnt vmcnt(1)
; __device__ __forceinline__ float epi_sigmoid(float v) { return __builtin_amdgcn_rcpf(1.0f + __expf(-v)); }
;     __device__ __forceinline__ void operator()(const f32x4 (&acc)[2][2][4][2], const Unit& u, int wr, int wc, int fr, int fq) const {
;         const int row0 = u.pm * BM + wr * 64 + fr, col0 = u.pn * BM + wc * 32 + 8 * fq;
; #pragma unroll
;         for (int ai = 0; ai < 2; ++ai)
; #pragma unroll
;             for (int m = 0; m < 4; ++m) { const size_t row = (size_t)(row0 + ai * HALF + m * 16);
; #pragma unroll
;                 for (int bj = 0; bj < 2; ++bj) { const int col = col0 + bj * HALF; f32x4 g0, g1; ld8bf(gates + row * 8192 + second * 4096 + col, g0, g1);
; #pragma unroll
;                     for (int j = 0; j < 4; ++j) { g0[j] = epi_sigmoid(g0[j]); g1[j] = epi_sigmoid(g1[j]); }
;                     f32x4 v0 = acc[ai][bj][m][0] * g0, v1 = acc[ai][bj][m][1] * g1;
;                     if (second) { f32x4 p0, p1; ld8bf(pm + row * 4096 + col, p0, p1); v0 += p0; v1 += p1; }
;                     st8bf(pm + row * 4096 + col, v0, v1); } }
	v_lshlrev_b32_e32 v56, 16, v60
	v_and_b32_e32 v57, 0xffff0000, v60
	v_lshlrev_b32_e32 v58, 16, v61
	v_and_b32_e32 v59, 0xffff0000, v61
	v_lshlrev_b32_e32 v60, 16, v62
	v_and_b32_e32 v61, 0xffff0000, v62
	v_lshlrev_b32_e32 v62, 16, v63
	v_and_b32_e32 v63, 0xffff0000, v63
	v_mul_f32_e32 v56, 0xbfb8aa3b, v56
	v_mul_f32_e32 v60, 0xbfb8aa3b, v60
	v_mul_f32_e32 v57, 0xbfb8aa3b, v57
	v_mul_f32_e32 v61, 0xbfb8aa3b, v61
	v_mul_f32_e32 v58, 0xbfb8aa3b, v58
	v_mul_f32_e32 v62, 0xbfb8aa3b, v62
	v_mul_f32_e32 v59, 0xbfb8aa3b, v59
	v_mul_f32_e32 v63, 0xbfb8aa3b, v63
	v_exp_f32_e32 v56, v56
	v_exp_f32_e32 v60, v60
	v_exp_f32_e32 v57, v57
	v_exp_f32_e32 v61, v61
	v_exp_f32_e32 v58, v58
	v_exp_f32_e32 v62, v62
	v_exp_f32_e32 v59, v59
	v_exp_f32_e32 v63, v63
	v_add_f32_e32 v56, 1.0, v56
	v_add_f32_e32 v60, 1.0, v60
	v_add_f32_e32 v57, 1.0, v57
	v_add_f32_e32 v70, 1.0, v61
	v_add_f32_e32 v61, 1.0, v58
	v_add_f32_e32 v62, 1.0, v62
	v_add_f32_e32 v59, 1.0, v59
	v_add_f32_e32 v63, 1.0, v63
	v_rcp_f32_e32 v56, v56
	v_rcp_f32_e32 v58, v60
	v_rcp_f32_e32 v57, v57
	v_rcp_f32_e32 v60, v61
	v_rcp_f32_e32 v61, v59
	v_rcp_f32_e32 v62, v62
	v_rcp_f32_e32 v63, v63
	v_rcp_f32_e32 v59, v70
	v_pk_mul_f32 v[54:55], v[54:55], v[60:61]
	v_pk_mul_f32 v[52:53], v[52:53], v[56:57]
	v_pk_mul_f32 v[56:57], v[50:51], v[62:63]
	v_pk_mul_f32 v[50:51], v[48:49], v[58:59]
	v_cvt_pk_bf16_f32 v48, v52, v53
	v_cvt_pk_bf16_f32 v49, v54, v55
	s_nop 0
	v_cvt_pk_bf16_f32 v50, v50, v51
	v_cvt_pk_bf16_f32 v51, v56, v57
	global_load_dwordx4 v[52:55], v[68:69], off
	s_nop 0
	global_store_dwordx4 v[66:67], v[48:51], off offset:256
	s_waitcnt vmcnt(1)
	s_nop 0
	v_lshlrev_b32_e32 v48, 16, v52
	v_and_b32_e32 v49, 0xffff0000, v52
	v_lshlrev_b32_e32 v50, 16, v53
	v_and_b32_e32 v51, 0xffff0000, v53
	v_lshlrev_b32_e32 v52, 16, v54
	v_and_b32_e32 v53, 0xffff0000, v54
	v_lshlrev_b32_e32 v54, 16, v55
	v_and_b32_e32 v55, 0xffff0000, v55
	v_mul_f32_e32 v48, 0xbfb8aa3b, v48
	v_mul_f32_e32 v52, 0xbfb8aa3b, v52
	v_mul_f32_e32 v49, 0xbfb8aa3b, v49
	v_mul_f32_e32 v53, 0xbfb8aa3b, v53
	v_mul_f32_e32 v50, 0xbfb8aa3b, v50
	v_mul_f32_e32 v54, 0xbfb8aa3b, v54
	v_mul_f32_e32 v51, 0xbfb8aa3b, v51
	v_mul_f32_e32 v55, 0xbfb8aa3b, v55
	v_exp_f32_e32 v48, v48
	v_exp_f32_e32 v52, v52
	v_exp_f32_e32 v49, v49
	v_exp_f32_e32 v53, v53
	v_exp_f32_e32 v50, v50
	v_exp_f32_e32 v54, v54
	v_exp_f32_e32 v51, v51
	v_exp_f32_e32 v55, v55
	v_add_f32_e32 v48, 1.0, v48
	v_add_f32_e32 v52, 1.0, v52
	v_add_f32_e32 v49, 1.0, v49
	v_add_f32_e32 v56, 1.0, v53
	v_add_f32_e32 v53, 1.0, v50
	v_add_f32_e32 v54, 1.0, v54
	v_add_f32_e32 v51, 1.0, v51
	v_add_f32_e32 v55, 1.0, v55
	v_rcp_f32_e32 v48, v48
	v_rcp_f32_e32 v50, v52
	v_rcp_f32_e32 v49, v49
	v_rcp_f32_e32 v52, v53
	v_rcp_f32_e32 v53, v51
	v_rcp_f32_e32 v54, v54
	v_rcp_f32_e32 v55, v55
	v_rcp_f32_e32 v51, v56
	v_pk_mul_f32 v[46:47], v[46:47], v[52:53]
	v_pk_mul_f32 v[44:45], v[44:45], v[48:49]
	v_pk_mul_f32 v[48:49], v[42:43], v[54:55]
	v_pk_mul_f32 v[42:43], v[40:41], v[50:51]
	v_cvt_pk_bf16_f32 v40, v44, v45
	v_cvt_pk_bf16_f32 v41, v46, v47
	v_lshlrev_b64 v[50:51], 13, v[64:65]
	v_cvt_pk_bf16_f32 v42, v42, v43
	v_cvt_pk_bf16_f32 v43, v48, v49
	global_load_dwordx4 v[44:47], v[68:69], off offset:256
	v_lshl_add_u64 v[50:51], s[6:7], 0, v[50:51]
	v_lshl_add_u64 v[50:51], v[50:51], 0, v[144:145]
	global_store_dwordx4 v[50:51], v[40:43], off
	v_add_u32_e32 v48, 0xa0, v146
	v_ashrrev_i32_e32 v49, 31, v48
	v_lshlrev_b64 v[52:53], 14, v[48:49]
	v_lshl_add_u64 v[52:53], s[4:5], 0, v[52:53]
	v_lshl_add_u64 v[52:53], v[52:53], 0, v[144:145]
	s_waitcnt vmcnt(1)
	v_lshlrev_b32_e32 v40, 16, v44
	v_and_b32_e32 v41, 0xffff0000, v44
	v_lshlrev_b32_e32 v42, 16, v45
	v_and_b32_e32 v43, 0xffff0000, v45
	v_lshlrev_b32_e32 v44, 16, v46
	v_and_b32_e32 v45, 0xffff0000, v46
	v_lshlrev_b32_e32 v46, 16, v47
	v_and_b32_e32 v47, 0xffff0000, v47
	v_mul_f32_e32 v40, 0xbfb8aa3b, v40
	v_mul_f32_e32 v44, 0xbfb8aa3b, v44
	v_mul_f32_e32 v41, 0xbfb8aa3b, v41
	v_mul_f32_e32 v45, 0xbfb8aa3b, v45
	v_mul_f32_e32 v42, 0xbfb8aa3b, v42
	v_mul_f32_e32 v46, 0xbfb8aa3b, v46
	v_mul_f32_e32 v43, 0xbfb8aa3b, v43
	v_mul_f32_e32 v47, 0xbfb8aa3b, v47
	v_exp_f32_e32 v40, v40
	v_exp_f32_e32 v44, v44
	v_exp_f32_e32 v41, v41
	v_exp_f32_e32 v45, v45
	v_exp_f32_e32 v42, v42
	v_exp_f32_e32 v46, v46
	v_exp_f32_e32 v43, v43
	v_exp_f32_e32 v47, v47
	v_add_f32_e32 v40, 1.0, v40
	v_add_f32_e32 v44, 1.0, v44
	v_add_f32_e32 v41, 1.0, v41
	v_add_f32_e32 v54, 1.0, v45
	v_add_f32_e32 v45, 1.0, v42
	v_add_f32_e32 v46, 1.0, v46
	v_add_f32_e32 v43, 1.0, v43
	v_add_f32_e32 v47, 1.0, v47
	v_rcp_f32_e32 v40, v40
	v_rcp_f32_e32 v42, v44
	v_rcp_f32_e32 v41, v41
	v_rcp_f32_e32 v44, v45
	v_rcp_f32_e32 v45, v43
	v_rcp_f32_e32 v46, v46
	v_rcp_f32_e32 v47, v47
	v_rcp_f32_e32 v43, v54
	v_pk_mul_f32 v[38:39], v[38:39], v[44:45]
	v_pk_mul_f32 v[36:37], v[36:37], v[40:41]
	v_pk_mul_f32 v[40:41], v[34:35], v[46:47]
	v_pk_mul_f32 v[34:35], v[32:33], v[42:43]
	v_cvt_pk_bf16_f32 v32, v36, v37
	v_cvt_pk_bf16_f32 v33, v38, v39
	s_nop 0
	v_cvt_pk_bf16_f32 v34, v34, v35
	v_cvt_pk_bf16_f32 v35, v40, v41
	global_load_dwordx4 v[36:39], v[52:53], off
	s_nop 0
	global_store_dwordx4 v[50:51], v[32:35], off offset:256
	s_waitcnt vmcnt(1)
; __device__ __forceinline__ float epi_sigmoid(float v) { return __builtin_amdgcn_rcpf(1.0f + __expf(-v)); }
;     __device__ __forceinline__ void operator()(const f32x4 (&acc)[2][2][4][2], const Unit& u, int wr, int wc, int fr, int fq) const {
;         const int row0 = u.pm * BM + wr * 64 + fr, col0 = u.pn * BM + wc * 32 + 8 * fq;
; #pragma unroll
;         for (int ai = 0; ai < 2; ++ai)
; #pragma unroll
;             for (int m = 0; m < 4; ++m) { const size_t row = (size_t)(row0 + ai * HALF + m * 16);
; #pragma unroll
;                 for (int bj = 0; bj < 2; ++bj) { const int col = col0 + bj * HALF; f32x4 g0, g1; ld8bf(gates + row * 8192 + second * 4096 + col, g0, g1);
; #pragma unroll
;                     for (int j = 0; j < 4; ++j) { g0[j] = epi_sigmoid(g0[j]); g1[j] = epi_sigmoid(g1[j]); }
;                     f32x4 v0 = acc[ai][bj][m][0] * g0, v1 = acc[ai][bj][m][1] * g1;
;                     if (second) { f32x4 p0, p1; ld8bf(pm + row * 4096 + col, p0, p1); v0 += p0; v1 += p1; }
;                     st8bf(pm + row * 4096 + col, v0, v1); } }
	s_nop 0
	v_lshlrev_b32_e32 v32, 16, v36
	v_and_b32_e32 v33, 0xffff0000, v36
	v_lshlrev_b32_e32 v34, 16, v37
	v_and_b32_e32 v35, 0xffff0000, v37
	v_lshlrev_b32_e32 v36, 16, v38
	v_and_b32_e32 v37, 0xffff0000, v38
	v_lshlrev_b32_e32 v38, 16, v39
	v_and_b32_e32 v39, 0xffff0000, v39
	v_mul_f32_e32 v32, 0xbfb8aa3b, v32
	v_mul_f32_e32 v36, 0xbfb8aa3b, v36
	v_mul_f32_e32 v33, 0xbfb8aa3b, v33
	v_mul_f32_e32 v37, 0xbfb8aa3b, v37
	v_mul_f32_e32 v34, 0xbfb8aa3b, v34
	v_mul_f32_e32 v38, 0xbfb8aa3b, v38
	v_mul_f32_e32 v35, 0xbfb8aa3b, v35
	v_mul_f32_e32 v39, 0xbfb8aa3b, v39
	v_exp_f32_e32 v32, v32
	v_exp_f32_e32 v36, v36
	v_exp_f32_e32 v33, v33
	v_exp_f32_e32 v37, v37
	v_exp_f32_e32 v34, v34
	v_exp_f32_e32 v38, v38
	v_exp_f32_e32 v35, v35
	v_exp_f32_e32 v39, v39
	v_add_f32_e32 v32, 1.0, v32
	v_add_f32_e32 v36, 1.0, v36
	v_add_f32_e32 v33, 1.0, v33
	v_add_f32_e32 v40, 1.0, v37
	v_add_f32_e32 v37, 1.0, v34
	v_add_f32_e32 v38, 1.0, v38
	v_add_f32_e32 v35, 1.0, v35
	v_add_f32_e32 v39, 1.0, v39
	v_rcp_f32_e32 v32, v32
	v_rcp_f32_e32 v34, v36
	v_rcp_f32_e32 v33, v33
	v_rcp_f32_e32 v36, v37
	v_rcp_f32_e32 v37, v35
	v_rcp_f32_e32 v38, v38
	v_rcp_f32_e32 v39, v39
	v_rcp_f32_e32 v35, v40
	v_pk_mul_f32 v[30:31], v[30:31], v[36:37]
	v_pk_mul_f32 v[28:29], v[28:29], v[32:33]
	v_pk_mul_f32 v[32:33], v[26:27], v[38:39]
	v_pk_mul_f32 v[26:27], v[24:25], v[34:35]
	v_cvt_pk_bf16_f32 v24, v28, v29
	v_cvt_pk_bf16_f32 v25, v30, v31
	v_lshlrev_b64 v[34:35], 13, v[48:49]
	v_cvt_pk_bf16_f32 v26, v26, v27
	v_cvt_pk_bf16_f32 v27, v32, v33
	global_load_dwordx4 v[28:31], v[52:53], off offset:256
	v_lshl_add_u64 v[34:35], s[6:7], 0, v[34:35]
	v_lshl_add_u64 v[34:35], v[34:35], 0, v[144:145]
	global_store_dwordx4 v[34:35], v[24:27], off
	v_add_u32_e32 v32, 0xb0, v146
	v_ashrrev_i32_e32 v33, 31, v32
	v_lshlrev_b64 v[36:37], 14, v[32:33]
	v_lshl_add_u64 v[36:37], s[4:5], 0, v[36:37]
	v_lshl_add_u64 v[36:37], v[36:37], 0, v[144:145]
	s_waitcnt vmcnt(1)
	v_lshlrev_b32_e32 v24, 16, v28
	v_and_b32_e32 v25, 0xffff0000, v28
	v_lshlrev_b32_e32 v26, 16, v29
	v_and_b32_e32 v27, 0xffff0000, v29
	v_lshlrev_b32_e32 v28, 16, v30
	v_and_b32_e32 v29, 0xffff0000, v30
	v_lshlrev_b32_e32 v30, 16, v31
	v_and_b32_e32 v31, 0xffff0000, v31
	v_mul_f32_e32 v24, 0xbfb8aa3b, v24
	v_mul_f32_e32 v28, 0xbfb8aa3b, v28
	v_mul_f32_e32 v25, 0xbfb8aa3b, v25
	v_mul_f32_e32 v29, 0xbfb8aa3b, v29
	v_mul_f32_e32 v26, 0xbfb8aa3b, v26
	v_mul_f32_e32 v30, 0xbfb8aa3b, v30
	v_mul_f32_e32 v27, 0xbfb8aa3b, v27
	v_mul_f32_e32 v31, 0xbfb8aa3b, v31
	v_exp_f32_e32 v24, v24
	v_exp_f32_e32 v28, v28
	v_exp_f32_e32 v25, v25
	v_exp_f32_e32 v29, v29
	v_exp_f32_e32 v26, v26
	v_exp_f32_e32 v30, v30
	v_exp_f32_e32 v27, v27
	v_exp_f32_e32 v31, v31
	v_add_f32_e32 v24, 1.0, v24
	v_add_f32_e32 v28, 1.0, v28
	v_add_f32_e32 v25, 1.0, v25
	v_add_f32_e32 v38, 1.0, v29
	v_add_f32_e32 v29, 1.0, v26
	v_add_f32_e32 v30, 1.0, v30
	v_add_f32_e32 v27, 1.0, v27
	v_add_f32_e32 v31, 1.0, v31
	v_rcp_f32_e32 v24, v24
	v_rcp_f32_e32 v26, v28
	v_rcp_f32_e32 v25, v25
	v_rcp_f32_e32 v28, v29
	v_rcp_f32_e32 v29, v27
	v_rcp_f32_e32 v30, v30
	v_rcp_f32_e32 v31, v31
	v_rcp_f32_e32 v27, v38
	v_pk_mul_f32 v[22:23], v[22:23], v[28:29]
	v_pk_mul_f32 v[20:21], v[20:21], v[24:25]
	v_pk_mul_f32 v[24:25], v[18:19], v[30:31]
	v_pk_mul_f32 v[18:19], v[16:17], v[26:27]
	v_cvt_pk_bf16_f32 v16, v20, v21
	v_cvt_pk_bf16_f32 v17, v22, v23
	s_nop 0
	v_cvt_pk_bf16_f32 v18, v18, v19
	v_cvt_pk_bf16_f32 v19, v24, v25
	global_load_dwordx4 v[20:23], v[36:37], off
	s_nop 0
	global_store_dwordx4 v[34:35], v[16:19], off offset:256
	s_waitcnt vmcnt(1)
	s_nop 0
	v_lshlrev_b32_e32 v16, 16, v20
	v_and_b32_e32 v17, 0xffff0000, v20
	v_lshlrev_b32_e32 v18, 16, v21
	v_and_b32_e32 v19, 0xffff0000, v21
	v_lshlrev_b32_e32 v20, 16, v22
	v_and_b32_e32 v21, 0xffff0000, v22
	v_lshlrev_b32_e32 v22, 16, v23
	v_and_b32_e32 v23, 0xffff0000, v23
	v_mul_f32_e32 v16, 0xbfb8aa3b, v16
	v_mul_f32_e32 v20, 0xbfb8aa3b, v20
	v_mul_f32_e32 v17, 0xbfb8aa3b, v17
	v_mul_f32_e32 v21, 0xbfb8aa3b, v21
	v_mul_f32_e32 v18, 0xbfb8aa3b, v18
	v_mul_f32_e32 v22, 0xbfb8aa3b, v22
	v_mul_f32_e32 v19, 0xbfb8aa3b, v19
	v_mul_f32_e32 v23, 0xbfb8aa3b, v23
	v_exp_f32_e32 v16, v16
	v_exp_f32_e32 v20, v20
	v_exp_f32_e32 v17, v17
	v_exp_f32_e32 v21, v21
	v_exp_f32_e32 v18, v18
	v_exp_f32_e32 v22, v22
	v_exp_f32_e32 v19, v19
	v_exp_f32_e32 v23, v23
	v_add_f32_e32 v16, 1.0, v16
	v_add_f32_e32 v20, 1.0, v20
	v_add_f32_e32 v17, 1.0, v17
	v_add_f32_e32 v24, 1.0, v21
	v_add_f32_e32 v21, 1.0, v18
	v_add_f32_e32 v22, 1.0, v22
	v_add_f32_e32 v19, 1.0, v19
	v_add_f32_e32 v23, 1.0, v23
	v_rcp_f32_e32 v16, v16
	v_rcp_f32_e32 v18, v20
	v_rcp_f32_e32 v17, v17
	v_rcp_f32_e32 v20, v21
	v_rcp_f32_e32 v21, v19
	v_rcp_f32_e32 v22, v22
	v_rcp_f32_e32 v23, v23
	v_rcp_f32_e32 v19, v24
	v_pk_mul_f32 v[14:15], v[14:15], v[20:21]
	v_pk_mul_f32 v[12:13], v[12:13], v[16:17]
	v_pk_mul_f32 v[16:17], v[10:11], v[22:23]
	v_pk_mul_f32 v[10:11], v[8:9], v[18:19]
	v_cvt_pk_bf16_f32 v8, v12, v13
	v_cvt_pk_bf16_f32 v9, v14, v15
	s_nop 0
	v_cvt_pk_bf16_f32 v10, v10, v11
	v_cvt_pk_bf16_f32 v11, v16, v17
	global_load_dwordx4 v[12:15], v[36:37], off offset:256
	v_lshlrev_b64 v[16:17], 13, v[32:33]
	v_lshl_add_u64 v[16:17], s[6:7], 0, v[16:17]
	v_lshl_add_u64 v[16:17], v[16:17], 0, v[144:145]
	global_store_dwordx4 v[16:17], v[8:11], off
	s_waitcnt vmcnt(1)
	s_nop 0
	v_lshlrev_b32_e32 v8, 16, v12
	v_and_b32_e32 v9, 0xffff0000, v12
	v_lshlrev_b32_e32 v10, 16, v13
	v_and_b32_e32 v11, 0xffff0000, v13
	v_lshlrev_b32_e32 v12, 16, v14
	v_and_b32_e32 v13, 0xffff0000, v14
	v_lshlrev_b32_e32 v14, 16, v15
	v_and_b32_e32 v15, 0xffff0000, v15
	v_mul_f32_e32 v8, 0xbfb8aa3b, v8
	v_mul_f32_e32 v12, 0xbfb8aa3b, v12
	v_mul_f32_e32 v9, 0xbfb8aa3b, v9
	v_mul_f32_e32 v13, 0xbfb8aa3b, v13
	v_mul_f32_e32 v10, 0xbfb8aa3b, v10
	v_mul_f32_e32 v14, 0xbfb8aa3b, v14
	v_mul_f32_e32 v11, 0xbfb8aa3b, v11
	v_mul_f32_e32 v15, 0xbfb8aa3b, v15
	v_exp_f32_e32 v8, v8
	v_exp_f32_e32 v12, v12
	v_exp_f32_e32 v9, v9
	v_exp_f32_e32 v13, v13
	v_exp_f32_e32 v10, v10
	v_exp_f32_e32 v14, v14
	v_exp_f32_e32 v11, v11
	v_exp_f32_e32 v15, v15
	v_add_f32_e32 v8, 1.0, v8
	v_add_f32_e32 v12, 1.0, v12
	v_add_f32_e32 v9, 1.0, v9
	v_add_f32_e32 v18, 1.0, v13
	v_add_f32_e32 v13, 1.0, v10
	v_add_f32_e32 v14, 1.0, v14
	v_add_f32_e32 v11, 1.0, v11
	v_add_f32_e32 v15, 1.0, v15
	v_rcp_f32_e32 v8, v8
	v_rcp_f32_e32 v10, v12
	v_rcp_f32_e32 v9, v9
	v_rcp_f32_e32 v12, v13
	v_rcp_f32_e32 v13, v11
	v_rcp_f32_e32 v14, v14
	v_rcp_f32_e32 v15, v15
	v_rcp_f32_e32 v11, v18
	v_pk_mul_f32 v[4:5], v[4:5], v[8:9]
	v_pk_mul_f32 v[6:7], v[6:7], v[12:13]
	v_pk_mul_f32 v[8:9], v[2:3], v[14:15]
	v_pk_mul_f32 v[2:3], v[0:1], v[10:11]
	v_cvt_pk_bf16_f32 v0, v4, v5
	v_cvt_pk_bf16_f32 v1, v6, v7
	s_nop 0
	v_cvt_pk_bf16_f32 v2, v2, v3
	v_cvt_pk_bf16_f32 v3, v8, v9
	global_store_dwordx4 v[16:17], v[0:3], off offset:256
	s_cbranch_vccnz .LBB0_919
	s_andn2_b64 vcc, exec, s[0:1]
	s_cbranch_vccnz .LBB0_918
	s_barrier
	s_branch .LBB0_918

; #define PG8_STAGE(bufoff, gbase, voff) do { _Pragma("unroll") for (int _i = 0; _i < 2; ++_i) \
;         __builtin_amdgcn_global_load_lds((const unsigned*)((const char*)(gbase) + (voff)[_i]), (PG8_LAS unsigned*)(lds + (bufoff) + ldsw + _i * 8192), 16, 0, 0); } while (0)
; #define PG8_LDA(dst, b, h) do { _Pragma("unroll") for (int m = 0; m < 4; ++m) _Pragma("unroll") for (int k = 0; k < 2; ++k) dst[m][k] = *(const PG8_LAS bf16x8*)(lds + PG8_SA(b, h) + aoff + m * 2048 + k * 1024); } while (0)
; #define PG8_LDB(dst, b, h) do { _Pragma("unroll") for (int n = 0; n < 2; ++n) _Pragma("unroll") for (int k = 0; k < 2; ++k) dst[n][k] = *(const PG8_LAS bf16x8*)(lds + PG8_SB(b, h) + boff + n * 2048 + k * 1024); } while (0)
; #define PG8_WAIT_V(n) asm volatile("s_waitcnt vmcnt(" #n ")" ::: "memory")
; #define PG8_WAIT_L(n) asm volatile("s_waitcnt lgkmcnt(" #n ")" ::: "memory")
; #define PG8_BAR __builtin_amdgcn_s_barrier()
; #define PG8_SCHED __builtin_amdgcn_sched_barrier(0)
; template <class Epi, class Sched, bool ALIGN_EPI = false, bool SP2 = false>
; __device__ __forceinline__ void gemm_phase(PG8_LAS unsigned char* lds, const Gemm g, const Sched& S, const Epi& E, int tid_in) {
;     ...
;             PG8_LDB(B0, 0, 0); PG8_LDB(B1, 0, 1); PG8_SCHED; PG8_LDA(At, 0, 0); PG8_STAGE(PG8_SA(1, 1), a1 + hstepA, voffA);
;             PG8_WAIT_V(8); PG8_WAIT_L(0); PG8_BAR; PG8_MMA(0, 0, At, B0); PG8_MMA(0, 1, At, B1); PG8_BAR; PG8_SCHED;
;             PG8_LDA(At, 0, 1); PG8_STAGE(PG8_SB(0, 0), b2, voffB); PG8_STAGE(PG8_SB(0, 1), b2 + hstep, voffB); PG8_STAGE(PG8_SA(0, 0), a2, voffA);
;             PG8_WAIT_V(8); PG8_WAIT_L(0); PG8_BAR; PG8_MMA(1, 0, At, B0); PG8_MMA(1, 1, At, B1); PG8_BAR; PG8_SCHED;
.LBB0_952:
	ds_read_b128 v[144:147], v155
	ds_read_b128 v[148:151], v155 offset:1024
	ds_read_b128 v[158:161], v155 offset:2048
	ds_read_b128 v[162:165], v155 offset:3072
	ds_read_b128 v[166:169], v156
	ds_read_b128 v[170:173], v156 offset:1024
	ds_read_b128 v[174:177], v156 offset:2048
	ds_read_b128 v[178:181], v156 offset:3072
	s_add_u32 s28, s26, 0xfff00080
	s_addc_u32 s29, s27, -1
	s_cmp_eq_u32 s54, 60
	s_cselect_b32 s31, s19, s29
	s_cselect_b32 s30, s50, s28
	s_cselect_b32 s29, s17, s53
	s_cselect_b32 s28, s51, s52
	s_add_i32 m0, s25, 0xc000
	ds_read_b128 v[182:185], v157
	ds_read_b128 v[186:189], v157 offset:1024
	ds_read_b128 v[190:193], v157 offset:2048
	ds_read_b128 v[194:197], v157 offset:3072
	ds_read_b128 v[198:201], v157 offset:4096
	ds_read_b128 v[202:205], v157 offset:5120
	ds_read_b128 v[206:209], v157 offset:6144
	ds_read_b128 v[210:213], v157 offset:7168
	global_load_lds_dwordx4 v136, s[26:27]
	s_add_i32 m0, s25, 0xe000
	s_nop 0
	global_load_lds_dwordx4 v138, s[26:27]
	s_waitcnt vmcnt(8)
	s_waitcnt lgkmcnt(0)
	s_barrier
	s_setprio 1
	s_waitcnt lgkmcnt(0)
	v_mfma_f32_16x16x32_bf16 v[124:127], v[144:147], v[182:185], v[124:127]
	v_mfma_f32_16x16x32_bf16 v[124:127], v[148:151], v[186:189], v[124:127]
	v_mfma_f32_16x16x32_bf16 v[108:111], v[148:151], v[194:197], v[108:111]
	v_mfma_f32_16x16x32_bf16 v[108:111], v[144:147], v[190:193], v[108:111]
	v_mfma_f32_16x16x32_bf16 v[92:95], v[144:147], v[198:201], v[92:95]
	v_mfma_f32_16x16x32_bf16 v[92:95], v[148:151], v[202:205], v[92:95]
	v_mfma_f32_16x16x32_bf16 v[76:79], v[148:151], v[210:213], v[76:79]
	v_mfma_f32_16x16x32_bf16 v[76:79], v[144:147], v[206:209], v[76:79]
	v_mfma_f32_16x16x32_bf16 v[120:123], v[158:161], v[182:185], v[120:123]
	v_mfma_f32_16x16x32_bf16 v[120:123], v[162:165], v[186:189], v[120:123]
	v_mfma_f32_16x16x32_bf16 v[104:107], v[162:165], v[194:197], v[104:107]
	v_mfma_f32_16x16x32_bf16 v[104:107], v[158:161], v[190:193], v[104:107]
	v_mfma_f32_16x16x32_bf16 v[88:91], v[158:161], v[198:201], v[88:91]
	v_mfma_f32_16x16x32_bf16 v[88:91], v[162:165], v[202:205], v[88:91]
	v_mfma_f32_16x16x32_bf16 v[72:75], v[162:165], v[210:213], v[72:75]
	v_mfma_f32_16x16x32_bf16 v[72:75], v[158:161], v[206:209], v[72:75]
	s_setprio 0
	s_setprio 1
	v_mfma_f32_16x16x32_bf16 v[116:119], v[166:169], v[182:185], v[116:119]
	v_mfma_f32_16x16x32_bf16 v[116:119], v[170:173], v[186:189], v[116:119]
	v_mfma_f32_16x16x32_bf16 v[100:103], v[170:173], v[194:197], v[100:103]
	v_mfma_f32_16x16x32_bf16 v[100:103], v[166:169], v[190:193], v[100:103]
	v_mfma_f32_16x16x32_bf16 v[84:87], v[166:169], v[198:201], v[84:87]
	v_mfma_f32_16x16x32_bf16 v[84:87], v[170:173], v[202:205], v[84:87]
	v_mfma_f32_16x16x32_bf16 v[68:71], v[170:173], v[210:213], v[68:71]
	v_mfma_f32_16x16x32_bf16 v[68:71], v[166:169], v[206:209], v[68:71]
	v_mfma_f32_16x16x32_bf16 v[112:115], v[174:177], v[182:185], v[112:115]
	v_mfma_f32_16x16x32_bf16 v[112:115], v[178:181], v[186:189], v[112:115]
	v_mfma_f32_16x16x32_bf16 v[96:99], v[178:181], v[194:197], v[96:99]
	v_mfma_f32_16x16x32_bf16 v[96:99], v[174:177], v[190:193], v[96:99]
	v_mfma_f32_16x16x32_bf16 v[80:83], v[174:177], v[198:201], v[80:83]
	v_mfma_f32_16x16x32_bf16 v[80:83], v[178:181], v[202:205], v[80:83]
	v_mfma_f32_16x16x32_bf16 v[64:67], v[178:181], v[210:213], v[64:67]
	v_mfma_f32_16x16x32_bf16 v[64:67], v[174:177], v[206:209], v[64:67]
	s_setprio 0
	s_barrier
	s_add_u32 s98, s28, 0x80
	s_addc_u32 s99, s29, 0
	s_add_u32 s100, s30, 0x80
	s_addc_u32 s101, s31, 0
	s_add_i32 s55, s47, s38
	s_mov_b32 m0, s55
	ds_read_b128 v[182:185], v157 offset:16384
	ds_read_b128 v[186:189], v157 offset:17408
	ds_read_b128 v[190:193], v157 offset:18432
	ds_read_b128 v[194:197], v157 offset:19456
	ds_read_b128 v[198:201], v157 offset:20480
	ds_read_b128 v[202:205], v157 offset:21504
	ds_read_b128 v[206:209], v157 offset:22528
	ds_read_b128 v[210:213], v157 offset:23552
	global_load_lds_dwordx4 v130, s[28:29]
	s_add_i32 m0, s55, 0x2000
	s_add_u32 s56, s28, 0x100000
	s_addc_u32 s57, s29, 0
	s_add_i32 s55, s48, s38
	global_load_lds_dwordx4 v134, s[28:29]
	s_mov_b32 m0, s55
	s_nop 0
	global_load_lds_dwordx4 v130, s[56:57]
	s_add_i32 m0, s55, 0x2000
	s_nop 0
	global_load_lds_dwordx4 v134, s[56:57]
	s_mov_b32 m0, s25
	s_nop 0
	global_load_lds_dwordx4 v128, s[30:31]
	s_mov_b32 m0, s39
	s_nop 0
	global_load_lds_dwordx4 v132, s[30:31]
	s_waitcnt vmcnt(8)
	s_waitcnt lgkmcnt(0)
	s_barrier
	s_setprio 1
	s_waitcnt lgkmcnt(0)
	v_mfma_f32_16x16x32_bf16 v[60:63], v[144:147], v[182:185], v[60:63]
	v_mfma_f32_16x16x32_bf16 v[60:63], v[148:151], v[186:189], v[60:63]
	v_mfma_f32_16x16x32_bf16 v[44:47], v[148:151], v[194:197], v[44:47]
	v_mfma_f32_16x16x32_bf16 v[44:47], v[144:147], v[190:193], v[44:47]
	v_mfma_f32_16x16x32_bf16 v[28:31], v[144:147], v[198:201], v[28:31]
	v_mfma_f32_16x16x32_bf16 v[28:31], v[148:151], v[202:205], v[28:31]
	v_mfma_f32_16x16x32_bf16 v[12:15], v[148:151], v[210:213], v[12:15]
	v_mfma_f32_16x16x32_bf16 v[12:15], v[144:147], v[206:209], v[12:15]
	v_mfma_f32_16x16x32_bf16 v[56:59], v[158:161], v[182:185], v[56:59]
	v_mfma_f32_16x16x32_bf16 v[56:59], v[162:165], v[186:189], v[56:59]
	v_mfma_f32_16x16x32_bf16 v[40:43], v[162:165], v[194:197], v[40:43]
	v_mfma_f32_16x16x32_bf16 v[40:43], v[158:161], v[190:193], v[40:43]
	v_mfma_f32_16x16x32_bf16 v[24:27], v[158:161], v[198:201], v[24:27]
	v_mfma_f32_16x16x32_bf16 v[24:27], v[162:165], v[202:205], v[24:27]
	v_mfma_f32_16x16x32_bf16 v[8:11], v[162:165], v[210:213], v[8:11]
	v_mfma_f32_16x16x32_bf16 v[8:11], v[158:161], v[206:209], v[8:11]
	s_setprio 0
	s_setprio 1
	v_mfma_f32_16x16x32_bf16 v[52:55], v[166:169], v[182:185], v[52:55]
	v_mfma_f32_16x16x32_bf16 v[52:55], v[170:173], v[186:189], v[52:55]
	v_mfma_f32_16x16x32_bf16 v[36:39], v[170:173], v[194:197], v[36:39]
	v_mfma_f32_16x16x32_bf16 v[36:39], v[166:169], v[190:193], v[36:39]
	v_mfma_f32_16x16x32_bf16 v[20:23], v[166:169], v[198:201], v[20:23]
	v_mfma_f32_16x16x32_bf16 v[20:23], v[170:173], v[202:205], v[20:23]
	v_mfma_f32_16x16x32_bf16 v[4:7], v[170:173], v[210:213], v[4:7]
	v_mfma_f32_16x16x32_bf16 v[4:7], v[166:169], v[206:209], v[4:7]
	v_mfma_f32_16x16x32_bf16 v[48:51], v[174:177], v[182:185], v[48:51]
	v_mfma_f32_16x16x32_bf16 v[48:51], v[178:181], v[186:189], v[48:51]
	v_mfma_f32_16x16x32_bf16 v[32:35], v[178:181], v[194:197], v[32:35]
	v_mfma_f32_16x16x32_bf16 v[32:35], v[174:177], v[190:193], v[32:35]
	v_mfma_f32_16x16x32_bf16 v[16:19], v[174:177], v[198:201], v[16:19]
	v_mfma_f32_16x16x32_bf16 v[16:19], v[178:181], v[202:205], v[16:19]
	v_mfma_f32_16x16x32_bf16 v[0:3], v[178:181], v[210:213], v[0:3]
	v_mfma_f32_16x16x32_bf16 v[0:3], v[174:177], v[206:209], v[0:3]
	s_setprio 0
	s_barrier
; #define PG8_STAGE(bufoff, gbase, voff) do { _Pragma("unroll") for (int _i = 0; _i < 2; ++_i) \
;         __builtin_amdgcn_global_load_lds((const unsigned*)((const char*)(gbase) + (voff)[_i]), (PG8_LAS unsigned*)(lds + (bufoff) + ldsw + _i * 8192), 16, 0, 0); } while (0)
; #define PG8_LDA(dst, b, h) do { _Pragma("unroll") for (int m = 0; m < 4; ++m) _Pragma("unroll") for (int k = 0; k < 2; ++k) dst[m][k] = *(const PG8_LAS bf16x8*)(lds + PG8_SA(b, h) + aoff + m * 2048 + k * 1024); } while (0)
; #define PG8_LDB(dst, b, h) do { _Pragma("unroll") for (int n = 0; n < 2; ++n) _Pragma("unroll") for (int k = 0; k < 2; ++k) dst[n][k] = *(const PG8_LAS bf16x8*)(lds + PG8_SB(b, h) + boff + n * 2048 + k * 1024); } while (0)
; #define PG8_WAIT_V(n) asm volatile("s_waitcnt vmcnt(" #n ")" ::: "memory")
; #define PG8_WAIT_L(n) asm volatile("s_waitcnt lgkmcnt(" #n ")" ::: "memory")
; #define PG8_BAR __builtin_amdgcn_s_barrier()
; #define PG8_SCHED __builtin_amdgcn_sched_barrier(0)
; template <class Epi, class Sched, bool ALIGN_EPI = false, bool SP2 = false>
; __device__ __forceinline__ void gemm_phase(PG8_LAS unsigned char* lds, const Gemm g, const Sched& S, const Epi& E, int tid_in) {
;     ...
;             PG8_LDB(B0, 1, 0); PG8_LDB(B1, 1, 1); PG8_SCHED; PG8_LDA(At, 1, 0); PG8_STAGE(PG8_SA(0, 1), a2 + hstepA, voffA);
;             PG8_WAIT_V(8); PG8_WAIT_L(0); PG8_BAR; PG8_MMA(0, 0, At, B0); PG8_MMA(0, 1, At, B1); PG8_BAR; PG8_SCHED;
;             PG8_LDA(At, 1, 1); PG8_STAGE(PG8_SB(1, 0), b3, voffB); PG8_STAGE(PG8_SB(1, 1), b3 + hstep, voffB); PG8_STAGE(PG8_SA(1, 0), a3, voffA);
;             PG8_WAIT_V(8); PG8_WAIT_L(0); PG8_BAR; PG8_MMA(1, 0, At, B0); PG8_MMA(1, 1, At, B1); PG8_BAR; PG8_SCHED;
	s_add_i32 s55, 0, 0x18000
	s_add_i32 s56, 0, 0x1c000
	v_add_u32_e32 v162, s55, v153
	v_add_u32_e32 v178, s56, v153
	ds_read_b128 v[144:147], v162
	ds_read_b128 v[148:151], v162 offset:1024
	ds_read_b128 v[158:161], v162 offset:2048
	ds_read_b128 v[162:165], v162 offset:3072
	ds_read_b128 v[166:169], v178
	ds_read_b128 v[170:173], v178 offset:1024
	ds_read_b128 v[174:177], v178 offset:2048
	ds_read_b128 v[178:181], v178 offset:3072
	s_add_u32 s30, s30, 0x100000
	s_addc_u32 s31, s31, 0
	s_mov_b32 m0, s40
	ds_read_b128 v[182:185], v157 offset:32768
	ds_read_b128 v[186:189], v157 offset:33792
	ds_read_b128 v[190:193], v157 offset:34816
	ds_read_b128 v[194:197], v157 offset:35840
	ds_read_b128 v[198:201], v157 offset:36864
	ds_read_b128 v[202:205], v157 offset:37888
	ds_read_b128 v[206:209], v157 offset:38912
	ds_read_b128 v[210:213], v157 offset:39936
	global_load_lds_dwordx4 v128, s[30:31]
	s_mov_b32 m0, s41
	s_nop 0
	global_load_lds_dwordx4 v132, s[30:31]
	s_waitcnt vmcnt(8)
	s_waitcnt lgkmcnt(0)
	s_barrier
	s_setprio 1
	s_waitcnt lgkmcnt(0)
	v_mfma_f32_16x16x32_bf16 v[124:127], v[144:147], v[182:185], v[124:127]
	v_mfma_f32_16x16x32_bf16 v[124:127], v[148:151], v[186:189], v[124:127]
	v_mfma_f32_16x16x32_bf16 v[108:111], v[148:151], v[194:197], v[108:111]
	v_mfma_f32_16x16x32_bf16 v[108:111], v[144:147], v[190:193], v[108:111]
	v_mfma_f32_16x16x32_bf16 v[92:95], v[144:147], v[198:201], v[92:95]
	v_mfma_f32_16x16x32_bf16 v[92:95], v[148:151], v[202:205], v[92:95]
	v_mfma_f32_16x16x32_bf16 v[76:79], v[148:151], v[210:213], v[76:79]
	v_mfma_f32_16x16x32_bf16 v[76:79], v[144:147], v[206:209], v[76:79]
	v_mfma_f32_16x16x32_bf16 v[120:123], v[158:161], v[182:185], v[120:123]
	v_mfma_f32_16x16x32_bf16 v[120:123], v[162:165], v[186:189], v[120:123]
	v_mfma_f32_16x16x32_bf16 v[104:107], v[162:165], v[194:197], v[104:107]
	v_mfma_f32_16x16x32_bf16 v[104:107], v[158:161], v[190:193], v[104:107]
	v_mfma_f32_16x16x32_bf16 v[88:91], v[158:161], v[198:201], v[88:91]
	v_mfma_f32_16x16x32_bf16 v[88:91], v[162:165], v[202:205], v[88:91]
	v_mfma_f32_16x16x32_bf16 v[72:75], v[162:165], v[210:213], v[72:75]
	v_mfma_f32_16x16x32_bf16 v[72:75], v[158:161], v[206:209], v[72:75]
	s_setprio 0
	s_setprio 1
	v_mfma_f32_16x16x32_bf16 v[116:119], v[166:169], v[182:185], v[116:119]
	v_mfma_f32_16x16x32_bf16 v[116:119], v[170:173], v[186:189], v[116:119]
	v_mfma_f32_16x16x32_bf16 v[100:103], v[170:173], v[194:197], v[100:103]
	v_mfma_f32_16x16x32_bf16 v[100:103], v[166:169], v[190:193], v[100:103]
	v_mfma_f32_16x16x32_bf16 v[84:87], v[166:169], v[198:201], v[84:87]
	v_mfma_f32_16x16x32_bf16 v[84:87], v[170:173], v[202:205], v[84:87]
	v_mfma_f32_16x16x32_bf16 v[68:71], v[170:173], v[210:213], v[68:71]
	v_mfma_f32_16x16x32_bf16 v[68:71], v[166:169], v[206:209], v[68:71]
	v_mfma_f32_16x16x32_bf16 v[112:115], v[174:177], v[182:185], v[112:115]
	v_mfma_f32_16x16x32_bf16 v[112:115], v[178:181], v[186:189], v[112:115]
	v_mfma_f32_16x16x32_bf16 v[96:99], v[178:181], v[194:197], v[96:99]
	v_mfma_f32_16x16x32_bf16 v[96:99], v[174:177], v[190:193], v[96:99]
	v_mfma_f32_16x16x32_bf16 v[80:83], v[174:177], v[198:201], v[80:83]
	v_mfma_f32_16x16x32_bf16 v[80:83], v[178:181], v[202:205], v[80:83]
	v_mfma_f32_16x16x32_bf16 v[64:67], v[178:181], v[210:213], v[64:67]
	v_mfma_f32_16x16x32_bf16 v[64:67], v[174:177], v[206:209], v[64:67]
	s_setprio 0
	s_barrier
	s_add_i32 s30, s55, s38
	s_mov_b32 m0, s30
	ds_read_b128 v[182:185], v157 offset:49152
	ds_read_b128 v[186:189], v157 offset:50176
	ds_read_b128 v[190:193], v157 offset:51200
	ds_read_b128 v[194:197], v157 offset:52224
	ds_read_b128 v[198:201], v157 offset:53248
	ds_read_b128 v[202:205], v157 offset:54272
	ds_read_b128 v[206:209], v157 offset:55296
	ds_read_b128 v[210:213], v157 offset:56320
	global_load_lds_dwordx4 v130, s[98:99]
	s_add_i32 m0, s30, 0x2000
	s_add_u32 s28, s28, 0x100080
	s_addc_u32 s29, s29, 0
	s_add_i32 s30, s56, s38
	global_load_lds_dwordx4 v134, s[98:99]
	s_mov_b32 m0, s30
	s_nop 0
	global_load_lds_dwordx4 v130, s[28:29]
	s_add_i32 m0, s30, 0x2000
	s_nop 0
	global_load_lds_dwordx4 v134, s[28:29]
	s_mov_b32 m0, s44
	s_nop 0
	global_load_lds_dwordx4 v128, s[100:101]
	s_mov_b32 m0, s45
	s_nop 0
	global_load_lds_dwordx4 v132, s[100:101]
	s_waitcnt vmcnt(8)
	s_waitcnt lgkmcnt(0)
	s_barrier
	s_setprio 1
	s_waitcnt lgkmcnt(0)
	v_mfma_f32_16x16x32_bf16 v[60:63], v[144:147], v[182:185], v[60:63]
	v_mfma_f32_16x16x32_bf16 v[60:63], v[148:151], v[186:189], v[60:63]
	v_mfma_f32_16x16x32_bf16 v[44:47], v[148:151], v[194:197], v[44:47]
	v_mfma_f32_16x16x32_bf16 v[44:47], v[144:147], v[190:193], v[44:47]
	v_mfma_f32_16x16x32_bf16 v[28:31], v[144:147], v[198:201], v[28:31]
	v_mfma_f32_16x16x32_bf16 v[28:31], v[148:151], v[202:205], v[28:31]
	v_mfma_f32_16x16x32_bf16 v[12:15], v[148:151], v[210:213], v[12:15]
	v_mfma_f32_16x16x32_bf16 v[12:15], v[144:147], v[206:209], v[12:15]
	v_mfma_f32_16x16x32_bf16 v[56:59], v[158:161], v[182:185], v[56:59]
	v_mfma_f32_16x16x32_bf16 v[56:59], v[162:165], v[186:189], v[56:59]
	v_mfma_f32_16x16x32_bf16 v[40:43], v[162:165], v[194:197], v[40:43]
	v_mfma_f32_16x16x32_bf16 v[40:43], v[158:161], v[190:193], v[40:43]
	v_mfma_f32_16x16x32_bf16 v[24:27], v[158:161], v[198:201], v[24:27]
	v_mfma_f32_16x16x32_bf16 v[24:27], v[162:165], v[202:205], v[24:27]
	v_mfma_f32_16x16x32_bf16 v[8:11], v[162:165], v[210:213], v[8:11]
	v_mfma_f32_16x16x32_bf16 v[8:11], v[158:161], v[206:209], v[8:11]
	s_setprio 0
	s_setprio 1
	v_mfma_f32_16x16x32_bf16 v[52:55], v[166:169], v[182:185], v[52:55]
	v_mfma_f32_16x16x32_bf16 v[52:55], v[170:173], v[186:189], v[52:55]
	v_mfma_f32_16x16x32_bf16 v[36:39], v[170:173], v[194:197], v[36:39]
	v_mfma_f32_16x16x32_bf16 v[36:39], v[166:169], v[190:193], v[36:39]
	v_mfma_f32_16x16x32_bf16 v[20:23], v[166:169], v[198:201], v[20:23]
	v_mfma_f32_16x16x32_bf16 v[20:23], v[170:173], v[202:205], v[20:23]
	v_mfma_f32_16x16x32_bf16 v[4:7], v[170:173], v[210:213], v[4:7]
	v_mfma_f32_16x16x32_bf16 v[4:7], v[166:169], v[206:209], v[4:7]
	v_mfma_f32_16x16x32_bf16 v[48:51], v[174:177], v[182:185], v[48:51]
	v_mfma_f32_16x16x32_bf16 v[48:51], v[178:181], v[186:189], v[48:51]
	v_mfma_f32_16x16x32_bf16 v[32:35], v[178:181], v[194:197], v[32:35]
	v_mfma_f32_16x16x32_bf16 v[32:35], v[174:177], v[190:193], v[32:35]
	v_mfma_f32_16x16x32_bf16 v[16:19], v[174:177], v[198:201], v[16:19]
	v_mfma_f32_16x16x32_bf16 v[16:19], v[178:181], v[202:205], v[16:19]
	v_mfma_f32_16x16x32_bf16 v[0:3], v[178:181], v[210:213], v[0:3]
	v_mfma_f32_16x16x32_bf16 v[0:3], v[174:177], v[206:209], v[0:3]
	s_setprio 0
	s_barrier
	s_add_i32 s54, s54, 2
	s_add_u32 s26, s26, 0x100
	s_addc_u32 s27, s27, 0
	s_add_u32 s52, s52, 0x100
	s_addc_u32 s53, s53, 0
	s_cmp_gt_u32 s54, 61
	s_cbranch_scc0 .LBB0_952
	s_and_b64 vcc, exec, s[12:13]
	s_cbranch_vccz .LBB0_955
	s_barrier
; __device__ __forceinline__ float epi_sigmoid(float v) { return __builtin_amdgcn_rcpf(1.0f + __expf(-v)); }
;     __device__ __forceinline__ void operator()(const f32x4 (&acc)[2][2][4][2], const Unit& u, int wr, int wc, int fr, int fq) const {
;         const int row0 = u.pm * BM + wr * 64 + fr, col0 = u.pn * BM + wc * 32 + 8 * fq;
; #pragma unroll
;         for (int ai = 0; ai < 2; ++ai)
; #pragma unroll
;             for (int m = 0; m < 4; ++m) { const size_t row = (size_t)(row0 + ai * HALF + m * 16);
; #pragma unroll
;                 for (int bj = 0; bj < 2; ++bj) { const int col = col0 + bj * HALF; f32x4 g0, g1; ld8bf(gates + row * 8192 + second * 4096 + col, g0, g1);
; #pragma unroll
;                     for (int j = 0; j < 4; ++j) { g0[j] = epi_sigmoid(g0[j]); g1[j] = epi_sigmoid(g1[j]); }
;                     f32x4 v0 = acc[ai][bj][m][0] * g0, v1 = acc[ai][bj][m][1] * g1;
;                     if (second) { f32x4 p0, p1; ld8bf(pm + row * 4096 + col, p0, p1); v0 += p0; v1 += p1; }
;                     st8bf(pm + row * 4096 + col, v0, v1); } }
.LBB0_955:
	v_lshl_add_u32 v148, s24, 8, v152
	v_ashrrev_i32_e32 v149, 31, v148
	v_lshl_or_b32 v146, s49, 8, v154
	v_lshlrev_b64 v[144:145], 14, v[148:149]
	v_lshl_add_u64 v[144:145], s[6:7], 0, v[144:145]
	v_ashrrev_i32_e32 v147, 31, v146
	v_lshl_add_u64 v[166:167], v[144:145], 0, s[14:15]
	v_lshlrev_b64 v[144:145], 1, v[146:147]
	v_lshl_add_u64 v[150:151], v[166:167], 0, v[144:145]
	global_load_dwordx4 v[158:161], v[150:151], off
	v_lshlrev_b64 v[150:151], 13, v[148:149]
	v_lshl_add_u64 v[150:151], s[8:9], 0, v[150:151]
	v_lshl_add_u64 v[150:151], v[150:151], 0, v[144:145]
	global_load_dwordx4 v[162:165], v[150:151], off
	v_or_b32_e32 v146, 0x80, v146
	v_ashrrev_i32_e32 v147, 31, v146
	v_lshlrev_b64 v[146:147], 1, v[146:147]
	v_lshl_add_u64 v[166:167], v[166:167], 0, v[146:147]
	s_andn2_b64 vcc, exec, s[2:3]
	s_mov_b64 s[2:3], -1
	s_waitcnt vmcnt(0)
	v_lshlrev_b32_e32 v149, 16, v158
	v_and_b32_e32 v168, 0xffff0000, v158
	v_lshlrev_b32_e32 v169, 16, v159
	v_and_b32_e32 v170, 0xffff0000, v159
	v_lshlrev_b32_e32 v171, 16, v160
	v_and_b32_e32 v172, 0xffff0000, v160
	v_lshlrev_b32_e32 v173, 16, v161
	v_and_b32_e32 v174, 0xffff0000, v161
	v_mul_f32_e32 v149, 0xbfb8aa3b, v149
	v_mul_f32_e32 v171, 0xbfb8aa3b, v171
	v_mul_f32_e32 v168, 0xbfb8aa3b, v168
	v_mul_f32_e32 v172, 0xbfb8aa3b, v172
	v_mul_f32_e32 v169, 0xbfb8aa3b, v169
	v_mul_f32_e32 v173, 0xbfb8aa3b, v173
	v_mul_f32_e32 v170, 0xbfb8aa3b, v170
	v_mul_f32_e32 v174, 0xbfb8aa3b, v174
	v_exp_f32_e32 v149, v149
	v_exp_f32_e32 v171, v171
	v_exp_f32_e32 v168, v168
	v_exp_f32_e32 v172, v172
	v_exp_f32_e32 v169, v169
	v_exp_f32_e32 v173, v173
	v_exp_f32_e32 v170, v170
	v_exp_f32_e32 v174, v174
	v_add_f32_e32 v149, 1.0, v149
	v_add_f32_e32 v171, 1.0, v171
	v_add_f32_e32 v175, 1.0, v168
	v_add_f32_e32 v176, 1.0, v172
	v_add_f32_e32 v172, 1.0, v169
	v_add_f32_e32 v177, 1.0, v173
	v_add_f32_e32 v173, 1.0, v170
	v_add_f32_e32 v178, 1.0, v174
	v_rcp_f32_e32 v168, v149
	v_rcp_f32_e32 v170, v171
	v_rcp_f32_e32 v169, v175
	v_rcp_f32_e32 v172, v172
	v_rcp_f32_e32 v173, v173
	v_rcp_f32_e32 v174, v177
	v_rcp_f32_e32 v175, v178
	v_rcp_f32_e32 v171, v176
	v_lshlrev_b32_e32 v158, 16, v162
	v_and_b32_e32 v159, 0xffff0000, v162
	v_lshlrev_b32_e32 v160, 16, v163
	v_and_b32_e32 v161, 0xffff0000, v163
	v_lshlrev_b32_e32 v162, 16, v164
	v_and_b32_e32 v163, 0xffff0000, v164
	v_lshlrev_b32_e32 v164, 16, v165
	v_and_b32_e32 v165, 0xffff0000, v165
	v_pk_fma_f32 v[126:127], v[126:127], v[172:173], v[160:161]
	v_pk_fma_f32 v[124:125], v[124:125], v[168:169], v[158:159]
	v_pk_fma_f32 v[158:159], v[122:123], v[174:175], v[164:165]
	v_pk_fma_f32 v[122:123], v[120:121], v[170:171], v[162:163]
	v_cvt_pk_bf16_f32 v120, v124, v125
	v_cvt_pk_bf16_f32 v121, v126, v127
	v_or_b32_e32 v162, 16, v148
	v_cvt_pk_bf16_f32 v122, v122, v123
	v_cvt_pk_bf16_f32 v123, v158, v159
	global_load_dwordx4 v[124:127], v[166:167], off
	global_load_dwordx4 v[158:161], v[150:151], off offset:256
	v_ashrrev_i32_e32 v163, 31, v162
	global_store_dwordx4 v[150:151], v[120:123], off
	v_lshlrev_b64 v[164:165], 14, v[162:163]
	v_lshl_add_u64 v[164:165], s[6:7], 0, v[164:165]
	v_lshl_add_u64 v[164:165], v[164:165], 0, s[14:15]
	v_lshl_add_u64 v[166:167], v[164:165], 0, v[144:145]
	s_waitcnt vmcnt(2)
	v_lshlrev_b32_e32 v149, 16, v124
	v_and_b32_e32 v168, 0xffff0000, v124
	v_lshlrev_b32_e32 v169, 16, v125
	v_lshlrev_b32_e32 v171, 16, v126
	v_and_b32_e32 v172, 0xffff0000, v126
	v_and_b32_e32 v170, 0xffff0000, v125
	v_lshlrev_b32_e32 v173, 16, v127
	v_and_b32_e32 v174, 0xffff0000, v127
	s_waitcnt vmcnt(1)
	v_lshlrev_b32_e32 v120, 16, v158
	v_and_b32_e32 v121, 0xffff0000, v158
	v_lshlrev_b32_e32 v122, 16, v159
	v_and_b32_e32 v123, 0xffff0000, v159
	v_lshlrev_b32_e32 v124, 16, v160
	v_and_b32_e32 v125, 0xffff0000, v160
	v_lshlrev_b32_e32 v126, 16, v161
	v_and_b32_e32 v127, 0xffff0000, v161
	v_mul_f32_e32 v149, 0xbfb8aa3b, v149
	v_mul_f32_e32 v158, 0xbfb8aa3b, v171
	v_mul_f32_e32 v159, 0xbfb8aa3b, v168
	v_mul_f32_e32 v160, 0xbfb8aa3b, v172
	v_mul_f32_e32 v161, 0xbfb8aa3b, v169
	v_mul_f32_e32 v168, 0xbfb8aa3b, v173
	v_mul_f32_e32 v169, 0xbfb8aa3b, v170
	v_mul_f32_e32 v170, 0xbfb8aa3b, v174
	v_exp_f32_e32 v149, v149
	v_exp_f32_e32 v158, v158
	v_exp_f32_e32 v159, v159
	v_exp_f32_e32 v160, v160
	v_exp_f32_e32 v161, v161
	v_exp_f32_e32 v168, v168
	v_exp_f32_e32 v169, v169
	v_exp_f32_e32 v170, v170
	v_add_f32_e32 v149, 1.0, v149
	v_add_f32_e32 v171, 1.0, v158
	v_add_f32_e32 v159, 1.0, v159
	v_add_f32_e32 v172, 1.0, v160
	v_add_f32_e32 v161, 1.0, v161
	v_add_f32_e32 v173, 1.0, v168
	v_add_f32_e32 v169, 1.0, v169
	v_add_f32_e32 v174, 1.0, v170
	v_rcp_f32_e32 v158, v149
	v_rcp_f32_e32 v160, v171
	v_rcp_f32_e32 v159, v159
	v_rcp_f32_e32 v168, v161
	v_rcp_f32_e32 v161, v172
	v_rcp_f32_e32 v169, v169
	v_rcp_f32_e32 v170, v173
	v_rcp_f32_e32 v171, v174
	v_pk_fma_f32 v[116:117], v[116:117], v[158:159], v[120:121]
	v_pk_fma_f32 v[112:113], v[112:113], v[160:161], v[124:125]
	v_pk_fma_f32 v[118:119], v[118:119], v[168:169], v[122:123]
	v_pk_fma_f32 v[120:121], v[114:115], v[170:171], v[126:127]
	v_cvt_pk_bf16_f32 v114, v116, v117
	v_cvt_pk_bf16_f32 v115, v118, v119
	v_cvt_pk_bf16_f32 v116, v112, v113
	v_lshlrev_b64 v[112:113], 13, v[162:163]
	v_lshl_add_u64 v[112:113], s[8:9], 0, v[112:113]
	v_cvt_pk_bf16_f32 v117, v120, v121
	global_load_dwordx4 v[118:121], v[166:167], off
	v_lshl_add_u64 v[112:113], v[112:113], 0, v[144:145]
	global_load_dwordx4 v[122:125], v[112:113], off
	v_lshl_add_u64 v[126:127], v[164:165], 0, v[146:147]
	global_store_dwordx4 v[150:151], v[114:117], off offset:256
	s_waitcnt vmcnt(2)
; __device__ __forceinline__ float epi_sigmoid(float v) { return __builtin_amdgcn_rcpf(1.0f + __expf(-v)); }
;     __device__ __forceinline__ void operator()(const f32x4 (&acc)[2][2][4][2], const Unit& u, int wr, int wc, int fr, int fq) const {
;         const int row0 = u.pm * BM + wr * 64 + fr, col0 = u.pn * BM + wc * 32 + 8 * fq;
; #pragma unroll
;         for (int ai = 0; ai < 2; ++ai)
; #pragma unroll
;             for (int m = 0; m < 4; ++m) { const size_t row = (size_t)(row0 + ai * HALF + m * 16);
; #pragma unroll
;                 for (int bj = 0; bj < 2; ++bj) { const int col = col0 + bj * HALF; f32x4 g0, g1; ld8bf(gates + row * 8192 + second * 4096 + col, g0, g1);
; #pragma unroll
;                     for (int j = 0; j < 4; ++j) { g0[j] = epi_sigmoid(g0[j]); g1[j] = epi_sigmoid(g1[j]); }
;                     f32x4 v0 = acc[ai][bj][m][0] * g0, v1 = acc[ai][bj][m][1] * g1;
;                     if (second) { f32x4 p0, p1; ld8bf(pm + row * 4096 + col, p0, p1); v0 += p0; v1 += p1; }
;                     st8bf(pm + row * 4096 + col, v0, v1); } }
	v_lshlrev_b32_e32 v149, 16, v118
	v_and_b32_e32 v150, 0xffff0000, v118
	v_lshlrev_b32_e32 v151, 16, v119
	v_and_b32_e32 v158, 0xffff0000, v119
	v_lshlrev_b32_e32 v159, 16, v120
	v_and_b32_e32 v160, 0xffff0000, v120
	v_lshlrev_b32_e32 v161, 16, v121
	v_and_b32_e32 v162, 0xffff0000, v121
	s_waitcnt vmcnt(1)
	v_lshlrev_b32_e32 v114, 16, v122
	v_and_b32_e32 v115, 0xffff0000, v122
	v_lshlrev_b32_e32 v116, 16, v123
	v_and_b32_e32 v117, 0xffff0000, v123
	v_lshlrev_b32_e32 v118, 16, v124
	v_and_b32_e32 v119, 0xffff0000, v124
	v_lshlrev_b32_e32 v120, 16, v125
	v_and_b32_e32 v121, 0xffff0000, v125
	v_mul_f32_e32 v122, 0xbfb8aa3b, v149
	v_mul_f32_e32 v123, 0xbfb8aa3b, v159
	v_mul_f32_e32 v124, 0xbfb8aa3b, v150
	v_mul_f32_e32 v125, 0xbfb8aa3b, v160
	v_mul_f32_e32 v149, 0xbfb8aa3b, v151
	v_mul_f32_e32 v150, 0xbfb8aa3b, v161
	v_mul_f32_e32 v151, 0xbfb8aa3b, v158
	v_mul_f32_e32 v158, 0xbfb8aa3b, v162
	v_exp_f32_e32 v122, v122
	v_exp_f32_e32 v123, v123
	v_exp_f32_e32 v124, v124
	v_exp_f32_e32 v125, v125
	v_exp_f32_e32 v149, v149
	v_exp_f32_e32 v150, v150
	v_exp_f32_e32 v151, v151
	v_exp_f32_e32 v158, v158
	v_add_f32_e32 v122, 1.0, v122
	v_add_f32_e32 v123, 1.0, v123
	v_add_f32_e32 v159, 1.0, v124
	v_add_f32_e32 v125, 1.0, v125
	v_add_f32_e32 v149, 1.0, v149
	v_add_f32_e32 v160, 1.0, v150
	v_add_f32_e32 v151, 1.0, v151
	v_add_f32_e32 v161, 1.0, v158
	v_rcp_f32_e32 v122, v122
	v_rcp_f32_e32 v124, v123
	v_rcp_f32_e32 v123, v159
	v_rcp_f32_e32 v150, v149
	v_rcp_f32_e32 v151, v151
	v_rcp_f32_e32 v158, v160
	v_rcp_f32_e32 v159, v161
	v_rcp_f32_e32 v125, v125
	v_pk_fma_f32 v[110:111], v[110:111], v[150:151], v[116:117]
	v_pk_fma_f32 v[108:109], v[108:109], v[122:123], v[114:115]
	v_pk_fma_f32 v[114:115], v[106:107], v[158:159], v[120:121]
	v_pk_fma_f32 v[106:107], v[104:105], v[124:125], v[118:119]
	v_cvt_pk_bf16_f32 v104, v108, v109
	v_cvt_pk_bf16_f32 v105, v110, v111
	v_or_b32_e32 v118, 32, v148
	v_cvt_pk_bf16_f32 v106, v106, v107
	v_cvt_pk_bf16_f32 v107, v114, v115
	global_load_dwordx4 v[108:111], v[126:127], off
	global_load_dwordx4 v[114:117], v[112:113], off offset:256
	v_ashrrev_i32_e32 v119, 31, v118
	global_store_dwordx4 v[112:113], v[104:107], off
	v_lshlrev_b64 v[120:121], 14, v[118:119]
	v_lshl_add_u64 v[120:121], s[6:7], 0, v[120:121]
	v_lshl_add_u64 v[120:121], v[120:121], 0, s[14:15]
	v_lshl_add_u64 v[122:123], v[120:121], 0, v[144:145]
	s_waitcnt vmcnt(2)
	v_lshlrev_b32_e32 v124, 16, v108
	v_and_b32_e32 v125, 0xffff0000, v108
	v_lshlrev_b32_e32 v149, 16, v110
	v_and_b32_e32 v150, 0xffff0000, v110
	v_lshlrev_b32_e32 v126, 16, v109
	v_and_b32_e32 v127, 0xffff0000, v109
	v_lshlrev_b32_e32 v151, 16, v111
	v_and_b32_e32 v158, 0xffff0000, v111
	s_waitcnt vmcnt(1)
	v_lshlrev_b32_e32 v104, 16, v114
	v_and_b32_e32 v105, 0xffff0000, v114
	v_lshlrev_b32_e32 v106, 16, v115
	v_and_b32_e32 v107, 0xffff0000, v115
	v_lshlrev_b32_e32 v108, 16, v116
	v_and_b32_e32 v109, 0xffff0000, v116
	v_lshlrev_b32_e32 v110, 16, v117
	v_and_b32_e32 v111, 0xffff0000, v117
	v_mul_f32_e32 v114, 0xbfb8aa3b, v124
	v_mul_f32_e32 v115, 0xbfb8aa3b, v149
	v_mul_f32_e32 v116, 0xbfb8aa3b, v125
	v_mul_f32_e32 v117, 0xbfb8aa3b, v150
	v_mul_f32_e32 v124, 0xbfb8aa3b, v126
	v_mul_f32_e32 v125, 0xbfb8aa3b, v151
	v_mul_f32_e32 v126, 0xbfb8aa3b, v127
	v_mul_f32_e32 v127, 0xbfb8aa3b, v158
	v_exp_f32_e32 v114, v114
	v_exp_f32_e32 v115, v115
	v_exp_f32_e32 v116, v116
	v_exp_f32_e32 v117, v117
	v_exp_f32_e32 v124, v124
	v_exp_f32_e32 v125, v125
	v_exp_f32_e32 v126, v126
	v_exp_f32_e32 v127, v127
	v_add_f32_e32 v114, 1.0, v114
	v_add_f32_e32 v115, 1.0, v115
	v_add_f32_e32 v149, 1.0, v116
	v_add_f32_e32 v117, 1.0, v117
	v_add_f32_e32 v124, 1.0, v124
	v_add_f32_e32 v150, 1.0, v125
	v_add_f32_e32 v125, 1.0, v126
	v_add_f32_e32 v127, 1.0, v127
	v_rcp_f32_e32 v114, v114
	v_rcp_f32_e32 v116, v115
	v_rcp_f32_e32 v115, v149
	v_rcp_f32_e32 v117, v117
	v_rcp_f32_e32 v124, v124
	v_rcp_f32_e32 v125, v125
	v_rcp_f32_e32 v126, v150
	v_rcp_f32_e32 v127, v127
	v_pk_fma_f32 v[100:101], v[100:101], v[114:115], v[104:105]
	v_pk_fma_f32 v[96:97], v[96:97], v[116:117], v[108:109]
	v_pk_fma_f32 v[102:103], v[102:103], v[124:125], v[106:107]
	v_pk_fma_f32 v[104:105], v[98:99], v[126:127], v[110:111]
	v_cvt_pk_bf16_f32 v98, v100, v101
	v_cvt_pk_bf16_f32 v99, v102, v103
	v_cvt_pk_bf16_f32 v100, v96, v97
	v_lshlrev_b64 v[96:97], 13, v[118:119]
	v_lshl_add_u64 v[96:97], s[8:9], 0, v[96:97]
	v_cvt_pk_bf16_f32 v101, v104, v105
	global_load_dwordx4 v[102:105], v[122:123], off
	v_lshl_add_u64 v[96:97], v[96:97], 0, v[144:145]
	global_load_dwordx4 v[106:109], v[96:97], off
	v_lshl_add_u64 v[110:111], v[120:121], 0, v[146:147]
	global_store_dwordx4 v[112:113], v[98:101], off offset:256
	s_waitcnt vmcnt(2)
	v_lshlrev_b32_e32 v112, 16, v102
	v_and_b32_e32 v113, 0xffff0000, v102
	v_lshlrev_b32_e32 v114, 16, v103
	v_and_b32_e32 v115, 0xffff0000, v103
	v_lshlrev_b32_e32 v116, 16, v104
	v_and_b32_e32 v117, 0xffff0000, v104
	v_lshlrev_b32_e32 v118, 16, v105
	v_and_b32_e32 v119, 0xffff0000, v105
	s_waitcnt vmcnt(1)
; __device__ __forceinline__ float epi_sigmoid(float v) { return __builtin_amdgcn_rcpf(1.0f + __expf(-v)); }
;     __device__ __forceinline__ void operator()(const f32x4 (&acc)[2][2][4][2], const Unit& u, int wr, int wc, int fr, int fq) const {
;         const int row0 = u.pm * BM + wr * 64 + fr, col0 = u.pn * BM + wc * 32 + 8 * fq;
; #pragma unroll
;         for (int ai = 0; ai < 2; ++ai)
; #pragma unroll
;             for (int m = 0; m < 4; ++m) { const size_t row = (size_t)(row0 + ai * HALF + m * 16);
; #pragma unroll
;                 for (int bj = 0; bj < 2; ++bj) { const int col = col0 + bj * HALF; f32x4 g0, g1; ld8bf(gates + row * 8192 + second * 4096 + col, g0, g1);
; #pragma unroll
;                     for (int j = 0; j < 4; ++j) { g0[j] = epi_sigmoid(g0[j]); g1[j] = epi_sigmoid(g1[j]); }
;                     f32x4 v0 = acc[ai][bj][m][0] * g0, v1 = acc[ai][bj][m][1] * g1;
;                     if (second) { f32x4 p0, p1; ld8bf(pm + row * 4096 + col, p0, p1); v0 += p0; v1 += p1; }
;                     st8bf(pm + row * 4096 + col, v0, v1); } }
	v_lshlrev_b32_e32 v98, 16, v106
	v_and_b32_e32 v99, 0xffff0000, v106
	v_lshlrev_b32_e32 v100, 16, v107
	v_and_b32_e32 v101, 0xffff0000, v107
	v_lshlrev_b32_e32 v102, 16, v108
	v_and_b32_e32 v103, 0xffff0000, v108
	v_lshlrev_b32_e32 v104, 16, v109
	v_and_b32_e32 v105, 0xffff0000, v109
	v_mul_f32_e32 v106, 0xbfb8aa3b, v112
	v_mul_f32_e32 v107, 0xbfb8aa3b, v116
	v_mul_f32_e32 v108, 0xbfb8aa3b, v113
	v_mul_f32_e32 v109, 0xbfb8aa3b, v117
	v_mul_f32_e32 v112, 0xbfb8aa3b, v114
	v_mul_f32_e32 v113, 0xbfb8aa3b, v118
	v_mul_f32_e32 v114, 0xbfb8aa3b, v115
	v_mul_f32_e32 v115, 0xbfb8aa3b, v119
	v_exp_f32_e32 v106, v106
	v_exp_f32_e32 v107, v107
	v_exp_f32_e32 v108, v108
	v_exp_f32_e32 v109, v109
	v_exp_f32_e32 v112, v112
	v_exp_f32_e32 v113, v113
	v_exp_f32_e32 v114, v114
	v_exp_f32_e32 v115, v115
	v_add_f32_e32 v106, 1.0, v106
	v_add_f32_e32 v107, 1.0, v107
	v_add_f32_e32 v116, 1.0, v108
	v_add_f32_e32 v109, 1.0, v109
	v_add_f32_e32 v112, 1.0, v112
	v_add_f32_e32 v117, 1.0, v113
	v_add_f32_e32 v113, 1.0, v114
	v_add_f32_e32 v115, 1.0, v115
	v_rcp_f32_e32 v106, v106
	v_rcp_f32_e32 v108, v107
	v_rcp_f32_e32 v107, v116
	v_rcp_f32_e32 v112, v112
	v_rcp_f32_e32 v113, v113
	v_rcp_f32_e32 v114, v117
	v_rcp_f32_e32 v115, v115
	v_rcp_f32_e32 v109, v109
	v_pk_fma_f32 v[94:95], v[94:95], v[112:113], v[100:101]
	v_pk_fma_f32 v[92:93], v[92:93], v[106:107], v[98:99]
	v_pk_fma_f32 v[98:99], v[90:91], v[114:115], v[104:105]
	v_pk_fma_f32 v[90:91], v[88:89], v[108:109], v[102:103]
	v_cvt_pk_bf16_f32 v88, v92, v93
	v_cvt_pk_bf16_f32 v89, v94, v95
	v_or_b32_e32 v102, 48, v148
	v_cvt_pk_bf16_f32 v90, v90, v91
	v_cvt_pk_bf16_f32 v91, v98, v99
	global_load_dwordx4 v[92:95], v[110:111], off
	global_load_dwordx4 v[98:101], v[96:97], off offset:256
	v_ashrrev_i32_e32 v103, 31, v102
	global_store_dwordx4 v[96:97], v[88:91], off
	v_lshlrev_b64 v[104:105], 14, v[102:103]
	v_lshl_add_u64 v[104:105], s[6:7], 0, v[104:105]
	v_lshl_add_u64 v[104:105], v[104:105], 0, s[14:15]
	v_lshl_add_u64 v[106:107], v[104:105], 0, v[144:145]
	s_waitcnt vmcnt(2)
	v_lshlrev_b32_e32 v108, 16, v92
	v_and_b32_e32 v109, 0xffff0000, v92
	v_lshlrev_b32_e32 v112, 16, v94
	v_and_b32_e32 v113, 0xffff0000, v94
	v_lshlrev_b32_e32 v110, 16, v93
	v_and_b32_e32 v111, 0xffff0000, v93
	v_lshlrev_b32_e32 v114, 16, v95
	v_and_b32_e32 v115, 0xffff0000, v95
	s_waitcnt vmcnt(1)
	v_lshlrev_b32_e32 v88, 16, v98
	v_and_b32_e32 v89, 0xffff0000, v98
	v_lshlrev_b32_e32 v90, 16, v99
	v_and_b32_e32 v91, 0xffff0000, v99
	v_lshlrev_b32_e32 v92, 16, v100
	v_and_b32_e32 v93, 0xffff0000, v100
	v_lshlrev_b32_e32 v94, 16, v101
	v_and_b32_e32 v95, 0xffff0000, v101
	v_mul_f32_e32 v98, 0xbfb8aa3b, v108
	v_mul_f32_e32 v99, 0xbfb8aa3b, v112
	v_mul_f32_e32 v100, 0xbfb8aa3b, v109
	v_mul_f32_e32 v101, 0xbfb8aa3b, v113
	v_mul_f32_e32 v108, 0xbfb8aa3b, v110
	v_mul_f32_e32 v109, 0xbfb8aa3b, v114
	v_mul_f32_e32 v110, 0xbfb8aa3b, v111
	v_mul_f32_e32 v111, 0xbfb8aa3b, v115
	v_exp_f32_e32 v98, v98
	v_exp_f32_e32 v99, v99
	v_exp_f32_e32 v100, v100
	v_exp_f32_e32 v101, v101
	v_exp_f32_e32 v108, v108
	v_exp_f32_e32 v109, v109
	v_exp_f32_e32 v110, v110
	v_exp_f32_e32 v111, v111
	v_add_f32_e32 v98, 1.0, v98
	v_add_f32_e32 v99, 1.0, v99
	v_add_f32_e32 v112, 1.0, v100
	v_add_f32_e32 v101, 1.0, v101
	v_add_f32_e32 v108, 1.0, v108
	v_add_f32_e32 v113, 1.0, v109
	v_add_f32_e32 v109, 1.0, v110
	v_add_f32_e32 v111, 1.0, v111
	v_rcp_f32_e32 v98, v98
	v_rcp_f32_e32 v100, v99
	v_rcp_f32_e32 v99, v112
	v_rcp_f32_e32 v101, v101
	v_rcp_f32_e32 v108, v108
	v_rcp_f32_e32 v109, v109
	v_rcp_f32_e32 v110, v113
	v_rcp_f32_e32 v111, v111
	v_pk_fma_f32 v[84:85], v[84:85], v[98:99], v[88:89]
	v_pk_fma_f32 v[80:81], v[80:81], v[100:101], v[92:93]
	v_pk_fma_f32 v[86:87], v[86:87], v[108:109], v[90:91]
	v_pk_fma_f32 v[88:89], v[82:83], v[110:111], v[94:95]
	v_cvt_pk_bf16_f32 v82, v84, v85
	v_cvt_pk_bf16_f32 v83, v86, v87
	v_cvt_pk_bf16_f32 v84, v80, v81
	v_lshlrev_b64 v[80:81], 13, v[102:103]
	v_lshl_add_u64 v[80:81], s[8:9], 0, v[80:81]
	v_cvt_pk_bf16_f32 v85, v88, v89
	global_load_dwordx4 v[86:89], v[106:107], off
	v_lshl_add_u64 v[80:81], v[80:81], 0, v[144:145]
	global_load_dwordx4 v[90:93], v[80:81], off
	v_lshl_add_u64 v[94:95], v[104:105], 0, v[146:147]
	global_store_dwordx4 v[96:97], v[82:85], off offset:256
	s_waitcnt vmcnt(2)
	v_lshlrev_b32_e32 v96, 16, v86
	v_and_b32_e32 v97, 0xffff0000, v86
	v_lshlrev_b32_e32 v98, 16, v87
	v_and_b32_e32 v99, 0xffff0000, v87
	v_lshlrev_b32_e32 v100, 16, v88
	v_and_b32_e32 v101, 0xffff0000, v88
	v_lshlrev_b32_e32 v102, 16, v89
	v_and_b32_e32 v103, 0xffff0000, v89
	s_waitcnt vmcnt(1)
	v_lshlrev_b32_e32 v82, 16, v90
	v_and_b32_e32 v83, 0xffff0000, v90
	v_lshlrev_b32_e32 v84, 16, v91
	v_and_b32_e32 v85, 0xffff0000, v91
	v_lshlrev_b32_e32 v86, 16, v92
	v_and_b32_e32 v87, 0xffff0000, v92
	v_lshlrev_b32_e32 v88, 16, v93
	v_and_b32_e32 v89, 0xffff0000, v93
	v_mul_f32_e32 v90, 0xbfb8aa3b, v96
	v_mul_f32_e32 v91, 0xbfb8aa3b, v100
	v_mul_f32_e32 v92, 0xbfb8aa3b, v97
	v_mul_f32_e32 v93, 0xbfb8aa3b, v101
	v_mul_f32_e32 v96, 0xbfb8aa3b, v98
	v_mul_f32_e32 v97, 0xbfb8aa3b, v102
	v_mul_f32_e32 v98, 0xbfb8aa3b, v99
	v_mul_f32_e32 v99, 0xbfb8aa3b, v103
	v_exp_f32_e32 v90, v90
	v_exp_f32_e32 v91, v91
	v_exp_f32_e32 v92, v92
	v_exp_f32_e32 v93, v93
	v_exp_f32_e32 v96, v96
	v_exp_f32_e32 v97, v97
	v_exp_f32_e32 v98, v98
	v_exp_f32_e32 v99, v99
	v_add_f32_e32 v90, 1.0, v90
	v_add_f32_e32 v91, 1.0, v91
	v_add_f32_e32 v100, 1.0, v92
	v_add_f32_e32 v93, 1.0, v93
	v_add_f32_e32 v96, 1.0, v96
	v_add_f32_e32 v101, 1.0, v97
	v_add_f32_e32 v97, 1.0, v98
	v_add_f32_e32 v99, 1.0, v99
	v_rcp_f32_e32 v90, v90
	v_rcp_f32_e32 v92, v91
	v_rcp_f32_e32 v91, v100
	v_rcp_f32_e32 v96, v96
	v_rcp_f32_e32 v97, v97
	v_rcp_f32_e32 v98, v101
	v_rcp_f32_e32 v99, v99
	v_rcp_f32_e32 v93, v93
	v_pk_fma_f32 v[78:79], v[78:79], v[96:97], v[84:85]
	v_pk_fma_f32 v[76:77], v[76:77], v[90:91], v[82:83]
	v_pk_fma_f32 v[82:83], v[74:75], v[98:99], v[88:89]
	v_pk_fma_f32 v[74:75], v[72:73], v[92:93], v[86:87]
	v_cvt_pk_bf16_f32 v72, v76, v77
	v_cvt_pk_bf16_f32 v73, v78, v79
	v_add_u32_e32 v86, 0x80, v148
	v_cvt_pk_bf16_f32 v74, v74, v75
	v_cvt_pk_bf16_f32 v75, v82, v83
	global_load_dwordx4 v[76:79], v[94:95], off
	global_load_dwordx4 v[82:85], v[80:81], off offset:256
	v_ashrrev_i32_e32 v87, 31, v86
	global_store_dwordx4 v[80:81], v[72:75], off
	v_lshlrev_b64 v[88:89], 14, v[86:87]
	v_lshl_add_u64 v[88:89], s[6:7], 0, v[88:89]
	v_lshl_add_u64 v[88:89], v[88:89], 0, s[14:15]
	v_lshl_add_u64 v[90:91], v[88:89], 0, v[144:145]
	s_waitcnt vmcnt(2)
; __device__ __forceinline__ float epi_sigmoid(float v) { return __builtin_amdgcn_rcpf(1.0f + __expf(-v)); }
;     __device__ __forceinline__ void operator()(const f32x4 (&acc)[2][2][4][2], const Unit& u, int wr, int wc, int fr, int fq) const {
;         const int row0 = u.pm * BM + wr * 64 + fr, col0 = u.pn * BM + wc * 32 + 8 * fq;
; #pragma unroll
;         for (int ai = 0; ai < 2; ++ai)
; #pragma unroll
;             for (int m = 0; m < 4; ++m) { const size_t row = (size_t)(row0 + ai * HALF + m * 16);
; #pragma unroll
;                 for (int bj = 0; bj < 2; ++bj) { const int col = col0 + bj * HALF; f32x4 g0, g1; ld8bf(gates + row * 8192 + second * 4096 + col, g0, g1);
; #pragma unroll
;                     for (int j = 0; j < 4; ++j) { g0[j] = epi_sigmoid(g0[j]); g1[j] = epi_sigmoid(g1[j]); }
;                     f32x4 v0 = acc[ai][bj][m][0] * g0, v1 = acc[ai][bj][m][1] * g1;
;                     if (second) { f32x4 p0, p1; ld8bf(pm + row * 4096 + col, p0, p1); v0 += p0; v1 += p1; }
;                     st8bf(pm + row * 4096 + col, v0, v1); } }
	v_lshlrev_b32_e32 v92, 16, v76
	v_and_b32_e32 v93, 0xffff0000, v76
	v_lshlrev_b32_e32 v96, 16, v78
	v_and_b32_e32 v97, 0xffff0000, v78
	v_lshlrev_b32_e32 v94, 16, v77
	v_and_b32_e32 v95, 0xffff0000, v77
	v_lshlrev_b32_e32 v98, 16, v79
	v_and_b32_e32 v99, 0xffff0000, v79
	s_waitcnt vmcnt(1)
	v_lshlrev_b32_e32 v72, 16, v82
	v_and_b32_e32 v73, 0xffff0000, v82
	v_lshlrev_b32_e32 v74, 16, v83
	v_and_b32_e32 v75, 0xffff0000, v83
	v_lshlrev_b32_e32 v76, 16, v84
	v_and_b32_e32 v77, 0xffff0000, v84
	v_lshlrev_b32_e32 v78, 16, v85
	v_and_b32_e32 v79, 0xffff0000, v85
	v_mul_f32_e32 v82, 0xbfb8aa3b, v92
	v_mul_f32_e32 v83, 0xbfb8aa3b, v96
	v_mul_f32_e32 v84, 0xbfb8aa3b, v93
	v_mul_f32_e32 v85, 0xbfb8aa3b, v97
	v_mul_f32_e32 v92, 0xbfb8aa3b, v94
	v_mul_f32_e32 v93, 0xbfb8aa3b, v98
	v_mul_f32_e32 v94, 0xbfb8aa3b, v95
	v_mul_f32_e32 v95, 0xbfb8aa3b, v99
	v_exp_f32_e32 v82, v82
	v_exp_f32_e32 v83, v83
	v_exp_f32_e32 v84, v84
	v_exp_f32_e32 v85, v85
	v_exp_f32_e32 v92, v92
	v_exp_f32_e32 v93, v93
	v_exp_f32_e32 v94, v94
	v_exp_f32_e32 v95, v95
	v_add_f32_e32 v82, 1.0, v82
	v_add_f32_e32 v83, 1.0, v83
	v_add_f32_e32 v96, 1.0, v84
	v_add_f32_e32 v85, 1.0, v85
	v_add_f32_e32 v92, 1.0, v92
	v_add_f32_e32 v97, 1.0, v93
	v_add_f32_e32 v93, 1.0, v94
	v_add_f32_e32 v95, 1.0, v95
	v_rcp_f32_e32 v82, v82
	v_rcp_f32_e32 v84, v83
	v_rcp_f32_e32 v83, v96
	v_rcp_f32_e32 v85, v85
	v_rcp_f32_e32 v92, v92
	v_rcp_f32_e32 v93, v93
	v_rcp_f32_e32 v94, v97
	v_rcp_f32_e32 v95, v95
	v_pk_fma_f32 v[68:69], v[68:69], v[82:83], v[72:73]
	v_pk_fma_f32 v[64:65], v[64:65], v[84:85], v[76:77]
	v_pk_fma_f32 v[70:71], v[70:71], v[92:93], v[74:75]
	v_pk_fma_f32 v[72:73], v[66:67], v[94:95], v[78:79]
	v_cvt_pk_bf16_f32 v66, v68, v69
	v_cvt_pk_bf16_f32 v67, v70, v71
	v_cvt_pk_bf16_f32 v68, v64, v65
	v_lshlrev_b64 v[64:65], 13, v[86:87]
	v_lshl_add_u64 v[64:65], s[8:9], 0, v[64:65]
	v_cvt_pk_bf16_f32 v69, v72, v73
	global_load_dwordx4 v[70:73], v[90:91], off
	v_lshl_add_u64 v[64:65], v[64:65], 0, v[144:145]
	global_load_dwordx4 v[74:77], v[64:65], off
	v_lshl_add_u64 v[78:79], v[88:89], 0, v[146:147]
	global_store_dwordx4 v[80:81], v[66:69], off offset:256
	s_waitcnt vmcnt(2)
	v_lshlrev_b32_e32 v80, 16, v70
	v_and_b32_e32 v81, 0xffff0000, v70
	v_lshlrev_b32_e32 v82, 16, v71
	v_and_b32_e32 v83, 0xffff0000, v71
	v_lshlrev_b32_e32 v84, 16, v72
	v_and_b32_e32 v85, 0xffff0000, v72
	v_lshlrev_b32_e32 v86, 16, v73
	v_and_b32_e32 v87, 0xffff0000, v73
	s_waitcnt vmcnt(1)
	v_lshlrev_b32_e32 v66, 16, v74
	v_and_b32_e32 v67, 0xffff0000, v74
	v_lshlrev_b32_e32 v68, 16, v75
	v_and_b32_e32 v69, 0xffff0000, v75
	v_lshlrev_b32_e32 v70, 16, v76
	v_and_b32_e32 v71, 0xffff0000, v76
	v_lshlrev_b32_e32 v72, 16, v77
	v_and_b32_e32 v73, 0xffff0000, v77
	v_mul_f32_e32 v74, 0xbfb8aa3b, v80
	v_mul_f32_e32 v75, 0xbfb8aa3b, v84
	v_mul_f32_e32 v76, 0xbfb8aa3b, v81
	v_mul_f32_e32 v77, 0xbfb8aa3b, v85
	v_mul_f32_e32 v80, 0xbfb8aa3b, v82
	v_mul_f32_e32 v81, 0xbfb8aa3b, v86
	v_mul_f32_e32 v82, 0xbfb8aa3b, v83
	v_mul_f32_e32 v83, 0xbfb8aa3b, v87
	v_exp_f32_e32 v74, v74
	v_exp_f32_e32 v75, v75
	v_exp_f32_e32 v76, v76
	v_exp_f32_e32 v77, v77
	v_exp_f32_e32 v80, v80
	v_exp_f32_e32 v81, v81
	v_exp_f32_e32 v82, v82
	v_exp_f32_e32 v83, v83
	v_add_f32_e32 v74, 1.0, v74
	v_add_f32_e32 v75, 1.0, v75
	v_add_f32_e32 v84, 1.0, v76
	v_add_f32_e32 v77, 1.0, v77
	v_add_f32_e32 v80, 1.0, v80
	v_add_f32_e32 v85, 1.0, v81
	v_add_f32_e32 v81, 1.0, v82
	v_add_f32_e32 v83, 1.0, v83
	v_rcp_f32_e32 v74, v74
	v_rcp_f32_e32 v76, v75
	v_rcp_f32_e32 v75, v84
	v_rcp_f32_e32 v80, v80
	v_rcp_f32_e32 v81, v81
	v_rcp_f32_e32 v82, v85
	v_rcp_f32_e32 v83, v83
	v_rcp_f32_e32 v77, v77
	v_pk_fma_f32 v[62:63], v[62:63], v[80:81], v[68:69]
	v_pk_fma_f32 v[60:61], v[60:61], v[74:75], v[66:67]
	v_pk_fma_f32 v[66:67], v[58:59], v[82:83], v[72:73]
	v_pk_fma_f32 v[58:59], v[56:57], v[76:77], v[70:71]
	v_cvt_pk_bf16_f32 v56, v60, v61
	v_cvt_pk_bf16_f32 v57, v62, v63
	v_add_u32_e32 v70, 0x90, v148
	v_cvt_pk_bf16_f32 v58, v58, v59
	v_cvt_pk_bf16_f32 v59, v66, v67
	global_load_dwordx4 v[60:63], v[78:79], off
	global_load_dwordx4 v[66:69], v[64:65], off offset:256
	v_ashrrev_i32_e32 v71, 31, v70
	global_store_dwordx4 v[64:65], v[56:59], off
	v_lshlrev_b64 v[72:73], 14, v[70:71]
	v_lshl_add_u64 v[72:73], s[6:7], 0, v[72:73]
	v_lshl_add_u64 v[72:73], v[72:73], 0, s[14:15]
	v_lshl_add_u64 v[74:75], v[72:73], 0, v[144:145]
	s_waitcnt vmcnt(2)
	v_lshlrev_b32_e32 v76, 16, v60
	v_and_b32_e32 v77, 0xffff0000, v60
	v_lshlrev_b32_e32 v80, 16, v62
	v_and_b32_e32 v81, 0xffff0000, v62
	v_lshlrev_b32_e32 v78, 16, v61
	v_and_b32_e32 v79, 0xffff0000, v61
	v_lshlrev_b32_e32 v82, 16, v63
	v_and_b32_e32 v83, 0xffff0000, v63
	s_waitcnt vmcnt(1)
	v_lshlrev_b32_e32 v56, 16, v66
	v_and_b32_e32 v57, 0xffff0000, v66
	v_lshlrev_b32_e32 v58, 16, v67
	v_and_b32_e32 v59, 0xffff0000, v67
	v_lshlrev_b32_e32 v60, 16, v68
	v_and_b32_e32 v61, 0xffff0000, v68
	v_lshlrev_b32_e32 v62, 16, v69
	v_and_b32_e32 v63, 0xffff0000, v69
	v_mul_f32_e32 v66, 0xbfb8aa3b, v76
	v_mul_f32_e32 v67, 0xbfb8aa3b, v80
	v_mul_f32_e32 v68, 0xbfb8aa3b, v77
	v_mul_f32_e32 v69, 0xbfb8aa3b, v81
	v_mul_f32_e32 v76, 0xbfb8aa3b, v78
	v_mul_f32_e32 v77, 0xbfb8aa3b, v82
	v_mul_f32_e32 v78, 0xbfb8aa3b, v79
	v_mul_f32_e32 v79, 0xbfb8aa3b, v83
	v_exp_f32_e32 v66, v66
	v_exp_f32_e32 v67, v67
	v_exp_f32_e32 v68, v68
	v_exp_f32_e32 v69, v69
	v_exp_f32_e32 v76, v76
	v_exp_f32_e32 v77, v77
	v_exp_f32_e32 v78, v78
	v_exp_f32_e32 v79, v79
	v_add_f32_e32 v66, 1.0, v66
	v_add_f32_e32 v67, 1.0, v67
	v_add_f32_e32 v80, 1.0, v68
	v_add_f32_e32 v69, 1.0, v69
	v_add_f32_e32 v76, 1.0, v76
	v_add_f32_e32 v81, 1.0, v77
	v_add_f32_e32 v77, 1.0, v78
	v_add_f32_e32 v79, 1.0, v79
	v_rcp_f32_e32 v66, v66
	v_rcp_f32_e32 v68, v67
	v_rcp_f32_e32 v67, v80
	v_rcp_f32_e32 v69, v69
	v_rcp_f32_e32 v76, v76
	v_rcp_f32_e32 v77, v77
	v_rcp_f32_e32 v78, v81
	v_rcp_f32_e32 v79, v79
	v_pk_fma_f32 v[52:53], v[52:53], v[66:67], v[56:57]
	v_pk_fma_f32 v[48:49], v[48:49], v[68:69], v[60:61]
	v_pk_fma_f32 v[54:55], v[54:55], v[76:77], v[58:59]
	v_pk_fma_f32 v[56:57], v[50:51], v[78:79], v[62:63]
	v_cvt_pk_bf16_f32 v50, v52, v53
	v_cvt_pk_bf16_f32 v51, v54, v55
	v_cvt_pk_bf16_f32 v52, v48, v49
	v_lshlrev_b64 v[48:49], 13, v[70:71]
	v_lshl_add_u64 v[48:49], s[8:9], 0, v[48:49]
	v_cvt_pk_bf16_f32 v53, v56, v57
	global_load_dwordx4 v[54:57], v[74:75], off
	v_lshl_add_u64 v[48:49], v[48:49], 0, v[144:145]
	global_load_dwordx4 v[58:61], v[48:49], off
	v_lshl_add_u64 v[62:63], v[72:73], 0, v[146:147]
	global_store_dwordx4 v[64:65], v[50:53], off offset:256
	s_waitcnt vmcnt(2)
; __device__ __forceinline__ float epi_sigmoid(float v) { return __builtin_amdgcn_rcpf(1.0f + __expf(-v)); }
;     __device__ __forceinline__ void operator()(const f32x4 (&acc)[2][2][4][2], const Unit& u, int wr, int wc, int fr, int fq) const {
;         const int row0 = u.pm * BM + wr * 64 + fr, col0 = u.pn * BM + wc * 32 + 8 * fq;
; #pragma unroll
;         for (int ai = 0; ai < 2; ++ai)
; #pragma unroll
;             for (int m = 0; m < 4; ++m) { const size_t row = (size_t)(row0 + ai * HALF + m * 16);
; #pragma unroll
;                 for (int bj = 0; bj < 2; ++bj) { const int col = col0 + bj * HALF; f32x4 g0, g1; ld8bf(gates + row * 8192 + second * 4096 + col, g0, g1);
; #pragma unroll
;                     for (int j = 0; j < 4; ++j) { g0[j] = epi_sigmoid(g0[j]); g1[j] = epi_sigmoid(g1[j]); }
;                     f32x4 v0 = acc[ai][bj][m][0] * g0, v1 = acc[ai][bj][m][1] * g1;
;                     if (second) { f32x4 p0, p1; ld8bf(pm + row * 4096 + col, p0, p1); v0 += p0; v1 += p1; }
;                     st8bf(pm + row * 4096 + col, v0, v1); } }
	v_lshlrev_b32_e32 v64, 16, v54
	v_and_b32_e32 v65, 0xffff0000, v54
	v_lshlrev_b32_e32 v66, 16, v55
	v_and_b32_e32 v67, 0xffff0000, v55
	v_lshlrev_b32_e32 v68, 16, v56
	v_and_b32_e32 v69, 0xffff0000, v56
	v_lshlrev_b32_e32 v70, 16, v57
	v_and_b32_e32 v71, 0xffff0000, v57
	s_waitcnt vmcnt(1)
	v_lshlrev_b32_e32 v50, 16, v58
	v_and_b32_e32 v51, 0xffff0000, v58
	v_lshlrev_b32_e32 v52, 16, v59
	v_and_b32_e32 v53, 0xffff0000, v59
	v_lshlrev_b32_e32 v54, 16, v60
	v_and_b32_e32 v55, 0xffff0000, v60
	v_lshlrev_b32_e32 v56, 16, v61
	v_and_b32_e32 v57, 0xffff0000, v61
	v_mul_f32_e32 v58, 0xbfb8aa3b, v64
	v_mul_f32_e32 v59, 0xbfb8aa3b, v68
	v_mul_f32_e32 v60, 0xbfb8aa3b, v65
	v_mul_f32_e32 v61, 0xbfb8aa3b, v69
	v_mul_f32_e32 v64, 0xbfb8aa3b, v66
	v_mul_f32_e32 v65, 0xbfb8aa3b, v70
	v_mul_f32_e32 v66, 0xbfb8aa3b, v67
	v_mul_f32_e32 v67, 0xbfb8aa3b, v71
	v_exp_f32_e32 v58, v58
	v_exp_f32_e32 v59, v59
	v_exp_f32_e32 v60, v60
	v_exp_f32_e32 v61, v61
	v_exp_f32_e32 v64, v64
	v_exp_f32_e32 v65, v65
	v_exp_f32_e32 v66, v66
	v_exp_f32_e32 v67, v67
	v_add_f32_e32 v58, 1.0, v58
	v_add_f32_e32 v59, 1.0, v59
	v_add_f32_e32 v68, 1.0, v60
	v_add_f32_e32 v61, 1.0, v61
	v_add_f32_e32 v64, 1.0, v64
	v_add_f32_e32 v69, 1.0, v65
	v_add_f32_e32 v65, 1.0, v66
	v_add_f32_e32 v67, 1.0, v67
	v_rcp_f32_e32 v58, v58
	v_rcp_f32_e32 v60, v59
	v_rcp_f32_e32 v59, v68
	v_rcp_f32_e32 v64, v64
	v_rcp_f32_e32 v65, v65
	v_rcp_f32_e32 v66, v69
	v_rcp_f32_e32 v67, v67
	v_rcp_f32_e32 v61, v61
	v_pk_fma_f32 v[46:47], v[46:47], v[64:65], v[52:53]
	v_pk_fma_f32 v[44:45], v[44:45], v[58:59], v[50:51]
	v_pk_fma_f32 v[50:51], v[42:43], v[66:67], v[56:57]
	v_pk_fma_f32 v[42:43], v[40:41], v[60:61], v[54:55]
	v_cvt_pk_bf16_f32 v40, v44, v45
	v_cvt_pk_bf16_f32 v41, v46, v47
	v_add_u32_e32 v54, 0xa0, v148
	v_cvt_pk_bf16_f32 v42, v42, v43
	v_cvt_pk_bf16_f32 v43, v50, v51
	global_load_dwordx4 v[44:47], v[62:63], off
	global_load_dwordx4 v[50:53], v[48:49], off offset:256
	v_ashrrev_i32_e32 v55, 31, v54
	global_store_dwordx4 v[48:49], v[40:43], off
	v_lshlrev_b64 v[56:57], 14, v[54:55]
	v_lshl_add_u64 v[56:57], s[6:7], 0, v[56:57]
	v_lshl_add_u64 v[56:57], v[56:57], 0, s[14:15]
	v_lshl_add_u64 v[58:59], v[56:57], 0, v[144:145]
	s_waitcnt vmcnt(2)
	v_lshlrev_b32_e32 v60, 16, v44
	v_and_b32_e32 v61, 0xffff0000, v44
	v_lshlrev_b32_e32 v64, 16, v46
	v_and_b32_e32 v65, 0xffff0000, v46
	v_lshlrev_b32_e32 v62, 16, v45
	v_and_b32_e32 v63, 0xffff0000, v45
	v_lshlrev_b32_e32 v66, 16, v47
	v_and_b32_e32 v67, 0xffff0000, v47
	s_waitcnt vmcnt(1)
	v_lshlrev_b32_e32 v40, 16, v50
	v_and_b32_e32 v41, 0xffff0000, v50
	v_lshlrev_b32_e32 v42, 16, v51
	v_and_b32_e32 v43, 0xffff0000, v51
	v_lshlrev_b32_e32 v44, 16, v52
	v_and_b32_e32 v45, 0xffff0000, v52
	v_lshlrev_b32_e32 v46, 16, v53
	v_and_b32_e32 v47, 0xffff0000, v53
	v_mul_f32_e32 v50, 0xbfb8aa3b, v60
	v_mul_f32_e32 v51, 0xbfb8aa3b, v64
	v_mul_f32_e32 v52, 0xbfb8aa3b, v61
	v_mul_f32_e32 v53, 0xbfb8aa3b, v65
	v_mul_f32_e32 v60, 0xbfb8aa3b, v62
	v_mul_f32_e32 v61, 0xbfb8aa3b, v66
	v_mul_f32_e32 v62, 0xbfb8aa3b, v63
	v_mul_f32_e32 v63, 0xbfb8aa3b, v67
	v_exp_f32_e32 v50, v50
	v_exp_f32_e32 v51, v51
	v_exp_f32_e32 v52, v52
	v_exp_f32_e32 v53, v53
	v_exp_f32_e32 v60, v60
	v_exp_f32_e32 v61, v61
	v_exp_f32_e32 v62, v62
	v_exp_f32_e32 v63, v63
	v_add_f32_e32 v50, 1.0, v50
	v_add_f32_e32 v51, 1.0, v51
	v_add_f32_e32 v64, 1.0, v52
	v_add_f32_e32 v53, 1.0, v53
	v_add_f32_e32 v60, 1.0, v60
	v_add_f32_e32 v65, 1.0, v61
	v_add_f32_e32 v61, 1.0, v62
	v_add_f32_e32 v63, 1.0, v63
	v_rcp_f32_e32 v50, v50
	v_rcp_f32_e32 v52, v51
	v_rcp_f32_e32 v51, v64
	v_rcp_f32_e32 v53, v53
	v_rcp_f32_e32 v60, v60
	v_rcp_f32_e32 v61, v61
	v_rcp_f32_e32 v62, v65
	v_rcp_f32_e32 v63, v63
	v_pk_fma_f32 v[36:37], v[36:37], v[50:51], v[40:41]
	v_pk_fma_f32 v[32:33], v[32:33], v[52:53], v[44:45]
	v_pk_fma_f32 v[38:39], v[38:39], v[60:61], v[42:43]
	v_pk_fma_f32 v[40:41], v[34:35], v[62:63], v[46:47]
	v_cvt_pk_bf16_f32 v34, v36, v37
	v_cvt_pk_bf16_f32 v35, v38, v39
	v_cvt_pk_bf16_f32 v36, v32, v33
	v_lshlrev_b64 v[32:33], 13, v[54:55]
	v_lshl_add_u64 v[32:33], s[8:9], 0, v[32:33]
	v_cvt_pk_bf16_f32 v37, v40, v41
	global_load_dwordx4 v[38:41], v[58:59], off
	v_lshl_add_u64 v[32:33], v[32:33], 0, v[144:145]
	global_load_dwordx4 v[42:45], v[32:33], off
	v_lshl_add_u64 v[46:47], v[56:57], 0, v[146:147]
	global_store_dwordx4 v[48:49], v[34:37], off offset:256
	s_waitcnt vmcnt(2)
	v_lshlrev_b32_e32 v48, 16, v38
	v_and_b32_e32 v49, 0xffff0000, v38
	v_lshlrev_b32_e32 v50, 16, v39
	v_and_b32_e32 v51, 0xffff0000, v39
	v_lshlrev_b32_e32 v52, 16, v40
	v_and_b32_e32 v53, 0xffff0000, v40
	v_lshlrev_b32_e32 v54, 16, v41
	v_and_b32_e32 v55, 0xffff0000, v41
	s_waitcnt vmcnt(1)
; __device__ __forceinline__ float epi_sigmoid(float v) { return __builtin_amdgcn_rcpf(1.0f + __expf(-v)); }
;     __device__ __forceinline__ void operator()(const f32x4 (&acc)[2][2][4][2], const Unit& u, int wr, int wc, int fr, int fq) const {
;         const int row0 = u.pm * BM + wr * 64 + fr, col0 = u.pn * BM + wc * 32 + 8 * fq;
; #pragma unroll
;         for (int ai = 0; ai < 2; ++ai)
; #pragma unroll
;             for (int m = 0; m < 4; ++m) { const size_t row = (size_t)(row0 + ai * HALF + m * 16);
; #pragma unroll
;                 for (int bj = 0; bj < 2; ++bj) { const int col = col0 + bj * HALF; f32x4 g0, g1; ld8bf(gates + row * 8192 + second * 4096 + col, g0, g1);
; #pragma unroll
;                     for (int j = 0; j < 4; ++j) { g0[j] = epi_sigmoid(g0[j]); g1[j] = epi_sigmoid(g1[j]); }
;                     f32x4 v0 = acc[ai][bj][m][0] * g0, v1 = acc[ai][bj][m][1] * g1;
;                     if (second) { f32x4 p0, p1; ld8bf(pm + row * 4096 + col, p0, p1); v0 += p0; v1 += p1; }
;                     st8bf(pm + row * 4096 + col, v0, v1); } }
	v_lshlrev_b32_e32 v34, 16, v42
	v_and_b32_e32 v35, 0xffff0000, v42
	v_lshlrev_b32_e32 v36, 16, v43
	v_and_b32_e32 v37, 0xffff0000, v43
	v_lshlrev_b32_e32 v38, 16, v44
	v_and_b32_e32 v39, 0xffff0000, v44
	v_lshlrev_b32_e32 v40, 16, v45
	v_and_b32_e32 v41, 0xffff0000, v45
	v_mul_f32_e32 v42, 0xbfb8aa3b, v48
	v_mul_f32_e32 v43, 0xbfb8aa3b, v52
	v_mul_f32_e32 v44, 0xbfb8aa3b, v49
	v_mul_f32_e32 v45, 0xbfb8aa3b, v53
	v_mul_f32_e32 v48, 0xbfb8aa3b, v50
	v_mul_f32_e32 v49, 0xbfb8aa3b, v54
	v_mul_f32_e32 v50, 0xbfb8aa3b, v51
	v_mul_f32_e32 v51, 0xbfb8aa3b, v55
	v_exp_f32_e32 v42, v42
	v_exp_f32_e32 v43, v43
	v_exp_f32_e32 v44, v44
	v_exp_f32_e32 v45, v45
	v_exp_f32_e32 v48, v48
	v_exp_f32_e32 v49, v49
	v_exp_f32_e32 v50, v50
	v_exp_f32_e32 v51, v51
	v_add_f32_e32 v42, 1.0, v42
	v_add_f32_e32 v43, 1.0, v43
	v_add_f32_e32 v52, 1.0, v44
	v_add_f32_e32 v45, 1.0, v45
	v_add_f32_e32 v48, 1.0, v48
	v_add_f32_e32 v53, 1.0, v49
	v_add_f32_e32 v49, 1.0, v50
	v_add_f32_e32 v51, 1.0, v51
	v_rcp_f32_e32 v42, v42
	v_rcp_f32_e32 v44, v43
	v_rcp_f32_e32 v43, v52
	v_rcp_f32_e32 v48, v48
	v_rcp_f32_e32 v49, v49
	v_rcp_f32_e32 v50, v53
	v_rcp_f32_e32 v51, v51
	v_rcp_f32_e32 v45, v45
	v_pk_fma_f32 v[30:31], v[30:31], v[48:49], v[36:37]
	v_pk_fma_f32 v[28:29], v[28:29], v[42:43], v[34:35]
	v_pk_fma_f32 v[34:35], v[26:27], v[50:51], v[40:41]
	v_pk_fma_f32 v[26:27], v[24:25], v[44:45], v[38:39]
	v_cvt_pk_bf16_f32 v24, v28, v29
	v_cvt_pk_bf16_f32 v25, v30, v31
	v_add_u32_e32 v38, 0xb0, v148
	v_cvt_pk_bf16_f32 v26, v26, v27
	v_cvt_pk_bf16_f32 v27, v34, v35
	global_load_dwordx4 v[28:31], v[46:47], off
	global_load_dwordx4 v[34:37], v[32:33], off offset:256
	v_ashrrev_i32_e32 v39, 31, v38
	global_store_dwordx4 v[32:33], v[24:27], off
	v_lshlrev_b64 v[40:41], 14, v[38:39]
	v_lshl_add_u64 v[40:41], s[6:7], 0, v[40:41]
	v_lshl_add_u64 v[40:41], v[40:41], 0, s[14:15]
	v_lshl_add_u64 v[42:43], v[40:41], 0, v[144:145]
	s_waitcnt vmcnt(2)
	v_lshlrev_b32_e32 v44, 16, v28
	v_and_b32_e32 v45, 0xffff0000, v28
	v_lshlrev_b32_e32 v48, 16, v30
	v_and_b32_e32 v49, 0xffff0000, v30
	v_lshlrev_b32_e32 v46, 16, v29
	v_and_b32_e32 v47, 0xffff0000, v29
	v_lshlrev_b32_e32 v50, 16, v31
	v_and_b32_e32 v51, 0xffff0000, v31
	s_waitcnt vmcnt(1)
	v_lshlrev_b32_e32 v24, 16, v34
	v_and_b32_e32 v25, 0xffff0000, v34
	v_lshlrev_b32_e32 v26, 16, v35
	v_and_b32_e32 v27, 0xffff0000, v35
	v_lshlrev_b32_e32 v28, 16, v36
	v_and_b32_e32 v29, 0xffff0000, v36
	v_lshlrev_b32_e32 v30, 16, v37
	v_and_b32_e32 v31, 0xffff0000, v37
	v_mul_f32_e32 v34, 0xbfb8aa3b, v44
	v_mul_f32_e32 v35, 0xbfb8aa3b, v48
	v_mul_f32_e32 v36, 0xbfb8aa3b, v45
	v_mul_f32_e32 v37, 0xbfb8aa3b, v49
	v_mul_f32_e32 v44, 0xbfb8aa3b, v46
	v_mul_f32_e32 v45, 0xbfb8aa3b, v50
	v_mul_f32_e32 v46, 0xbfb8aa3b, v47
	v_mul_f32_e32 v47, 0xbfb8aa3b, v51
	v_exp_f32_e32 v34, v34
	v_exp_f32_e32 v35, v35
	v_exp_f32_e32 v36, v36
	v_exp_f32_e32 v37, v37
	v_exp_f32_e32 v44, v44
	v_exp_f32_e32 v45, v45
	v_exp_f32_e32 v46, v46
	v_exp_f32_e32 v47, v47
	v_add_f32_e32 v34, 1.0, v34
	v_add_f32_e32 v35, 1.0, v35
	v_add_f32_e32 v48, 1.0, v36
	v_add_f32_e32 v37, 1.0, v37
	v_add_f32_e32 v44, 1.0, v44
	v_add_f32_e32 v49, 1.0, v45
	v_add_f32_e32 v45, 1.0, v46
	v_add_f32_e32 v47, 1.0, v47
	v_rcp_f32_e32 v34, v34
	v_rcp_f32_e32 v36, v35
	v_rcp_f32_e32 v35, v48
	v_rcp_f32_e32 v37, v37
	v_rcp_f32_e32 v44, v44
	v_rcp_f32_e32 v45, v45
	v_rcp_f32_e32 v46, v49
	v_rcp_f32_e32 v47, v47
	v_pk_fma_f32 v[20:21], v[20:21], v[34:35], v[24:25]
	v_pk_fma_f32 v[16:17], v[16:17], v[36:37], v[28:29]
	v_pk_fma_f32 v[22:23], v[22:23], v[44:45], v[26:27]
	v_pk_fma_f32 v[24:25], v[18:19], v[46:47], v[30:31]
	v_cvt_pk_bf16_f32 v18, v20, v21
	v_cvt_pk_bf16_f32 v19, v22, v23
	v_cvt_pk_bf16_f32 v20, v16, v17
	v_lshlrev_b64 v[16:17], 13, v[38:39]
	v_lshl_add_u64 v[16:17], s[8:9], 0, v[16:17]
	v_cvt_pk_bf16_f32 v21, v24, v25
	global_load_dwordx4 v[22:25], v[42:43], off
	v_lshl_add_u64 v[16:17], v[16:17], 0, v[144:145]
	global_load_dwordx4 v[26:29], v[16:17], off
	v_lshl_add_u64 v[30:31], v[40:41], 0, v[146:147]
	global_store_dwordx4 v[32:33], v[18:21], off offset:256
	s_waitcnt vmcnt(2)
; __device__ __forceinline__ float epi_sigmoid(float v) { return __builtin_amdgcn_rcpf(1.0f + __expf(-v)); }
;     __device__ __forceinline__ void operator()(const f32x4 (&acc)[2][2][4][2], const Unit& u, int wr, int wc, int fr, int fq) const {
;         const int row0 = u.pm * BM + wr * 64 + fr, col0 = u.pn * BM + wc * 32 + 8 * fq;
; #pragma unroll
;         for (int ai = 0; ai < 2; ++ai)
; #pragma unroll
;             for (int m = 0; m < 4; ++m) { const size_t row = (size_t)(row0 + ai * HALF + m * 16);
; #pragma unroll
;                 for (int bj = 0; bj < 2; ++bj) { const int col = col0 + bj * HALF; f32x4 g0, g1; ld8bf(gates + row * 8192 + second * 4096 + col, g0, g1);
; #pragma unroll
;                     for (int j = 0; j < 4; ++j) { g0[j] = epi_sigmoid(g0[j]); g1[j] = epi_sigmoid(g1[j]); }
;                     f32x4 v0 = acc[ai][bj][m][0] * g0, v1 = acc[ai][bj][m][1] * g1;
;                     if (second) { f32x4 p0, p1; ld8bf(pm + row * 4096 + col, p0, p1); v0 += p0; v1 += p1; }
;                     st8bf(pm + row * 4096 + col, v0, v1); } }
	v_lshlrev_b32_e32 v32, 16, v22
	v_and_b32_e32 v33, 0xffff0000, v22
	v_lshlrev_b32_e32 v34, 16, v23
	v_and_b32_e32 v35, 0xffff0000, v23
	v_lshlrev_b32_e32 v36, 16, v24
	v_and_b32_e32 v37, 0xffff0000, v24
	v_lshlrev_b32_e32 v38, 16, v25
	v_and_b32_e32 v39, 0xffff0000, v25
	s_waitcnt vmcnt(1)
	v_lshlrev_b32_e32 v18, 16, v26
	v_and_b32_e32 v19, 0xffff0000, v26
	v_lshlrev_b32_e32 v20, 16, v27
	v_and_b32_e32 v21, 0xffff0000, v27
	v_lshlrev_b32_e32 v22, 16, v28
	v_and_b32_e32 v23, 0xffff0000, v28
	v_lshlrev_b32_e32 v24, 16, v29
	v_and_b32_e32 v25, 0xffff0000, v29
	v_mul_f32_e32 v26, 0xbfb8aa3b, v32
	v_mul_f32_e32 v27, 0xbfb8aa3b, v36
	v_mul_f32_e32 v28, 0xbfb8aa3b, v33
	v_mul_f32_e32 v29, 0xbfb8aa3b, v37
	v_mul_f32_e32 v32, 0xbfb8aa3b, v34
	v_mul_f32_e32 v33, 0xbfb8aa3b, v38
	v_mul_f32_e32 v34, 0xbfb8aa3b, v35
	v_mul_f32_e32 v35, 0xbfb8aa3b, v39
	v_exp_f32_e32 v26, v26
	v_exp_f32_e32 v27, v27
	v_exp_f32_e32 v28, v28
	v_exp_f32_e32 v29, v29
	v_exp_f32_e32 v32, v32
	v_exp_f32_e32 v33, v33
	v_exp_f32_e32 v34, v34
	v_exp_f32_e32 v35, v35
	v_add_f32_e32 v26, 1.0, v26
	v_add_f32_e32 v27, 1.0, v27
	v_add_f32_e32 v36, 1.0, v28
	v_add_f32_e32 v29, 1.0, v29
	v_add_f32_e32 v32, 1.0, v32
	v_add_f32_e32 v37, 1.0, v33
	v_add_f32_e32 v33, 1.0, v34
	v_add_f32_e32 v35, 1.0, v35
	v_rcp_f32_e32 v26, v26
	v_rcp_f32_e32 v28, v27
	v_rcp_f32_e32 v27, v36
	v_rcp_f32_e32 v32, v32
	v_rcp_f32_e32 v33, v33
	v_rcp_f32_e32 v34, v37
	v_rcp_f32_e32 v35, v35
	v_rcp_f32_e32 v29, v29
	v_pk_fma_f32 v[14:15], v[14:15], v[32:33], v[20:21]
	v_pk_fma_f32 v[12:13], v[12:13], v[26:27], v[18:19]
	v_pk_fma_f32 v[18:19], v[10:11], v[34:35], v[24:25]
	v_pk_fma_f32 v[10:11], v[8:9], v[28:29], v[22:23]
	v_cvt_pk_bf16_f32 v8, v12, v13
	v_cvt_pk_bf16_f32 v9, v14, v15
	s_nop 0
	v_cvt_pk_bf16_f32 v10, v10, v11
	v_cvt_pk_bf16_f32 v11, v18, v19
	global_load_dwordx4 v[12:15], v[30:31], off
	global_load_dwordx4 v[18:21], v[16:17], off offset:256
	s_waitcnt vmcnt(1)
	v_lshlrev_b32_e32 v22, 16, v12
	v_and_b32_e32 v23, 0xffff0000, v12
	v_lshlrev_b32_e32 v24, 16, v13
	v_and_b32_e32 v25, 0xffff0000, v13
	v_lshlrev_b32_e32 v26, 16, v14
	v_and_b32_e32 v27, 0xffff0000, v14
	v_lshlrev_b32_e32 v28, 16, v15
	v_and_b32_e32 v29, 0xffff0000, v15
	global_store_dwordx4 v[16:17], v[8:11], off
	s_waitcnt vmcnt(1)
	v_lshlrev_b32_e32 v12, 16, v20
	v_and_b32_e32 v13, 0xffff0000, v20
	v_lshlrev_b32_e32 v8, 16, v18
	v_and_b32_e32 v9, 0xffff0000, v18
	v_lshlrev_b32_e32 v10, 16, v19
	v_and_b32_e32 v11, 0xffff0000, v19
	v_lshlrev_b32_e32 v14, 16, v21
	v_and_b32_e32 v15, 0xffff0000, v21
	v_mul_f32_e32 v18, 0xbfb8aa3b, v22
	v_mul_f32_e32 v19, 0xbfb8aa3b, v26
	v_mul_f32_e32 v20, 0xbfb8aa3b, v23
	v_mul_f32_e32 v21, 0xbfb8aa3b, v27
	v_mul_f32_e32 v22, 0xbfb8aa3b, v24
	v_mul_f32_e32 v23, 0xbfb8aa3b, v28
	v_mul_f32_e32 v24, 0xbfb8aa3b, v25
	v_mul_f32_e32 v25, 0xbfb8aa3b, v29
	v_exp_f32_e32 v18, v18
	v_exp_f32_e32 v19, v19
	v_exp_f32_e32 v20, v20
	v_exp_f32_e32 v21, v21
	v_exp_f32_e32 v23, v23
	v_exp_f32_e32 v25, v25
	v_exp_f32_e32 v22, v22
	v_exp_f32_e32 v24, v24
	v_add_f32_e32 v18, 1.0, v18
	v_add_f32_e32 v19, 1.0, v19
	v_add_f32_e32 v26, 1.0, v20
	v_add_f32_e32 v21, 1.0, v21
	v_add_f32_e32 v27, 1.0, v23
	v_add_f32_e32 v25, 1.0, v25
	v_add_f32_e32 v22, 1.0, v22
	v_add_f32_e32 v23, 1.0, v24
	v_rcp_f32_e32 v18, v18
	v_rcp_f32_e32 v20, v19
	v_rcp_f32_e32 v19, v26
	v_rcp_f32_e32 v24, v27
	v_rcp_f32_e32 v25, v25
	v_rcp_f32_e32 v21, v21
	v_rcp_f32_e32 v22, v22
	v_rcp_f32_e32 v23, v23
	v_pk_fma_f32 v[4:5], v[4:5], v[18:19], v[8:9]
	v_pk_fma_f32 v[8:9], v[2:3], v[24:25], v[14:15]
	v_pk_fma_f32 v[2:3], v[0:1], v[20:21], v[12:13]
	v_pk_fma_f32 v[6:7], v[6:7], v[22:23], v[10:11]
	v_cvt_pk_bf16_f32 v0, v4, v5
	s_nop 0
	v_cvt_pk_bf16_f32 v1, v6, v7
	v_cvt_pk_bf16_f32 v2, v2, v3
	v_cvt_pk_bf16_f32 v3, v8, v9
	global_store_dwordx4 v[16:17], v[0:3], off offset:256
	s_cbranch_vccnz .LBB0_944
	s_andn2_b64 vcc, exec, s[4:5]
	s_cbranch_vccnz .LBB0_943
	s_barrier
	s_branch .LBB0_943

; #define PG8_STAGE(bufoff, gbase, voff) do { _Pragma("unroll") for (int _i = 0; _i < 2; ++_i) \
;         __builtin_amdgcn_global_load_lds((const unsigned*)((const char*)(gbase) + (voff)[_i]), (PG8_LAS unsigned*)(lds + (bufoff) + ldsw + _i * 8192), 16, 0, 0); } while (0)
; #define PG8_LDA(dst, b, h) do { _Pragma("unroll") for (int m = 0; m < 4; ++m) _Pragma("unroll") for (int k = 0; k < 2; ++k) dst[m][k] = *(const PG8_LAS bf16x8*)(lds + PG8_SA(b, h) + aoff + m * 2048 + k * 1024); } while (0)
; #define PG8_LDB(dst, b, h) do { _Pragma("unroll") for (int n = 0; n < 2; ++n) _Pragma("unroll") for (int k = 0; k < 2; ++k) dst[n][k] = *(const PG8_LAS bf16x8*)(lds + PG8_SB(b, h) + boff + n * 2048 + k * 1024); } while (0)
; #define PG8_WAIT_V(n) asm volatile("s_waitcnt vmcnt(" #n ")" ::: "memory")
; #define PG8_WAIT_L(n) asm volatile("s_waitcnt lgkmcnt(" #n ")" ::: "memory")
; #define PG8_BAR __builtin_amdgcn_s_barrier()
; #define PG8_SCHED __builtin_amdgcn_sched_barrier(0)
; template <class Epi, class Sched, bool ALIGN_EPI = false, bool SP2 = false>
; __device__ __forceinline__ void gemm_phase(PG8_LAS unsigned char* lds, const Gemm g, const Sched& S, const Epi& E, int tid_in) {
;     ...
;             PG8_LDB(B0, 0, 0); PG8_LDB(B1, 0, 1); PG8_SCHED; PG8_LDA(At, 0, 0); PG8_STAGE(PG8_SA(1, 1), a1 + hstepA, voffA);
;             PG8_WAIT_V(8); PG8_WAIT_L(0); PG8_BAR; PG8_MMA(0, 0, At, B0); PG8_MMA(0, 1, At, B1); PG8_BAR; PG8_SCHED;
;             PG8_LDA(At, 0, 1); PG8_STAGE(PG8_SB(0, 0), b2, voffB); PG8_STAGE(PG8_SB(0, 1), b2 + hstep, voffB); PG8_STAGE(PG8_SA(0, 0), a2, voffA);
;             PG8_WAIT_V(8); PG8_WAIT_L(0); PG8_BAR; PG8_MMA(1, 0, At, B0); PG8_MMA(1, 1, At, B1); PG8_BAR; PG8_SCHED;
.LBB0_1031:
	ds_read_b128 v[128:131], v167
	ds_read_b128 v[132:135], v167 offset:1024
	ds_read_b128 v[152:155], v167 offset:2048
	ds_read_b128 v[156:159], v167 offset:3072
	ds_read_b128 v[160:163], v168
	ds_read_b128 v[170:173], v168 offset:1024
	ds_read_b128 v[174:177], v168 offset:2048
	ds_read_b128 v[178:181], v168 offset:3072
	s_add_u32 s36, s34, 0xfff00080
	s_addc_u32 s37, s35, -1
	s_cmp_eq_u32 s61, 60
	s_cselect_b32 s39, s25, s37
	s_cselect_b32 s38, s57, s36
	s_cselect_b32 s37, s23, s60
	s_cselect_b32 s36, s58, s59
	s_add_i32 m0, s31, 0xc000
	ds_read_b128 v[182:185], v169
	ds_read_b128 v[186:189], v169 offset:1024
	ds_read_b128 v[190:193], v169 offset:2048
	ds_read_b128 v[194:197], v169 offset:3072
	ds_read_b128 v[198:201], v169 offset:4096
	ds_read_b128 v[202:205], v169 offset:5120
	ds_read_b128 v[206:209], v169 offset:6144
	ds_read_b128 v[210:213], v169 offset:7168
	global_load_lds_dwordx4 v144, s[34:35]
	s_add_i32 m0, s31, 0xe000
	s_nop 0
	global_load_lds_dwordx4 v146, s[34:35]
	s_waitcnt vmcnt(8)
	s_waitcnt lgkmcnt(0)
	s_barrier
	s_setprio 1
	s_waitcnt lgkmcnt(0)
	v_mfma_f32_16x16x32_bf16 v[124:127], v[128:131], v[182:185], v[124:127]
	v_mfma_f32_16x16x32_bf16 v[124:127], v[132:135], v[186:189], v[124:127]
	v_mfma_f32_16x16x32_bf16 v[116:119], v[132:135], v[194:197], v[116:119]
	v_mfma_f32_16x16x32_bf16 v[116:119], v[128:131], v[190:193], v[116:119]
	v_mfma_f32_16x16x32_bf16 v[108:111], v[128:131], v[198:201], v[108:111]
	v_mfma_f32_16x16x32_bf16 v[108:111], v[132:135], v[202:205], v[108:111]
	v_mfma_f32_16x16x32_bf16 v[100:103], v[132:135], v[210:213], v[100:103]
	v_mfma_f32_16x16x32_bf16 v[100:103], v[128:131], v[206:209], v[100:103]
	v_mfma_f32_16x16x32_bf16 v[120:123], v[152:155], v[182:185], v[120:123]
	v_mfma_f32_16x16x32_bf16 v[120:123], v[156:159], v[186:189], v[120:123]
	v_mfma_f32_16x16x32_bf16 v[112:115], v[156:159], v[194:197], v[112:115]
	v_mfma_f32_16x16x32_bf16 v[112:115], v[152:155], v[190:193], v[112:115]
	v_mfma_f32_16x16x32_bf16 v[104:107], v[152:155], v[198:201], v[104:107]
	v_mfma_f32_16x16x32_bf16 v[104:107], v[156:159], v[202:205], v[104:107]
	v_mfma_f32_16x16x32_bf16 v[96:99], v[156:159], v[210:213], v[96:99]
	v_mfma_f32_16x16x32_bf16 v[96:99], v[152:155], v[206:209], v[96:99]
	s_setprio 0
	s_setprio 1
	v_mfma_f32_16x16x32_bf16 v[68:71], v[160:163], v[182:185], v[68:71]
	v_mfma_f32_16x16x32_bf16 v[68:71], v[170:173], v[186:189], v[68:71]
	v_mfma_f32_16x16x32_bf16 v[52:55], v[170:173], v[194:197], v[52:55]
	v_mfma_f32_16x16x32_bf16 v[52:55], v[160:163], v[190:193], v[52:55]
	v_mfma_f32_16x16x32_bf16 v[44:47], v[160:163], v[198:201], v[44:47]
	v_mfma_f32_16x16x32_bf16 v[44:47], v[170:173], v[202:205], v[44:47]
	v_mfma_f32_16x16x32_bf16 v[36:39], v[170:173], v[210:213], v[36:39]
	v_mfma_f32_16x16x32_bf16 v[36:39], v[160:163], v[206:209], v[36:39]
	v_mfma_f32_16x16x32_bf16 v[60:63], v[174:177], v[182:185], v[60:63]
	v_mfma_f32_16x16x32_bf16 v[60:63], v[178:181], v[186:189], v[60:63]
	v_mfma_f32_16x16x32_bf16 v[48:51], v[178:181], v[194:197], v[48:51]
	v_mfma_f32_16x16x32_bf16 v[48:51], v[174:177], v[190:193], v[48:51]
	v_mfma_f32_16x16x32_bf16 v[40:43], v[174:177], v[198:201], v[40:43]
	v_mfma_f32_16x16x32_bf16 v[40:43], v[178:181], v[202:205], v[40:43]
	v_mfma_f32_16x16x32_bf16 v[32:35], v[178:181], v[210:213], v[32:35]
	v_mfma_f32_16x16x32_bf16 v[32:35], v[174:177], v[206:209], v[32:35]
	s_setprio 0
	s_barrier
	s_add_u32 s98, s36, 0x80
	s_addc_u32 s99, s37, 0
	s_add_u32 s100, s38, 0x80
	s_addc_u32 s101, s39, 0
	s_add_i32 s62, s54, s43
	s_mov_b32 m0, s62
	ds_read_b128 v[182:185], v169 offset:16384
	ds_read_b128 v[186:189], v169 offset:17408
	ds_read_b128 v[190:193], v169 offset:18432
	ds_read_b128 v[194:197], v169 offset:19456
	ds_read_b128 v[198:201], v169 offset:20480
	ds_read_b128 v[202:205], v169 offset:21504
	ds_read_b128 v[206:209], v169 offset:22528
	ds_read_b128 v[210:213], v169 offset:23552
	global_load_lds_dwordx4 v138, s[36:37]
	s_add_i32 m0, s62, 0x2000
	s_add_u32 s62, s36, 0x100000
	s_addc_u32 s63, s37, 0
	s_add_i32 s64, s55, s43
	global_load_lds_dwordx4 v142, s[36:37]
	s_mov_b32 m0, s64
	s_nop 0
	global_load_lds_dwordx4 v138, s[62:63]
	s_add_i32 m0, s64, 0x2000
	s_nop 0
	global_load_lds_dwordx4 v142, s[62:63]
	s_mov_b32 m0, s31
	s_nop 0
	global_load_lds_dwordx4 v136, s[38:39]
	s_mov_b32 m0, s44
	s_nop 0
	global_load_lds_dwordx4 v140, s[38:39]
	s_waitcnt vmcnt(8)
	s_waitcnt lgkmcnt(0)
	s_barrier
	s_setprio 1
	s_waitcnt lgkmcnt(0)
	v_mfma_f32_16x16x32_bf16 v[92:95], v[128:131], v[182:185], v[92:95]
	v_mfma_f32_16x16x32_bf16 v[92:95], v[132:135], v[186:189], v[92:95]
	v_mfma_f32_16x16x32_bf16 v[84:87], v[132:135], v[194:197], v[84:87]
	v_mfma_f32_16x16x32_bf16 v[84:87], v[128:131], v[190:193], v[84:87]
	v_mfma_f32_16x16x32_bf16 v[76:79], v[128:131], v[198:201], v[76:79]
	v_mfma_f32_16x16x32_bf16 v[76:79], v[132:135], v[202:205], v[76:79]
	v_mfma_f32_16x16x32_bf16 v[64:67], v[132:135], v[210:213], v[64:67]
	v_mfma_f32_16x16x32_bf16 v[64:67], v[128:131], v[206:209], v[64:67]
	v_mfma_f32_16x16x32_bf16 v[88:91], v[152:155], v[182:185], v[88:91]
	v_mfma_f32_16x16x32_bf16 v[88:91], v[156:159], v[186:189], v[88:91]
	v_mfma_f32_16x16x32_bf16 v[80:83], v[156:159], v[194:197], v[80:83]
	v_mfma_f32_16x16x32_bf16 v[80:83], v[152:155], v[190:193], v[80:83]
	v_mfma_f32_16x16x32_bf16 v[72:75], v[152:155], v[198:201], v[72:75]
	v_mfma_f32_16x16x32_bf16 v[72:75], v[156:159], v[202:205], v[72:75]
	v_mfma_f32_16x16x32_bf16 v[56:59], v[156:159], v[210:213], v[56:59]
	v_mfma_f32_16x16x32_bf16 v[56:59], v[152:155], v[206:209], v[56:59]
	s_setprio 0
	s_setprio 1
	v_mfma_f32_16x16x32_bf16 v[28:31], v[160:163], v[182:185], v[28:31]
	v_mfma_f32_16x16x32_bf16 v[28:31], v[170:173], v[186:189], v[28:31]
	v_mfma_f32_16x16x32_bf16 v[20:23], v[170:173], v[194:197], v[20:23]
	v_mfma_f32_16x16x32_bf16 v[20:23], v[160:163], v[190:193], v[20:23]
	v_mfma_f32_16x16x32_bf16 v[12:15], v[160:163], v[198:201], v[12:15]
	v_mfma_f32_16x16x32_bf16 v[12:15], v[170:173], v[202:205], v[12:15]
	v_mfma_f32_16x16x32_bf16 v[4:7], v[170:173], v[210:213], v[4:7]
	v_mfma_f32_16x16x32_bf16 v[4:7], v[160:163], v[206:209], v[4:7]
	v_mfma_f32_16x16x32_bf16 v[24:27], v[174:177], v[182:185], v[24:27]
	v_mfma_f32_16x16x32_bf16 v[24:27], v[178:181], v[186:189], v[24:27]
	v_mfma_f32_16x16x32_bf16 v[16:19], v[178:181], v[194:197], v[16:19]
	v_mfma_f32_16x16x32_bf16 v[16:19], v[174:177], v[190:193], v[16:19]
	v_mfma_f32_16x16x32_bf16 v[8:11], v[174:177], v[198:201], v[8:11]
	v_mfma_f32_16x16x32_bf16 v[8:11], v[178:181], v[202:205], v[8:11]
	v_mfma_f32_16x16x32_bf16 v[0:3], v[178:181], v[210:213], v[0:3]
	v_mfma_f32_16x16x32_bf16 v[0:3], v[174:177], v[206:209], v[0:3]
	s_setprio 0
	s_barrier
; #define PG8_STAGE(bufoff, gbase, voff) do { _Pragma("unroll") for (int _i = 0; _i < 2; ++_i) \
;         __builtin_amdgcn_global_load_lds((const unsigned*)((const char*)(gbase) + (voff)[_i]), (PG8_LAS unsigned*)(lds + (bufoff) + ldsw + _i * 8192), 16, 0, 0); } while (0)
; #define PG8_LDA(dst, b, h) do { _Pragma("unroll") for (int m = 0; m < 4; ++m) _Pragma("unroll") for (int k = 0; k < 2; ++k) dst[m][k] = *(const PG8_LAS bf16x8*)(lds + PG8_SA(b, h) + aoff + m * 2048 + k * 1024); } while (0)
; #define PG8_LDB(dst, b, h) do { _Pragma("unroll") for (int n = 0; n < 2; ++n) _Pragma("unroll") for (int k = 0; k < 2; ++k) dst[n][k] = *(const PG8_LAS bf16x8*)(lds + PG8_SB(b, h) + boff + n * 2048 + k * 1024); } while (0)
; #define PG8_WAIT_V(n) asm volatile("s_waitcnt vmcnt(" #n ")" ::: "memory")
; #define PG8_WAIT_L(n) asm volatile("s_waitcnt lgkmcnt(" #n ")" ::: "memory")
; #define PG8_BAR __builtin_amdgcn_s_barrier()
; #define PG8_SCHED __builtin_amdgcn_sched_barrier(0)
; template <class Epi, class Sched, bool ALIGN_EPI = false, bool SP2 = false>
; __device__ __forceinline__ void gemm_phase(PG8_LAS unsigned char* lds, const Gemm g, const Sched& S, const Epi& E, int tid_in) {
;     ...
;         for (int t = 0; t < nt; t += 2) {
;             const bool last = (t == nt - 2);
;             const char* a1 = cA + (size_t)(t + 1) * kstep;
;             const char* a2 = last ? nA : cA + (size_t)(t + 2) * kstep; const char* b2 = last ? nB : cB + (size_t)(t + 2) * kstep;
;     ...
;             PG8_LDB(B0, 1, 0); PG8_LDB(B1, 1, 1); PG8_SCHED; PG8_LDA(At, 1, 0); PG8_STAGE(PG8_SA(0, 1), a2 + hstepA, voffA);
;             PG8_WAIT_V(8); PG8_WAIT_L(0); PG8_BAR; PG8_MMA(0, 0, At, B0); PG8_MMA(0, 1, At, B1); PG8_BAR; PG8_SCHED;
;             PG8_LDA(At, 1, 1); PG8_STAGE(PG8_SB(1, 0), b3, voffB); PG8_STAGE(PG8_SB(1, 1), b3 + hstep, voffB); PG8_STAGE(PG8_SA(1, 0), a3, voffA);
;             PG8_WAIT_V(8); PG8_WAIT_L(0); PG8_BAR; PG8_MMA(1, 0, At, B0); PG8_MMA(1, 1, At, B1); PG8_BAR; PG8_SCHED;
	s_add_i32 s62, 0, 0x18000
	s_add_i32 s63, 0, 0x1c000
	v_add_u32_e32 v156, s62, v165
	v_add_u32_e32 v178, s63, v165
	ds_read_b128 v[128:131], v156
	ds_read_b128 v[132:135], v156 offset:1024
	ds_read_b128 v[152:155], v156 offset:2048
	ds_read_b128 v[156:159], v156 offset:3072
	ds_read_b128 v[160:163], v178
	ds_read_b128 v[170:173], v178 offset:1024
	ds_read_b128 v[174:177], v178 offset:2048
	ds_read_b128 v[178:181], v178 offset:3072
	s_add_u32 s38, s38, 0x100000
	s_addc_u32 s39, s39, 0
	s_mov_b32 m0, s45
	ds_read_b128 v[182:185], v169 offset:32768
	ds_read_b128 v[186:189], v169 offset:33792
	ds_read_b128 v[190:193], v169 offset:34816
	ds_read_b128 v[194:197], v169 offset:35840
	ds_read_b128 v[198:201], v169 offset:36864
	ds_read_b128 v[202:205], v169 offset:37888
	ds_read_b128 v[206:209], v169 offset:38912
	ds_read_b128 v[210:213], v169 offset:39936
	global_load_lds_dwordx4 v136, s[38:39]
	s_mov_b32 m0, s46
	s_nop 0
	global_load_lds_dwordx4 v140, s[38:39]
	s_waitcnt vmcnt(8)
	s_waitcnt lgkmcnt(0)
	s_barrier
	s_setprio 1
	s_waitcnt lgkmcnt(0)
	v_mfma_f32_16x16x32_bf16 v[124:127], v[128:131], v[182:185], v[124:127]
	v_mfma_f32_16x16x32_bf16 v[124:127], v[132:135], v[186:189], v[124:127]
	v_mfma_f32_16x16x32_bf16 v[116:119], v[132:135], v[194:197], v[116:119]
	v_mfma_f32_16x16x32_bf16 v[116:119], v[128:131], v[190:193], v[116:119]
	v_mfma_f32_16x16x32_bf16 v[108:111], v[128:131], v[198:201], v[108:111]
	v_mfma_f32_16x16x32_bf16 v[108:111], v[132:135], v[202:205], v[108:111]
	v_mfma_f32_16x16x32_bf16 v[100:103], v[132:135], v[210:213], v[100:103]
	v_mfma_f32_16x16x32_bf16 v[100:103], v[128:131], v[206:209], v[100:103]
	v_mfma_f32_16x16x32_bf16 v[120:123], v[152:155], v[182:185], v[120:123]
	v_mfma_f32_16x16x32_bf16 v[120:123], v[156:159], v[186:189], v[120:123]
	v_mfma_f32_16x16x32_bf16 v[112:115], v[156:159], v[194:197], v[112:115]
	v_mfma_f32_16x16x32_bf16 v[112:115], v[152:155], v[190:193], v[112:115]
	v_mfma_f32_16x16x32_bf16 v[104:107], v[152:155], v[198:201], v[104:107]
	v_mfma_f32_16x16x32_bf16 v[104:107], v[156:159], v[202:205], v[104:107]
	v_mfma_f32_16x16x32_bf16 v[96:99], v[156:159], v[210:213], v[96:99]
	v_mfma_f32_16x16x32_bf16 v[96:99], v[152:155], v[206:209], v[96:99]
	s_setprio 0
	s_setprio 1
	v_mfma_f32_16x16x32_bf16 v[68:71], v[160:163], v[182:185], v[68:71]
	v_mfma_f32_16x16x32_bf16 v[68:71], v[170:173], v[186:189], v[68:71]
	v_mfma_f32_16x16x32_bf16 v[52:55], v[170:173], v[194:197], v[52:55]
	v_mfma_f32_16x16x32_bf16 v[52:55], v[160:163], v[190:193], v[52:55]
	v_mfma_f32_16x16x32_bf16 v[44:47], v[160:163], v[198:201], v[44:47]
	v_mfma_f32_16x16x32_bf16 v[44:47], v[170:173], v[202:205], v[44:47]
	v_mfma_f32_16x16x32_bf16 v[36:39], v[170:173], v[210:213], v[36:39]
	v_mfma_f32_16x16x32_bf16 v[36:39], v[160:163], v[206:209], v[36:39]
	v_mfma_f32_16x16x32_bf16 v[60:63], v[174:177], v[182:185], v[60:63]
	v_mfma_f32_16x16x32_bf16 v[60:63], v[178:181], v[186:189], v[60:63]
	v_mfma_f32_16x16x32_bf16 v[48:51], v[178:181], v[194:197], v[48:51]
	v_mfma_f32_16x16x32_bf16 v[48:51], v[174:177], v[190:193], v[48:51]
	v_mfma_f32_16x16x32_bf16 v[40:43], v[174:177], v[198:201], v[40:43]
	v_mfma_f32_16x16x32_bf16 v[40:43], v[178:181], v[202:205], v[40:43]
	v_mfma_f32_16x16x32_bf16 v[32:35], v[178:181], v[210:213], v[32:35]
	v_mfma_f32_16x16x32_bf16 v[32:35], v[174:177], v[206:209], v[32:35]
	s_setprio 0
	s_barrier
	s_add_i32 s38, s62, s43
	s_mov_b32 m0, s38
	ds_read_b128 v[182:185], v169 offset:49152
	ds_read_b128 v[186:189], v169 offset:50176
	ds_read_b128 v[190:193], v169 offset:51200
	ds_read_b128 v[194:197], v169 offset:52224
	ds_read_b128 v[198:201], v169 offset:53248
	ds_read_b128 v[202:205], v169 offset:54272
	ds_read_b128 v[206:209], v169 offset:55296
	ds_read_b128 v[210:213], v169 offset:56320
	global_load_lds_dwordx4 v138, s[98:99]
	s_add_i32 m0, s38, 0x2000
	s_add_u32 s36, s36, 0x100080
	s_addc_u32 s37, s37, 0
	s_add_i32 s38, s63, s43
	global_load_lds_dwordx4 v142, s[98:99]
	s_mov_b32 m0, s38
	s_nop 0
	global_load_lds_dwordx4 v138, s[36:37]
	s_add_i32 m0, s38, 0x2000
	s_nop 0
	global_load_lds_dwordx4 v142, s[36:37]
	s_mov_b32 m0, s51
	s_nop 0
	global_load_lds_dwordx4 v136, s[100:101]
	s_mov_b32 m0, s52
	s_nop 0
	global_load_lds_dwordx4 v140, s[100:101]
	s_waitcnt vmcnt(8)
	s_waitcnt lgkmcnt(0)
	s_barrier
	s_setprio 1
	s_waitcnt lgkmcnt(0)
	v_mfma_f32_16x16x32_bf16 v[92:95], v[128:131], v[182:185], v[92:95]
	v_mfma_f32_16x16x32_bf16 v[92:95], v[132:135], v[186:189], v[92:95]
	v_mfma_f32_16x16x32_bf16 v[84:87], v[132:135], v[194:197], v[84:87]
	v_mfma_f32_16x16x32_bf16 v[84:87], v[128:131], v[190:193], v[84:87]
	v_mfma_f32_16x16x32_bf16 v[76:79], v[128:131], v[198:201], v[76:79]
	v_mfma_f32_16x16x32_bf16 v[76:79], v[132:135], v[202:205], v[76:79]
	v_mfma_f32_16x16x32_bf16 v[64:67], v[132:135], v[210:213], v[64:67]
	v_mfma_f32_16x16x32_bf16 v[64:67], v[128:131], v[206:209], v[64:67]
	v_mfma_f32_16x16x32_bf16 v[88:91], v[152:155], v[182:185], v[88:91]
	v_mfma_f32_16x16x32_bf16 v[88:91], v[156:159], v[186:189], v[88:91]
	v_mfma_f32_16x16x32_bf16 v[80:83], v[156:159], v[194:197], v[80:83]
	v_mfma_f32_16x16x32_bf16 v[80:83], v[152:155], v[190:193], v[80:83]
	v_mfma_f32_16x16x32_bf16 v[72:75], v[152:155], v[198:201], v[72:75]
	v_mfma_f32_16x16x32_bf16 v[72:75], v[156:159], v[202:205], v[72:75]
	v_mfma_f32_16x16x32_bf16 v[56:59], v[156:159], v[210:213], v[56:59]
	v_mfma_f32_16x16x32_bf16 v[56:59], v[152:155], v[206:209], v[56:59]
	s_setprio 0
	s_setprio 1
	v_mfma_f32_16x16x32_bf16 v[28:31], v[160:163], v[182:185], v[28:31]
	v_mfma_f32_16x16x32_bf16 v[28:31], v[170:173], v[186:189], v[28:31]
	v_mfma_f32_16x16x32_bf16 v[20:23], v[170:173], v[194:197], v[20:23]
	v_mfma_f32_16x16x32_bf16 v[20:23], v[160:163], v[190:193], v[20:23]
	v_mfma_f32_16x16x32_bf16 v[12:15], v[160:163], v[198:201], v[12:15]
	v_mfma_f32_16x16x32_bf16 v[12:15], v[170:173], v[202:205], v[12:15]
	v_mfma_f32_16x16x32_bf16 v[4:7], v[170:173], v[210:213], v[4:7]
	v_mfma_f32_16x16x32_bf16 v[4:7], v[160:163], v[206:209], v[4:7]
	v_mfma_f32_16x16x32_bf16 v[24:27], v[174:177], v[182:185], v[24:27]
	v_mfma_f32_16x16x32_bf16 v[24:27], v[178:181], v[186:189], v[24:27]
	v_mfma_f32_16x16x32_bf16 v[16:19], v[178:181], v[194:197], v[16:19]
	v_mfma_f32_16x16x32_bf16 v[16:19], v[174:177], v[190:193], v[16:19]
	v_mfma_f32_16x16x32_bf16 v[8:11], v[174:177], v[198:201], v[8:11]
	v_mfma_f32_16x16x32_bf16 v[8:11], v[178:181], v[202:205], v[8:11]
	v_mfma_f32_16x16x32_bf16 v[0:3], v[178:181], v[210:213], v[0:3]
	v_mfma_f32_16x16x32_bf16 v[0:3], v[174:177], v[206:209], v[0:3]
	s_setprio 0
	s_barrier
	s_add_i32 s61, s61, 2
	s_add_u32 s34, s34, 0x100
	s_addc_u32 s35, s35, 0
	s_add_u32 s59, s59, 0x100
	s_addc_u32 s60, s60, 0
	s_cmp_gt_u32 s61, 61
	s_cbranch_scc0 .LBB0_1031
	s_and_b64 vcc, exec, s[10:11]
	s_cbranch_vccz .LBB0_1034
	s_barrier
;     __device__ __forceinline__ void operator()(const f32x4 (&acc)[2][2][4][2], const Unit& u, int wr, int wc, int fr, int fq) const {
;         const int row0 = u.pm * BM + wr * 64 + fr, col0 = u.pn * BM + wc * 32 + 8 * fq;
;         const float* g = gate + (size_t)(u.pm >> 4) * 24576;
; #pragma unroll
;         for (int bj = 0; bj < 2; ++bj) { const int col = col0 + bj * HALF; const f32x4 g0 = *(const f32x4*)(g + col), g1 = *(const f32x4*)(g + col + 4);
; #pragma unroll
;             for (int ai = 0; ai < 2; ++ai)
; #pragma unroll
;                 for (int m = 0; m < 4; ++m) { const size_t off = (size_t)(row0 + ai * HALF + m * 16) * 4096 + col;
;                     const f32x4 x0 = *(const f32x4*)(base + off), x1 = *(const f32x4*)(base + off + 4);
;                     *(f32x4*)(out + off) = x0 * alpha + g0 * acc[ai][bj][m][0]; *(f32x4*)(out + off + 4) = x1 * alpha + g1 * acc[ai][bj][m][1]; } }
;     }
.LBB0_1034:
	v_lshl_add_u32 v178, s30, 8, v164
	v_lshl_or_b32 v152, s56, 8, v166
	v_ashrrev_i32_e32 v179, 31, v178
	v_lshlrev_b64 v[154:155], 12, v[178:179]
	v_ashrrev_i32_e32 v153, 31, v152
	v_readlane_b32 s56, v254, 0
	s_ashr_i32 s23, s30, 4
	v_lshl_add_u64 v[128:129], v[154:155], 0, v[152:153]
	v_readlane_b32 s57, v254, 1
	s_mul_hi_i32 s25, s23, 0x18000
	s_mul_i32 s23, s23, 0x18000
	v_lshlrev_b64 v[160:161], 2, v[128:129]
	s_mov_b64 s[36:37], s[56:57]
	v_lshl_add_u64 v[158:159], s[36:37], 0, v[160:161]
	s_add_u32 s34, s49, s23
	global_load_dwordx4 v[170:173], v[158:159], off offset:16
	global_load_dwordx4 v[174:177], v[158:159], off
	s_addc_u32 s35, s50, s25
	v_lshl_add_u64 v[162:163], v[152:153], 2, s[34:35]
	global_load_dwordx4 v[132:135], v[162:163], off
	global_load_dwordx4 v[128:131], v[162:163], off offset:16
	v_or_b32_e32 v156, 16, v178
	v_ashrrev_i32_e32 v157, 31, v156
	v_lshlrev_b64 v[156:157], 12, v[156:157]
	v_lshl_add_u64 v[180:181], v[156:157], 0, v[152:153]
	v_lshl_add_u64 v[182:183], s[6:7], 0, v[160:161]
	v_lshlrev_b64 v[180:181], 2, v[180:181]
	v_lshl_add_u64 v[160:161], s[36:37], 0, v[180:181]
	s_andn2_b64 vcc, exec, s[2:3]
	s_mov_b64 s[2:3], -1
	v_readlane_b32 s58, v254, 2
	v_readlane_b32 s59, v254, 3
	v_readlane_b32 s60, v254, 4
	v_readlane_b32 s61, v254, 5
	v_readlane_b32 s62, v254, 6
	v_readlane_b32 s63, v254, 7
	v_readlane_b32 s64, v254, 8
	v_readlane_b32 s65, v254, 9
	v_readlane_b32 s66, v254, 10
	v_readlane_b32 s67, v254, 11
	v_readlane_b32 s68, v254, 12
	v_readlane_b32 s69, v254, 13
	v_readlane_b32 s70, v254, 14
	v_readlane_b32 s71, v254, 15
	s_waitcnt vmcnt(0)
	v_pk_mul_f32 v[172:173], v[172:173], s[14:15] op_sel_hi:[1,0]
	v_pk_mul_f32 v[176:177], v[176:177], s[14:15] op_sel_hi:[1,0]
	v_pk_mul_f32 v[174:175], v[174:175], s[14:15] op_sel_hi:[1,0]
	v_pk_mul_f32 v[170:171], v[170:171], s[14:15] op_sel_hi:[1,0]
	v_pk_fma_f32 v[126:127], v[126:127], v[134:135], v[176:177]
	v_pk_fma_f32 v[124:125], v[124:125], v[132:133], v[174:175]
	v_pk_fma_f32 v[122:123], v[122:123], v[130:131], v[172:173]
	v_pk_fma_f32 v[120:121], v[120:121], v[128:129], v[170:171]
	global_store_dwordx4 v[182:183], v[124:127], off
	global_store_dwordx4 v[182:183], v[120:123], off offset:16
	global_load_dwordx4 v[124:127], v[160:161], off
	s_nop 0
	global_load_dwordx4 v[170:173], v[160:161], off offset:16
	v_or_b32_e32 v120, 32, v178
	v_ashrrev_i32_e32 v121, 31, v120
	v_lshlrev_b64 v[120:121], 12, v[120:121]
	v_lshl_add_u64 v[122:123], v[120:121], 0, v[152:153]
	v_lshlrev_b64 v[174:175], 2, v[122:123]
	v_lshl_add_u64 v[176:177], s[6:7], 0, v[180:181]
	v_lshl_add_u64 v[122:123], s[36:37], 0, v[174:175]
	s_waitcnt vmcnt(1)
	v_pk_mul_f32 v[126:127], v[126:127], s[14:15] op_sel_hi:[1,0]
	v_pk_mul_f32 v[124:125], v[124:125], s[14:15] op_sel_hi:[1,0]
	s_waitcnt vmcnt(0)
	v_pk_mul_f32 v[172:173], v[172:173], s[14:15] op_sel_hi:[1,0]
	v_pk_mul_f32 v[170:171], v[170:171], s[14:15] op_sel_hi:[1,0]
	v_pk_fma_f32 v[118:119], v[118:119], v[134:135], v[126:127]
	v_pk_fma_f32 v[116:117], v[116:117], v[132:133], v[124:125]
	v_pk_fma_f32 v[114:115], v[114:115], v[130:131], v[172:173]
	v_pk_fma_f32 v[112:113], v[112:113], v[128:129], v[170:171]
	global_store_dwordx4 v[176:177], v[116:119], off
	global_store_dwordx4 v[176:177], v[112:115], off offset:16
	global_load_dwordx4 v[116:119], v[122:123], off
	s_nop 0
	global_load_dwordx4 v[124:127], v[122:123], off offset:16
	v_or_b32_e32 v112, 48, v178
	v_ashrrev_i32_e32 v113, 31, v112
	v_lshlrev_b64 v[112:113], 12, v[112:113]
	v_lshl_add_u64 v[114:115], v[112:113], 0, v[152:153]
	v_lshlrev_b64 v[170:171], 2, v[114:115]
	v_lshl_add_u64 v[172:173], s[6:7], 0, v[174:175]
	v_lshl_add_u64 v[114:115], s[36:37], 0, v[170:171]
	s_waitcnt vmcnt(1)
	v_pk_mul_f32 v[118:119], v[118:119], s[14:15] op_sel_hi:[1,0]
	v_pk_mul_f32 v[116:117], v[116:117], s[14:15] op_sel_hi:[1,0]
	s_waitcnt vmcnt(0)
	v_pk_mul_f32 v[126:127], v[126:127], s[14:15] op_sel_hi:[1,0]
	v_pk_mul_f32 v[124:125], v[124:125], s[14:15] op_sel_hi:[1,0]
	v_pk_fma_f32 v[110:111], v[110:111], v[134:135], v[118:119]
	v_pk_fma_f32 v[108:109], v[108:109], v[132:133], v[116:117]
	v_pk_fma_f32 v[106:107], v[106:107], v[130:131], v[126:127]
	v_pk_fma_f32 v[104:105], v[104:105], v[128:129], v[124:125]
	global_store_dwordx4 v[172:173], v[108:111], off
	global_store_dwordx4 v[172:173], v[104:107], off offset:16
	global_load_dwordx4 v[108:111], v[114:115], off
	s_nop 0
	global_load_dwordx4 v[116:119], v[114:115], off offset:16
	v_lshl_add_u64 v[104:105], v[154:155], 0, s[12:13]
	v_lshl_add_u64 v[106:107], v[104:105], 0, v[152:153]
	v_lshlrev_b64 v[124:125], 2, v[106:107]
	v_lshl_add_u64 v[126:127], s[6:7], 0, v[170:171]
	v_lshl_add_u64 v[106:107], s[36:37], 0, v[124:125]
	s_waitcnt vmcnt(1)
	v_pk_mul_f32 v[110:111], v[110:111], s[14:15] op_sel_hi:[1,0]
	v_pk_mul_f32 v[108:109], v[108:109], s[14:15] op_sel_hi:[1,0]
	s_waitcnt vmcnt(0)
	v_pk_mul_f32 v[118:119], v[118:119], s[14:15] op_sel_hi:[1,0]
	v_pk_mul_f32 v[116:117], v[116:117], s[14:15] op_sel_hi:[1,0]
	v_pk_fma_f32 v[102:103], v[102:103], v[134:135], v[110:111]
	v_pk_fma_f32 v[100:101], v[100:101], v[132:133], v[108:109]
	v_pk_fma_f32 v[98:99], v[98:99], v[130:131], v[118:119]
	v_pk_fma_f32 v[96:97], v[96:97], v[128:129], v[116:117]
	global_store_dwordx4 v[126:127], v[100:103], off
	global_store_dwordx4 v[126:127], v[96:99], off offset:16
	global_load_dwordx4 v[100:103], v[106:107], off
	s_nop 0
	global_load_dwordx4 v[108:111], v[106:107], off offset:16
	v_lshl_add_u64 v[96:97], v[154:155], 0, s[16:17]
	v_lshl_add_u64 v[98:99], v[96:97], 0, v[152:153]
	v_lshlrev_b64 v[116:117], 2, v[98:99]
	v_lshl_add_u64 v[118:119], s[6:7], 0, v[124:125]
	v_lshl_add_u64 v[98:99], s[36:37], 0, v[116:117]
	s_waitcnt vmcnt(1)
;     __device__ __forceinline__ void operator()(const f32x4 (&acc)[2][2][4][2], const Unit& u, int wr, int wc, int fr, int fq) const {
;         const int row0 = u.pm * BM + wr * 64 + fr, col0 = u.pn * BM + wc * 32 + 8 * fq;
;         const float* g = gate + (size_t)(u.pm >> 4) * 24576;
; #pragma unroll
;         for (int bj = 0; bj < 2; ++bj) { const int col = col0 + bj * HALF; const f32x4 g0 = *(const f32x4*)(g + col), g1 = *(const f32x4*)(g + col + 4);
; #pragma unroll
;             for (int ai = 0; ai < 2; ++ai)
; #pragma unroll
;                 for (int m = 0; m < 4; ++m) { const size_t off = (size_t)(row0 + ai * HALF + m * 16) * 4096 + col;
;                     const f32x4 x0 = *(const f32x4*)(base + off), x1 = *(const f32x4*)(base + off + 4);
;                     *(f32x4*)(out + off) = x0 * alpha + g0 * acc[ai][bj][m][0]; *(f32x4*)(out + off + 4) = x1 * alpha + g1 * acc[ai][bj][m][1]; } }
;     }
	v_pk_mul_f32 v[102:103], v[102:103], s[14:15] op_sel_hi:[1,0]
	v_pk_mul_f32 v[100:101], v[100:101], s[14:15] op_sel_hi:[1,0]
	s_waitcnt vmcnt(0)
	v_pk_mul_f32 v[110:111], v[110:111], s[14:15] op_sel_hi:[1,0]
	v_pk_mul_f32 v[108:109], v[108:109], s[14:15] op_sel_hi:[1,0]
	v_pk_fma_f32 v[94:95], v[94:95], v[134:135], v[102:103]
	v_pk_fma_f32 v[92:93], v[92:93], v[132:133], v[100:101]
	v_pk_fma_f32 v[90:91], v[90:91], v[130:131], v[110:111]
	v_pk_fma_f32 v[88:89], v[88:89], v[128:129], v[108:109]
	global_store_dwordx4 v[118:119], v[92:95], off
	global_store_dwordx4 v[118:119], v[88:91], off offset:16
	global_load_dwordx4 v[92:95], v[98:99], off
	s_nop 0
	global_load_dwordx4 v[100:103], v[98:99], off offset:16
	v_lshl_add_u64 v[88:89], v[154:155], 0, s[18:19]
	v_lshl_add_u64 v[90:91], v[88:89], 0, v[152:153]
	v_lshlrev_b64 v[108:109], 2, v[90:91]
	v_lshl_add_u64 v[110:111], s[6:7], 0, v[116:117]
	v_lshl_add_u64 v[90:91], s[36:37], 0, v[108:109]
	s_waitcnt vmcnt(1)
	v_pk_mul_f32 v[94:95], v[94:95], s[14:15] op_sel_hi:[1,0]
	v_pk_mul_f32 v[92:93], v[92:93], s[14:15] op_sel_hi:[1,0]
	s_waitcnt vmcnt(0)
	v_pk_mul_f32 v[102:103], v[102:103], s[14:15] op_sel_hi:[1,0]
	v_pk_mul_f32 v[100:101], v[100:101], s[14:15] op_sel_hi:[1,0]
	v_pk_fma_f32 v[86:87], v[86:87], v[134:135], v[94:95]
	v_pk_fma_f32 v[84:85], v[84:85], v[132:133], v[92:93]
	v_pk_fma_f32 v[82:83], v[82:83], v[130:131], v[102:103]
	v_pk_fma_f32 v[80:81], v[80:81], v[128:129], v[100:101]
	global_store_dwordx4 v[110:111], v[84:87], off
	global_store_dwordx4 v[110:111], v[80:83], off offset:16
	global_load_dwordx4 v[84:87], v[90:91], off
	s_nop 0
	global_load_dwordx4 v[92:95], v[90:91], off offset:16
	v_lshl_add_u64 v[80:81], v[154:155], 0, s[20:21]
	v_lshl_add_u64 v[82:83], v[80:81], 0, v[152:153]
	v_lshlrev_b64 v[100:101], 2, v[82:83]
	v_lshl_add_u64 v[102:103], s[6:7], 0, v[108:109]
	v_lshl_add_u64 v[82:83], s[36:37], 0, v[100:101]
	s_waitcnt vmcnt(1)
	v_pk_mul_f32 v[86:87], v[86:87], s[14:15] op_sel_hi:[1,0]
	v_pk_mul_f32 v[84:85], v[84:85], s[14:15] op_sel_hi:[1,0]
	s_waitcnt vmcnt(0)
	v_pk_mul_f32 v[94:95], v[94:95], s[14:15] op_sel_hi:[1,0]
	v_pk_mul_f32 v[92:93], v[92:93], s[14:15] op_sel_hi:[1,0]
	v_pk_fma_f32 v[78:79], v[78:79], v[134:135], v[86:87]
	v_pk_fma_f32 v[76:77], v[76:77], v[132:133], v[84:85]
	v_pk_fma_f32 v[74:75], v[74:75], v[130:131], v[94:95]
	v_pk_fma_f32 v[72:73], v[72:73], v[128:129], v[92:93]
	global_store_dwordx4 v[102:103], v[76:79], off
	global_store_dwordx4 v[102:103], v[72:75], off offset:16
	global_load_dwordx4 v[72:75], v[82:83], off
	s_nop 0
	global_load_dwordx4 v[76:79], v[82:83], off offset:16
	v_lshl_add_u64 v[84:85], s[6:7], 0, v[100:101]
	s_waitcnt vmcnt(1)
	v_pk_mul_f32 v[74:75], v[74:75], s[14:15] op_sel_hi:[1,0]
	v_pk_mul_f32 v[72:73], v[72:73], s[14:15] op_sel_hi:[1,0]
	s_waitcnt vmcnt(0)
	v_pk_mul_f32 v[78:79], v[78:79], s[14:15] op_sel_hi:[1,0]
	v_pk_mul_f32 v[76:77], v[76:77], s[14:15] op_sel_hi:[1,0]
	v_pk_fma_f32 v[66:67], v[66:67], v[134:135], v[74:75]
	v_pk_fma_f32 v[64:65], v[64:65], v[132:133], v[72:73]
	v_pk_fma_f32 v[58:59], v[58:59], v[130:131], v[78:79]
	v_pk_fma_f32 v[56:57], v[56:57], v[128:129], v[76:77]
	global_store_dwordx4 v[84:85], v[64:67], off
	global_store_dwordx4 v[84:85], v[56:59], off offset:16
	global_load_dwordx4 v[74:77], v[158:159], off offset:512
	s_nop 0
	global_load_dwordx4 v[84:87], v[158:159], off offset:528
	global_load_dwordx4 v[64:67], v[162:163], off offset:512
	global_load_dwordx4 v[56:59], v[162:163], off offset:528
	v_or_b32_e32 v72, 0x80, v152
	v_ashrrev_i32_e32 v73, 31, v72
	v_lshl_add_u64 v[78:79], v[154:155], 0, v[72:73]
	v_lshl_add_u64 v[78:79], v[78:79], 2, s[6:7]
	s_waitcnt vmcnt(3)
	v_pk_mul_f32 v[76:77], v[76:77], s[14:15] op_sel_hi:[1,0]
	v_pk_mul_f32 v[74:75], v[74:75], s[14:15] op_sel_hi:[1,0]
	s_waitcnt vmcnt(2)
	v_pk_mul_f32 v[86:87], v[86:87], s[14:15] op_sel_hi:[1,0]
	v_pk_mul_f32 v[84:85], v[84:85], s[14:15] op_sel_hi:[1,0]
	s_waitcnt vmcnt(1)
	v_pk_fma_f32 v[70:71], v[70:71], v[66:67], v[76:77]
	v_pk_fma_f32 v[68:69], v[68:69], v[64:65], v[74:75]
	s_waitcnt vmcnt(0)
	v_pk_fma_f32 v[62:63], v[62:63], v[58:59], v[86:87]
	v_pk_fma_f32 v[60:61], v[60:61], v[56:57], v[84:85]
	global_store_dwordx4 v[78:79], v[68:71], off
	global_store_dwordx4 v[78:79], v[60:63], off offset:16
	global_load_dwordx4 v[60:63], v[160:161], off offset:512
	s_nop 0
	global_load_dwordx4 v[68:71], v[160:161], off offset:528
	v_lshl_add_u64 v[74:75], v[156:157], 0, v[72:73]
	v_lshl_add_u64 v[74:75], v[74:75], 2, s[6:7]
	s_waitcnt vmcnt(1)
	v_pk_mul_f32 v[62:63], v[62:63], s[14:15] op_sel_hi:[1,0]
	v_pk_mul_f32 v[60:61], v[60:61], s[14:15] op_sel_hi:[1,0]
	s_waitcnt vmcnt(0)
	v_pk_mul_f32 v[70:71], v[70:71], s[14:15] op_sel_hi:[1,0]
	v_pk_mul_f32 v[68:69], v[68:69], s[14:15] op_sel_hi:[1,0]
	v_pk_fma_f32 v[54:55], v[54:55], v[66:67], v[62:63]
	v_pk_fma_f32 v[52:53], v[52:53], v[64:65], v[60:61]
	v_pk_fma_f32 v[50:51], v[50:51], v[58:59], v[70:71]
	v_pk_fma_f32 v[48:49], v[48:49], v[56:57], v[68:69]
	global_store_dwordx4 v[74:75], v[52:55], off
	global_store_dwordx4 v[74:75], v[48:51], off offset:16
	global_load_dwordx4 v[48:51], v[122:123], off offset:512
	s_nop 0
	global_load_dwordx4 v[52:55], v[122:123], off offset:528
	v_lshl_add_u64 v[60:61], v[120:121], 0, v[72:73]
	v_lshl_add_u64 v[60:61], v[60:61], 2, s[6:7]
	s_waitcnt vmcnt(1)
;     __device__ __forceinline__ void operator()(const f32x4 (&acc)[2][2][4][2], const Unit& u, int wr, int wc, int fr, int fq) const {
;         const int row0 = u.pm * BM + wr * 64 + fr, col0 = u.pn * BM + wc * 32 + 8 * fq;
;         const float* g = gate + (size_t)(u.pm >> 4) * 24576;
; #pragma unroll
;         for (int bj = 0; bj < 2; ++bj) { const int col = col0 + bj * HALF; const f32x4 g0 = *(const f32x4*)(g + col), g1 = *(const f32x4*)(g + col + 4);
; #pragma unroll
;             for (int ai = 0; ai < 2; ++ai)
; #pragma unroll
;                 for (int m = 0; m < 4; ++m) { const size_t off = (size_t)(row0 + ai * HALF + m * 16) * 4096 + col;
;                     const f32x4 x0 = *(const f32x4*)(base + off), x1 = *(const f32x4*)(base + off + 4);
;                     *(f32x4*)(out + off) = x0 * alpha + g0 * acc[ai][bj][m][0]; *(f32x4*)(out + off + 4) = x1 * alpha + g1 * acc[ai][bj][m][1]; } }
;     }
	v_pk_mul_f32 v[50:51], v[50:51], s[14:15] op_sel_hi:[1,0]
	v_pk_mul_f32 v[48:49], v[48:49], s[14:15] op_sel_hi:[1,0]
	s_waitcnt vmcnt(0)
	v_pk_mul_f32 v[54:55], v[54:55], s[14:15] op_sel_hi:[1,0]
	v_pk_mul_f32 v[52:53], v[52:53], s[14:15] op_sel_hi:[1,0]
	v_pk_fma_f32 v[46:47], v[46:47], v[66:67], v[50:51]
	v_pk_fma_f32 v[44:45], v[44:45], v[64:65], v[48:49]
	v_pk_fma_f32 v[42:43], v[42:43], v[58:59], v[54:55]
	v_pk_fma_f32 v[40:41], v[40:41], v[56:57], v[52:53]
	global_store_dwordx4 v[60:61], v[44:47], off
	global_store_dwordx4 v[60:61], v[40:43], off offset:16
	global_load_dwordx4 v[40:43], v[114:115], off offset:512
	s_nop 0
	global_load_dwordx4 v[44:47], v[114:115], off offset:528
	v_lshl_add_u64 v[48:49], v[112:113], 0, v[72:73]
	v_lshl_add_u64 v[48:49], v[48:49], 2, s[6:7]
	s_waitcnt vmcnt(1)
	v_pk_mul_f32 v[42:43], v[42:43], s[14:15] op_sel_hi:[1,0]
	v_pk_mul_f32 v[40:41], v[40:41], s[14:15] op_sel_hi:[1,0]
	s_waitcnt vmcnt(0)
	v_pk_mul_f32 v[46:47], v[46:47], s[14:15] op_sel_hi:[1,0]
	v_pk_mul_f32 v[44:45], v[44:45], s[14:15] op_sel_hi:[1,0]
	v_pk_fma_f32 v[38:39], v[38:39], v[66:67], v[42:43]
	v_pk_fma_f32 v[36:37], v[36:37], v[64:65], v[40:41]
	v_pk_fma_f32 v[34:35], v[34:35], v[58:59], v[46:47]
	v_pk_fma_f32 v[32:33], v[32:33], v[56:57], v[44:45]
	global_store_dwordx4 v[48:49], v[36:39], off
	global_store_dwordx4 v[48:49], v[32:35], off offset:16
	global_load_dwordx4 v[32:35], v[106:107], off offset:512
	s_nop 0
	global_load_dwordx4 v[36:39], v[106:107], off offset:528
	v_lshl_add_u64 v[40:41], v[104:105], 0, v[72:73]
	v_lshl_add_u64 v[40:41], v[40:41], 2, s[6:7]
	s_waitcnt vmcnt(1)
	v_pk_mul_f32 v[34:35], v[34:35], s[14:15] op_sel_hi:[1,0]
	v_pk_mul_f32 v[32:33], v[32:33], s[14:15] op_sel_hi:[1,0]
	s_waitcnt vmcnt(0)
	v_pk_mul_f32 v[38:39], v[38:39], s[14:15] op_sel_hi:[1,0]
	v_pk_mul_f32 v[36:37], v[36:37], s[14:15] op_sel_hi:[1,0]
	v_pk_fma_f32 v[30:31], v[30:31], v[66:67], v[34:35]
	v_pk_fma_f32 v[28:29], v[28:29], v[64:65], v[32:33]
	v_pk_fma_f32 v[26:27], v[26:27], v[58:59], v[38:39]
	v_pk_fma_f32 v[24:25], v[24:25], v[56:57], v[36:37]
	global_store_dwordx4 v[40:41], v[28:31], off
	global_store_dwordx4 v[40:41], v[24:27], off offset:16
	global_load_dwordx4 v[24:27], v[98:99], off offset:512
	s_nop 0
	global_load_dwordx4 v[28:31], v[98:99], off offset:528
	v_lshl_add_u64 v[32:33], v[96:97], 0, v[72:73]
	v_lshl_add_u64 v[32:33], v[32:33], 2, s[6:7]
	s_waitcnt vmcnt(1)
	v_pk_mul_f32 v[26:27], v[26:27], s[14:15] op_sel_hi:[1,0]
	v_pk_mul_f32 v[24:25], v[24:25], s[14:15] op_sel_hi:[1,0]
	s_waitcnt vmcnt(0)
	v_pk_mul_f32 v[30:31], v[30:31], s[14:15] op_sel_hi:[1,0]
	v_pk_mul_f32 v[28:29], v[28:29], s[14:15] op_sel_hi:[1,0]
	v_pk_fma_f32 v[22:23], v[22:23], v[66:67], v[26:27]
	v_pk_fma_f32 v[20:21], v[20:21], v[64:65], v[24:25]
	v_pk_fma_f32 v[18:19], v[18:19], v[58:59], v[30:31]
	v_pk_fma_f32 v[16:17], v[16:17], v[56:57], v[28:29]
	global_store_dwordx4 v[32:33], v[20:23], off
	global_store_dwordx4 v[32:33], v[16:19], off offset:16
	global_load_dwordx4 v[16:19], v[90:91], off offset:512
	s_nop 0
	global_load_dwordx4 v[20:23], v[90:91], off offset:528
	v_lshl_add_u64 v[24:25], v[88:89], 0, v[72:73]
	v_lshl_add_u64 v[24:25], v[24:25], 2, s[6:7]
	s_waitcnt vmcnt(1)
	v_pk_mul_f32 v[18:19], v[18:19], s[14:15] op_sel_hi:[1,0]
	v_pk_mul_f32 v[16:17], v[16:17], s[14:15] op_sel_hi:[1,0]
	s_waitcnt vmcnt(0)
	v_pk_mul_f32 v[22:23], v[22:23], s[14:15] op_sel_hi:[1,0]
	v_pk_mul_f32 v[20:21], v[20:21], s[14:15] op_sel_hi:[1,0]
	v_pk_fma_f32 v[14:15], v[14:15], v[66:67], v[18:19]
	v_pk_fma_f32 v[12:13], v[12:13], v[64:65], v[16:17]
	v_pk_fma_f32 v[10:11], v[10:11], v[58:59], v[22:23]
	v_pk_fma_f32 v[8:9], v[8:9], v[56:57], v[20:21]
	global_store_dwordx4 v[24:25], v[12:15], off
	global_store_dwordx4 v[24:25], v[8:11], off offset:16
	global_load_dwordx4 v[8:11], v[82:83], off offset:512
	s_nop 0
	global_load_dwordx4 v[12:15], v[82:83], off offset:528
	v_lshl_add_u64 v[16:17], v[80:81], 0, v[72:73]
	v_lshl_add_u64 v[16:17], v[16:17], 2, s[6:7]
	s_waitcnt vmcnt(1)
	v_pk_mul_f32 v[10:11], v[10:11], s[14:15] op_sel_hi:[1,0]
	v_pk_mul_f32 v[8:9], v[8:9], s[14:15] op_sel_hi:[1,0]
	s_waitcnt vmcnt(0)
	v_pk_mul_f32 v[14:15], v[14:15], s[14:15] op_sel_hi:[1,0]
	v_pk_mul_f32 v[12:13], v[12:13], s[14:15] op_sel_hi:[1,0]
	v_pk_fma_f32 v[6:7], v[6:7], v[66:67], v[10:11]
	v_pk_fma_f32 v[4:5], v[4:5], v[64:65], v[8:9]
	v_pk_fma_f32 v[2:3], v[2:3], v[58:59], v[14:15]
	v_pk_fma_f32 v[0:1], v[0:1], v[56:57], v[12:13]
	global_store_dwordx4 v[16:17], v[4:7], off
	global_store_dwordx4 v[16:17], v[0:3], off offset:16
	s_cbranch_vccnz .LBB0_1023
	s_andn2_b64 vcc, exec, s[4:5]
	s_cbranch_vccnz .LBB0_1022
	s_barrier
	s_branch .LBB0_1022

; #define PG8_STAGE(bufoff, gbase, voff) do { _Pragma("unroll") for (int _i = 0; _i < 2; ++_i) \
;         __builtin_amdgcn_global_load_lds((const unsigned*)((const char*)(gbase) + (voff)[_i]), (PG8_LAS unsigned*)(lds + (bufoff) + ldsw + _i * 8192), 16, 0, 0); } while (0)
; #define PG8_LDA(dst, b, h) do { _Pragma("unroll") for (int m = 0; m < 4; ++m) _Pragma("unroll") for (int k = 0; k < 2; ++k) dst[m][k] = *(const PG8_LAS bf16x8*)(lds + PG8_SA(b, h) + aoff + m * 2048 + k * 1024); } while (0)
; #define PG8_LDB(dst, b, h) do { _Pragma("unroll") for (int n = 0; n < 2; ++n) _Pragma("unroll") for (int k = 0; k < 2; ++k) dst[n][k] = *(const PG8_LAS bf16x8*)(lds + PG8_SB(b, h) + boff + n * 2048 + k * 1024); } while (0)
; #define PG8_WAIT_V(n) asm volatile("s_waitcnt vmcnt(" #n ")" ::: "memory")
; #define PG8_WAIT_L(n) asm volatile("s_waitcnt lgkmcnt(" #n ")" ::: "memory")
; #define PG8_BAR __builtin_amdgcn_s_barrier()
; #define PG8_SCHED __builtin_amdgcn_sched_barrier(0)
; template <class Epi, class Sched, bool ALIGN_EPI = false, bool SP2 = false>
; __device__ __forceinline__ void gemm_phase(PG8_LAS unsigned char* lds, const Gemm g, const Sched& S, const Epi& E, int tid_in) {
;     ...
;             PG8_LDB(B0, 0, 0); PG8_LDB(B1, 0, 1); PG8_SCHED; PG8_LDA(At, 0, 0); PG8_STAGE(PG8_SA(1, 1), a1 + hstepA, voffA);
;             PG8_WAIT_V(8); PG8_WAIT_L(0); PG8_BAR; PG8_MMA(0, 0, At, B0); PG8_MMA(0, 1, At, B1); PG8_BAR; PG8_SCHED;
;             PG8_LDA(At, 0, 1); PG8_STAGE(PG8_SB(0, 0), b2, voffB); PG8_STAGE(PG8_SB(0, 1), b2 + hstep, voffB); PG8_STAGE(PG8_SA(0, 0), a2, voffA);
;             PG8_WAIT_V(8); PG8_WAIT_L(0); PG8_BAR; PG8_MMA(1, 0, At, B0); PG8_MMA(1, 1, At, B1); PG8_BAR; PG8_SCHED;
.LBB0_1162:
	ds_read_b128 v[128:131], v192
	ds_read_b128 v[132:135], v192 offset:1024
	ds_read_b128 v[136:139], v192 offset:2048
	ds_read_b128 v[140:143], v192 offset:3072
	ds_read_b128 v[160:163], v193
	ds_read_b128 v[164:167], v193 offset:1024
	ds_read_b128 v[168:171], v193 offset:2048
	ds_read_b128 v[172:175], v193 offset:3072
	s_add_u32 s38, s36, 0x100
	s_addc_u32 s39, s37, 0
	s_cmp_eq_u32 s69, 60
	s_cselect_b32 s43, s27, s39
	s_cselect_b32 s42, s35, s38
	s_cselect_b32 s41, s25, s68
	s_cselect_b32 s40, s66, s67
	s_add_i32 m0, s52, 0xc000
	ds_read_b128 v[176:179], v194
	ds_read_b128 v[180:183], v194 offset:1024
	ds_read_b128 v[184:187], v194 offset:2048
	ds_read_b128 v[196:199], v194 offset:3072
	ds_read_b128 v[200:203], v194 offset:4096
	ds_read_b128 v[204:207], v194 offset:5120
	ds_read_b128 v[208:211], v194 offset:6144
	ds_read_b128 v[212:215], v194 offset:7168
	global_load_lds_dwordx4 v152, s[36:37]
	s_add_i32 m0, s52, 0xe000
	s_nop 0
	global_load_lds_dwordx4 v154, s[36:37]
	s_waitcnt vmcnt(8)
	s_waitcnt lgkmcnt(0)
	s_barrier
	s_setprio 1
	s_waitcnt lgkmcnt(0)
	v_mfma_f32_16x16x32_bf16 v[92:95], v[128:131], v[176:179], v[92:95]
	v_mfma_f32_16x16x32_bf16 v[92:95], v[132:135], v[180:183], v[92:95]
	v_mfma_f32_16x16x32_bf16 v[88:91], v[132:135], v[196:199], v[88:91]
	v_mfma_f32_16x16x32_bf16 v[88:91], v[128:131], v[184:187], v[88:91]
	v_mfma_f32_16x16x32_bf16 v[116:119], v[128:131], v[200:203], v[116:119]
	v_mfma_f32_16x16x32_bf16 v[116:119], v[132:135], v[204:207], v[116:119]
	v_mfma_f32_16x16x32_bf16 v[108:111], v[132:135], v[212:215], v[108:111]
	v_mfma_f32_16x16x32_bf16 v[108:111], v[128:131], v[208:211], v[108:111]
	v_mfma_f32_16x16x32_bf16 v[28:31], v[136:139], v[176:179], v[28:31]
	v_mfma_f32_16x16x32_bf16 v[28:31], v[140:143], v[180:183], v[28:31]
	v_mfma_f32_16x16x32_bf16 v[24:27], v[140:143], v[196:199], v[24:27]
	v_mfma_f32_16x16x32_bf16 v[24:27], v[136:139], v[184:187], v[24:27]
	v_mfma_f32_16x16x32_bf16 v[52:55], v[136:139], v[200:203], v[52:55]
	v_mfma_f32_16x16x32_bf16 v[52:55], v[140:143], v[204:207], v[52:55]
	v_mfma_f32_16x16x32_bf16 v[44:47], v[140:143], v[212:215], v[44:47]
	v_mfma_f32_16x16x32_bf16 v[44:47], v[136:139], v[208:211], v[44:47]
	s_setprio 0
	s_setprio 1
	v_mfma_f32_16x16x32_bf16 v[84:87], v[160:163], v[176:179], v[84:87]
	v_mfma_f32_16x16x32_bf16 v[84:87], v[164:167], v[180:183], v[84:87]
	v_mfma_f32_16x16x32_bf16 v[64:67], v[164:167], v[196:199], v[64:67]
	v_mfma_f32_16x16x32_bf16 v[64:67], v[160:163], v[184:187], v[64:67]
	v_mfma_f32_16x16x32_bf16 v[124:127], v[160:163], v[200:203], v[124:127]
	v_mfma_f32_16x16x32_bf16 v[124:127], v[164:167], v[204:207], v[124:127]
	v_mfma_f32_16x16x32_bf16 v[120:123], v[164:167], v[212:215], v[120:123]
	v_mfma_f32_16x16x32_bf16 v[120:123], v[160:163], v[208:211], v[120:123]
	v_mfma_f32_16x16x32_bf16 v[20:23], v[168:171], v[176:179], v[20:23]
	v_mfma_f32_16x16x32_bf16 v[20:23], v[172:175], v[180:183], v[20:23]
	v_mfma_f32_16x16x32_bf16 v[0:3], v[172:175], v[196:199], v[0:3]
	v_mfma_f32_16x16x32_bf16 v[0:3], v[168:171], v[184:187], v[0:3]
	v_mfma_f32_16x16x32_bf16 v[60:63], v[168:171], v[200:203], v[60:63]
	v_mfma_f32_16x16x32_bf16 v[60:63], v[172:175], v[204:207], v[60:63]
	v_mfma_f32_16x16x32_bf16 v[56:59], v[172:175], v[212:215], v[56:59]
	v_mfma_f32_16x16x32_bf16 v[56:59], v[168:171], v[208:211], v[56:59]
	s_setprio 0
	s_barrier
	s_add_u32 s98, s40, 0x80
	s_addc_u32 s99, s41, 0
	s_add_u32 s100, s42, 0x80
	s_addc_u32 s101, s43, 0
	s_add_i32 s36, s62, s49
	s_mov_b32 m0, s36
	ds_read_b128 v[176:179], v194 offset:16384
	ds_read_b128 v[180:183], v194 offset:17408
	ds_read_b128 v[184:187], v194 offset:18432
	ds_read_b128 v[196:199], v194 offset:19456
	ds_read_b128 v[200:203], v194 offset:20480
	ds_read_b128 v[204:207], v194 offset:21504
	ds_read_b128 v[208:211], v194 offset:22528
	ds_read_b128 v[212:215], v194 offset:23552
	global_load_lds_dwordx4 v148, s[40:41]
	s_add_i32 m0, s36, 0x2000
	s_add_u32 s36, s40, 0x100000
	s_addc_u32 s37, s41, 0
	s_add_i32 s70, s63, s49
	global_load_lds_dwordx4 v144, s[40:41]
	s_mov_b32 m0, s70
	s_nop 0
	global_load_lds_dwordx4 v148, s[36:37]
	s_add_i32 m0, s70, 0x2000
	s_nop 0
	global_load_lds_dwordx4 v144, s[36:37]
	s_mov_b32 m0, s52
	s_nop 0
	global_load_lds_dwordx4 v150, s[42:43]
	s_mov_b32 m0, s53
	s_nop 0
	global_load_lds_dwordx4 v146, s[42:43]
	s_waitcnt vmcnt(8)
	s_waitcnt lgkmcnt(0)
	s_barrier
	s_setprio 1
	s_waitcnt lgkmcnt(0)
	v_mfma_f32_16x16x32_bf16 v[100:103], v[128:131], v[176:179], v[100:103]
	v_mfma_f32_16x16x32_bf16 v[100:103], v[132:135], v[180:183], v[100:103]
	v_mfma_f32_16x16x32_bf16 v[96:99], v[132:135], v[196:199], v[96:99]
	v_mfma_f32_16x16x32_bf16 v[96:99], v[128:131], v[184:187], v[96:99]
	v_mfma_f32_16x16x32_bf16 v[80:83], v[128:131], v[200:203], v[80:83]
	v_mfma_f32_16x16x32_bf16 v[80:83], v[132:135], v[204:207], v[80:83]
	v_mfma_f32_16x16x32_bf16 v[76:79], v[132:135], v[212:215], v[76:79]
	v_mfma_f32_16x16x32_bf16 v[76:79], v[128:131], v[208:211], v[76:79]
	v_mfma_f32_16x16x32_bf16 v[36:39], v[136:139], v[176:179], v[36:39]
	v_mfma_f32_16x16x32_bf16 v[36:39], v[140:143], v[180:183], v[36:39]
	v_mfma_f32_16x16x32_bf16 v[32:35], v[140:143], v[196:199], v[32:35]
	v_mfma_f32_16x16x32_bf16 v[32:35], v[136:139], v[184:187], v[32:35]
	v_mfma_f32_16x16x32_bf16 v[16:19], v[136:139], v[200:203], v[16:19]
	v_mfma_f32_16x16x32_bf16 v[16:19], v[140:143], v[204:207], v[16:19]
	v_mfma_f32_16x16x32_bf16 v[12:15], v[140:143], v[212:215], v[12:15]
	v_mfma_f32_16x16x32_bf16 v[12:15], v[136:139], v[208:211], v[12:15]
	s_setprio 0
	s_setprio 1
	v_mfma_f32_16x16x32_bf16 v[112:115], v[160:163], v[176:179], v[112:115]
	v_mfma_f32_16x16x32_bf16 v[112:115], v[164:167], v[180:183], v[112:115]
	v_mfma_f32_16x16x32_bf16 v[104:107], v[164:167], v[196:199], v[104:107]
	v_mfma_f32_16x16x32_bf16 v[104:107], v[160:163], v[184:187], v[104:107]
	v_mfma_f32_16x16x32_bf16 v[72:75], v[160:163], v[200:203], v[72:75]
	v_mfma_f32_16x16x32_bf16 v[72:75], v[164:167], v[204:207], v[72:75]
	v_mfma_f32_16x16x32_bf16 v[68:71], v[164:167], v[212:215], v[68:71]
	v_mfma_f32_16x16x32_bf16 v[68:71], v[160:163], v[208:211], v[68:71]
	v_mfma_f32_16x16x32_bf16 v[48:51], v[168:171], v[176:179], v[48:51]
	v_mfma_f32_16x16x32_bf16 v[48:51], v[172:175], v[180:183], v[48:51]
	v_mfma_f32_16x16x32_bf16 v[40:43], v[172:175], v[196:199], v[40:43]
	v_mfma_f32_16x16x32_bf16 v[40:43], v[168:171], v[184:187], v[40:43]
	v_mfma_f32_16x16x32_bf16 v[8:11], v[168:171], v[200:203], v[8:11]
	v_mfma_f32_16x16x32_bf16 v[8:11], v[172:175], v[204:207], v[8:11]
	v_mfma_f32_16x16x32_bf16 v[4:7], v[172:175], v[212:215], v[4:7]
	v_mfma_f32_16x16x32_bf16 v[4:7], v[168:171], v[208:211], v[4:7]
	s_setprio 0
	s_barrier
; #define PG8_STAGE(bufoff, gbase, voff) do { _Pragma("unroll") for (int _i = 0; _i < 2; ++_i) \
;         __builtin_amdgcn_global_load_lds((const unsigned*)((const char*)(gbase) + (voff)[_i]), (PG8_LAS unsigned*)(lds + (bufoff) + ldsw + _i * 8192), 16, 0, 0); } while (0)
; #define PG8_LDA(dst, b, h) do { _Pragma("unroll") for (int m = 0; m < 4; ++m) _Pragma("unroll") for (int k = 0; k < 2; ++k) dst[m][k] = *(const PG8_LAS bf16x8*)(lds + PG8_SA(b, h) + aoff + m * 2048 + k * 1024); } while (0)
; #define PG8_LDB(dst, b, h) do { _Pragma("unroll") for (int n = 0; n < 2; ++n) _Pragma("unroll") for (int k = 0; k < 2; ++k) dst[n][k] = *(const PG8_LAS bf16x8*)(lds + PG8_SB(b, h) + boff + n * 2048 + k * 1024); } while (0)
; #define PG8_WAIT_V(n) asm volatile("s_waitcnt vmcnt(" #n ")" ::: "memory")
; #define PG8_WAIT_L(n) asm volatile("s_waitcnt lgkmcnt(" #n ")" ::: "memory")
; #define PG8_BAR __builtin_amdgcn_s_barrier()
; #define PG8_SCHED __builtin_amdgcn_sched_barrier(0)
; template <class Epi, class Sched, bool ALIGN_EPI = false, bool SP2 = false>
; __device__ __forceinline__ void gemm_phase(PG8_LAS unsigned char* lds, const Gemm g, const Sched& S, const Epi& E, int tid_in) {
;     ...
;         for (int t = 0; t < nt; t += 2) {
;             const bool last = (t == nt - 2);
;             const char* a1 = cA + (size_t)(t + 1) * kstep;
;             const char* a2 = last ? nA : cA + (size_t)(t + 2) * kstep; const char* b2 = last ? nB : cB + (size_t)(t + 2) * kstep;
;     ...
;             PG8_LDB(B0, 1, 0); PG8_LDB(B1, 1, 1); PG8_SCHED; PG8_LDA(At, 1, 0); PG8_STAGE(PG8_SA(0, 1), a2 + hstepA, voffA);
;             PG8_WAIT_V(8); PG8_WAIT_L(0); PG8_BAR; PG8_MMA(0, 0, At, B0); PG8_MMA(0, 1, At, B1); PG8_BAR; PG8_SCHED;
;             PG8_LDA(At, 1, 1); PG8_STAGE(PG8_SB(1, 0), b3, voffB); PG8_STAGE(PG8_SB(1, 1), b3 + hstep, voffB); PG8_STAGE(PG8_SA(1, 0), a3, voffA);
;             PG8_WAIT_V(8); PG8_WAIT_L(0); PG8_BAR; PG8_MMA(1, 0, At, B0); PG8_MMA(1, 1, At, B1); PG8_BAR; PG8_SCHED;
	s_add_i32 s70, 0, 0x18000
	s_add_i32 s71, 0, 0x1c000
	v_add_u32_e32 v140, s70, v189
	v_add_u32_e32 v172, s71, v189
	ds_read_b128 v[128:131], v140
	ds_read_b128 v[132:135], v140 offset:1024
	ds_read_b128 v[136:139], v140 offset:2048
	ds_read_b128 v[140:143], v140 offset:3072
	ds_read_b128 v[160:163], v172
	ds_read_b128 v[164:167], v172 offset:1024
	ds_read_b128 v[168:171], v172 offset:2048
	ds_read_b128 v[172:175], v172 offset:3072
	s_add_u32 s36, s42, 0x8000
	s_addc_u32 s37, s43, 0
	s_mov_b32 m0, s54
	ds_read_b128 v[176:179], v194 offset:32768
	ds_read_b128 v[180:183], v194 offset:33792
	ds_read_b128 v[184:187], v194 offset:34816
	ds_read_b128 v[196:199], v194 offset:35840
	ds_read_b128 v[200:203], v194 offset:36864
	ds_read_b128 v[204:207], v194 offset:37888
	ds_read_b128 v[208:211], v194 offset:38912
	ds_read_b128 v[212:215], v194 offset:39936
	global_load_lds_dwordx4 v150, s[36:37]
	s_mov_b32 m0, s55
	s_nop 0
	global_load_lds_dwordx4 v146, s[36:37]
	s_waitcnt vmcnt(8)
	s_waitcnt lgkmcnt(0)
	s_barrier
	s_setprio 1
	s_waitcnt lgkmcnt(0)
	v_mfma_f32_16x16x32_bf16 v[92:95], v[128:131], v[176:179], v[92:95]
	v_mfma_f32_16x16x32_bf16 v[92:95], v[132:135], v[180:183], v[92:95]
	v_mfma_f32_16x16x32_bf16 v[88:91], v[132:135], v[196:199], v[88:91]
	v_mfma_f32_16x16x32_bf16 v[88:91], v[128:131], v[184:187], v[88:91]
	v_mfma_f32_16x16x32_bf16 v[116:119], v[128:131], v[200:203], v[116:119]
	v_mfma_f32_16x16x32_bf16 v[116:119], v[132:135], v[204:207], v[116:119]
	v_mfma_f32_16x16x32_bf16 v[108:111], v[132:135], v[212:215], v[108:111]
	v_mfma_f32_16x16x32_bf16 v[108:111], v[128:131], v[208:211], v[108:111]
	v_mfma_f32_16x16x32_bf16 v[28:31], v[136:139], v[176:179], v[28:31]
	v_mfma_f32_16x16x32_bf16 v[28:31], v[140:143], v[180:183], v[28:31]
	v_mfma_f32_16x16x32_bf16 v[24:27], v[140:143], v[196:199], v[24:27]
	v_mfma_f32_16x16x32_bf16 v[24:27], v[136:139], v[184:187], v[24:27]
	v_mfma_f32_16x16x32_bf16 v[52:55], v[136:139], v[200:203], v[52:55]
	v_mfma_f32_16x16x32_bf16 v[52:55], v[140:143], v[204:207], v[52:55]
	v_mfma_f32_16x16x32_bf16 v[44:47], v[140:143], v[212:215], v[44:47]
	v_mfma_f32_16x16x32_bf16 v[44:47], v[136:139], v[208:211], v[44:47]
	s_setprio 0
	s_setprio 1
	v_mfma_f32_16x16x32_bf16 v[84:87], v[160:163], v[176:179], v[84:87]
	v_mfma_f32_16x16x32_bf16 v[84:87], v[164:167], v[180:183], v[84:87]
	v_mfma_f32_16x16x32_bf16 v[64:67], v[164:167], v[196:199], v[64:67]
	v_mfma_f32_16x16x32_bf16 v[64:67], v[160:163], v[184:187], v[64:67]
	v_mfma_f32_16x16x32_bf16 v[124:127], v[160:163], v[200:203], v[124:127]
	v_mfma_f32_16x16x32_bf16 v[124:127], v[164:167], v[204:207], v[124:127]
	v_mfma_f32_16x16x32_bf16 v[120:123], v[164:167], v[212:215], v[120:123]
	v_mfma_f32_16x16x32_bf16 v[120:123], v[160:163], v[208:211], v[120:123]
	v_mfma_f32_16x16x32_bf16 v[20:23], v[168:171], v[176:179], v[20:23]
	v_mfma_f32_16x16x32_bf16 v[20:23], v[172:175], v[180:183], v[20:23]
	v_mfma_f32_16x16x32_bf16 v[0:3], v[172:175], v[196:199], v[0:3]
	v_mfma_f32_16x16x32_bf16 v[0:3], v[168:171], v[184:187], v[0:3]
	v_mfma_f32_16x16x32_bf16 v[60:63], v[168:171], v[200:203], v[60:63]
	v_mfma_f32_16x16x32_bf16 v[60:63], v[172:175], v[204:207], v[60:63]
	v_mfma_f32_16x16x32_bf16 v[56:59], v[172:175], v[212:215], v[56:59]
	v_mfma_f32_16x16x32_bf16 v[56:59], v[168:171], v[208:211], v[56:59]
	s_setprio 0
	s_barrier
	s_add_i32 s36, s70, s49
	s_mov_b32 m0, s36
	ds_read_b128 v[176:179], v194 offset:49152
	ds_read_b128 v[180:183], v194 offset:50176
	ds_read_b128 v[184:187], v194 offset:51200
	ds_read_b128 v[196:199], v194 offset:52224
	ds_read_b128 v[200:203], v194 offset:53248
	ds_read_b128 v[204:207], v194 offset:54272
	ds_read_b128 v[208:211], v194 offset:55296
	ds_read_b128 v[212:215], v194 offset:56320
	global_load_lds_dwordx4 v148, s[98:99]
	s_add_i32 m0, s36, 0x2000
	s_add_u32 s36, s40, 0x100080
	s_addc_u32 s37, s41, 0
	s_add_i32 s40, s71, s49
	global_load_lds_dwordx4 v144, s[98:99]
	s_mov_b32 m0, s40
	s_nop 0
	global_load_lds_dwordx4 v148, s[36:37]
	s_add_i32 m0, s40, 0x2000
	s_nop 0
	global_load_lds_dwordx4 v144, s[36:37]
	s_mov_b32 m0, s59
	s_nop 0
	global_load_lds_dwordx4 v150, s[100:101]
	s_mov_b32 m0, s60
	s_nop 0
	global_load_lds_dwordx4 v146, s[100:101]
	s_waitcnt vmcnt(8)
	s_waitcnt lgkmcnt(0)
	s_barrier
	s_setprio 1
	s_waitcnt lgkmcnt(0)
	v_mfma_f32_16x16x32_bf16 v[100:103], v[128:131], v[176:179], v[100:103]
	v_mfma_f32_16x16x32_bf16 v[100:103], v[132:135], v[180:183], v[100:103]
	v_mfma_f32_16x16x32_bf16 v[96:99], v[132:135], v[196:199], v[96:99]
	v_mfma_f32_16x16x32_bf16 v[96:99], v[128:131], v[184:187], v[96:99]
	v_mfma_f32_16x16x32_bf16 v[80:83], v[128:131], v[200:203], v[80:83]
	v_mfma_f32_16x16x32_bf16 v[80:83], v[132:135], v[204:207], v[80:83]
	v_mfma_f32_16x16x32_bf16 v[76:79], v[132:135], v[212:215], v[76:79]
	v_mfma_f32_16x16x32_bf16 v[76:79], v[128:131], v[208:211], v[76:79]
	v_mfma_f32_16x16x32_bf16 v[36:39], v[136:139], v[176:179], v[36:39]
	v_mfma_f32_16x16x32_bf16 v[36:39], v[140:143], v[180:183], v[36:39]
	v_mfma_f32_16x16x32_bf16 v[32:35], v[140:143], v[196:199], v[32:35]
	v_mfma_f32_16x16x32_bf16 v[32:35], v[136:139], v[184:187], v[32:35]
	v_mfma_f32_16x16x32_bf16 v[16:19], v[136:139], v[200:203], v[16:19]
	v_mfma_f32_16x16x32_bf16 v[16:19], v[140:143], v[204:207], v[16:19]
	v_mfma_f32_16x16x32_bf16 v[12:15], v[140:143], v[212:215], v[12:15]
	v_mfma_f32_16x16x32_bf16 v[12:15], v[136:139], v[208:211], v[12:15]
	s_setprio 0
	s_setprio 1
	v_mfma_f32_16x16x32_bf16 v[112:115], v[160:163], v[176:179], v[112:115]
	v_mfma_f32_16x16x32_bf16 v[112:115], v[164:167], v[180:183], v[112:115]
	v_mfma_f32_16x16x32_bf16 v[104:107], v[164:167], v[196:199], v[104:107]
	v_mfma_f32_16x16x32_bf16 v[104:107], v[160:163], v[184:187], v[104:107]
	v_mfma_f32_16x16x32_bf16 v[72:75], v[160:163], v[200:203], v[72:75]
	v_mfma_f32_16x16x32_bf16 v[72:75], v[164:167], v[204:207], v[72:75]
	v_mfma_f32_16x16x32_bf16 v[68:71], v[164:167], v[212:215], v[68:71]
	v_mfma_f32_16x16x32_bf16 v[68:71], v[160:163], v[208:211], v[68:71]
	v_mfma_f32_16x16x32_bf16 v[48:51], v[168:171], v[176:179], v[48:51]
	v_mfma_f32_16x16x32_bf16 v[48:51], v[172:175], v[180:183], v[48:51]
	v_mfma_f32_16x16x32_bf16 v[40:43], v[172:175], v[196:199], v[40:43]
	v_mfma_f32_16x16x32_bf16 v[40:43], v[168:171], v[184:187], v[40:43]
	v_mfma_f32_16x16x32_bf16 v[8:11], v[168:171], v[200:203], v[8:11]
	v_mfma_f32_16x16x32_bf16 v[8:11], v[172:175], v[204:207], v[8:11]
	v_mfma_f32_16x16x32_bf16 v[4:7], v[172:175], v[212:215], v[4:7]
	v_mfma_f32_16x16x32_bf16 v[4:7], v[168:171], v[208:211], v[4:7]
	s_setprio 0
	s_barrier
	s_add_i32 s69, s69, 2
	s_add_u32 s67, s67, 0x100
	s_addc_u32 s68, s68, 0
	s_cmp_gt_u32 s69, 61
	s_mov_b64 s[36:37], s[38:39]
	s_cbranch_scc0 .LBB0_1162
	s_and_b64 vcc, exec, s[10:11]
	s_cbranch_vccz .LBB0_1165
	s_barrier

; #define PG8_STAGE(bufoff, gbase, voff) do { _Pragma("unroll") for (int _i = 0; _i < 2; ++_i) \
;         __builtin_amdgcn_global_load_lds((const unsigned*)((const char*)(gbase) + (voff)[_i]), (PG8_LAS unsigned*)(lds + (bufoff) + ldsw + _i * 8192), 16, 0, 0); } while (0)
; #define PG8_LDA(dst, b, h) do { _Pragma("unroll") for (int m = 0; m < 4; ++m) _Pragma("unroll") for (int k = 0; k < 2; ++k) dst[m][k] = *(const PG8_LAS bf16x8*)(lds + PG8_SA(b, h) + aoff + m * 2048 + k * 1024); } while (0)
; #define PG8_LDB(dst, b, h) do { _Pragma("unroll") for (int n = 0; n < 2; ++n) _Pragma("unroll") for (int k = 0; k < 2; ++k) dst[n][k] = *(const PG8_LAS bf16x8*)(lds + PG8_SB(b, h) + boff + n * 2048 + k * 1024); } while (0)
; #define PG8_WAIT_V(n) asm volatile("s_waitcnt vmcnt(" #n ")" ::: "memory")
; #define PG8_WAIT_L(n) asm volatile("s_waitcnt lgkmcnt(" #n ")" ::: "memory")
; #define PG8_BAR __builtin_amdgcn_s_barrier()
; #define PG8_SCHED __builtin_amdgcn_sched_barrier(0)
; template <class Epi, class Sched, bool ALIGN_EPI = false, bool SP2 = false>
; __device__ __forceinline__ void gemm_phase(PG8_LAS unsigned char* lds, const Gemm g, const Sched& S, const Epi& E, int tid_in) {
;     ...
;             PG8_LDB(B0, 0, 0); PG8_LDB(B1, 0, 1); PG8_SCHED; PG8_LDA(At, 0, 0); PG8_STAGE(PG8_SA(1, 1), a1 + hstepA, voffA);
;             PG8_WAIT_V(8); PG8_WAIT_L(0); PG8_BAR; PG8_MMA(0, 0, At, B0); PG8_MMA(0, 1, At, B1); PG8_BAR; PG8_SCHED;
;             PG8_LDA(At, 0, 1); PG8_STAGE(PG8_SB(0, 0), b2, voffB); PG8_STAGE(PG8_SB(0, 1), b2 + hstep, voffB); PG8_STAGE(PG8_SA(0, 0), a2, voffA);
;             PG8_WAIT_V(8); PG8_WAIT_L(0); PG8_BAR; PG8_MMA(1, 0, At, B0); PG8_MMA(1, 1, At, B1); PG8_BAR; PG8_SCHED;
.LBB0_1328:
	ds_read_b128 v[128:131], v191
	ds_read_b128 v[132:135], v191 offset:1024
	ds_read_b128 v[152:155], v191 offset:2048
	ds_read_b128 v[156:159], v191 offset:3072
	ds_read_b128 v[160:163], v192
	ds_read_b128 v[164:167], v192 offset:1024
	ds_read_b128 v[168:171], v192 offset:2048
	ds_read_b128 v[172:175], v192 offset:3072
	s_add_u32 s22, s20, 0x100
	s_addc_u32 s23, s21, 0
	s_cmpk_eq_i32 s53, 0xa8
	s_cselect_b32 s27, s5, s23
	s_cselect_b32 s26, s4, s22
	s_cselect_b32 s25, s19, s52
	s_cselect_b32 s24, s18, s51
	s_add_i32 m0, s34, 0xc000
	ds_read_b128 v[176:179], v193
	ds_read_b128 v[180:183], v193 offset:1024
	ds_read_b128 v[184:187], v193 offset:2048
	ds_read_b128 v[194:197], v193 offset:3072
	ds_read_b128 v[198:201], v193 offset:4096
	ds_read_b128 v[202:205], v193 offset:5120
	ds_read_b128 v[206:209], v193 offset:6144
	ds_read_b128 v[210:213], v193 offset:7168
	global_load_lds_dwordx4 v144, s[20:21]
	s_add_i32 m0, s34, 0xe000
	s_nop 0
	global_load_lds_dwordx4 v146, s[20:21]
	s_waitcnt vmcnt(8)
	s_waitcnt lgkmcnt(0)
	s_barrier
	s_setprio 1
	s_waitcnt lgkmcnt(0)
	v_mfma_f32_16x16x32_bf16 v[124:127], v[128:131], v[176:179], v[124:127]
	v_mfma_f32_16x16x32_bf16 v[124:127], v[132:135], v[180:183], v[124:127]
	v_mfma_f32_16x16x32_bf16 v[116:119], v[132:135], v[194:197], v[116:119]
	v_mfma_f32_16x16x32_bf16 v[116:119], v[128:131], v[184:187], v[116:119]
	v_mfma_f32_16x16x32_bf16 v[108:111], v[128:131], v[198:201], v[108:111]
	v_mfma_f32_16x16x32_bf16 v[108:111], v[132:135], v[202:205], v[108:111]
	v_mfma_f32_16x16x32_bf16 v[100:103], v[132:135], v[210:213], v[100:103]
	v_mfma_f32_16x16x32_bf16 v[100:103], v[128:131], v[206:209], v[100:103]
	v_mfma_f32_16x16x32_bf16 v[120:123], v[152:155], v[176:179], v[120:123]
	v_mfma_f32_16x16x32_bf16 v[120:123], v[156:159], v[180:183], v[120:123]
	v_mfma_f32_16x16x32_bf16 v[112:115], v[156:159], v[194:197], v[112:115]
	v_mfma_f32_16x16x32_bf16 v[112:115], v[152:155], v[184:187], v[112:115]
	v_mfma_f32_16x16x32_bf16 v[104:107], v[152:155], v[198:201], v[104:107]
	v_mfma_f32_16x16x32_bf16 v[104:107], v[156:159], v[202:205], v[104:107]
	v_mfma_f32_16x16x32_bf16 v[96:99], v[156:159], v[210:213], v[96:99]
	v_mfma_f32_16x16x32_bf16 v[96:99], v[152:155], v[206:209], v[96:99]
	s_setprio 0
	s_setprio 1
	v_mfma_f32_16x16x32_bf16 v[60:63], v[160:163], v[176:179], v[60:63]
	v_mfma_f32_16x16x32_bf16 v[60:63], v[164:167], v[180:183], v[60:63]
	v_mfma_f32_16x16x32_bf16 v[52:55], v[164:167], v[194:197], v[52:55]
	v_mfma_f32_16x16x32_bf16 v[52:55], v[160:163], v[184:187], v[52:55]
	v_mfma_f32_16x16x32_bf16 v[44:47], v[160:163], v[198:201], v[44:47]
	v_mfma_f32_16x16x32_bf16 v[44:47], v[164:167], v[202:205], v[44:47]
	v_mfma_f32_16x16x32_bf16 v[36:39], v[164:167], v[210:213], v[36:39]
	v_mfma_f32_16x16x32_bf16 v[36:39], v[160:163], v[206:209], v[36:39]
	v_mfma_f32_16x16x32_bf16 v[56:59], v[168:171], v[176:179], v[56:59]
	v_mfma_f32_16x16x32_bf16 v[56:59], v[172:175], v[180:183], v[56:59]
	v_mfma_f32_16x16x32_bf16 v[48:51], v[172:175], v[194:197], v[48:51]
	v_mfma_f32_16x16x32_bf16 v[48:51], v[168:171], v[184:187], v[48:51]
	v_mfma_f32_16x16x32_bf16 v[40:43], v[168:171], v[198:201], v[40:43]
	v_mfma_f32_16x16x32_bf16 v[40:43], v[172:175], v[202:205], v[40:43]
	v_mfma_f32_16x16x32_bf16 v[32:35], v[172:175], v[210:213], v[32:35]
	v_mfma_f32_16x16x32_bf16 v[32:35], v[168:171], v[206:209], v[32:35]
	s_setprio 0
	s_barrier
	s_add_u32 s98, s24, 0x80
	s_addc_u32 s99, s25, 0
	s_add_u32 s100, s26, 0x80
	s_addc_u32 s101, s27, 0
	s_add_i32 s20, s45, s33
	s_mov_b32 m0, s20
	ds_read_b128 v[176:179], v193 offset:16384
	ds_read_b128 v[180:183], v193 offset:17408
	ds_read_b128 v[184:187], v193 offset:18432
	ds_read_b128 v[194:197], v193 offset:19456
	ds_read_b128 v[198:201], v193 offset:20480
	ds_read_b128 v[202:205], v193 offset:21504
	ds_read_b128 v[206:209], v193 offset:22528
	ds_read_b128 v[210:213], v193 offset:23552
	global_load_lds_dwordx4 v138, s[24:25]
	s_add_i32 m0, s20, 0x2000
	s_add_u32 s20, s24, 0x2b0000
	s_addc_u32 s21, s25, 0
	s_add_i32 s54, s46, s33
	global_load_lds_dwordx4 v142, s[24:25]
	s_mov_b32 m0, s54
	s_nop 0
	global_load_lds_dwordx4 v138, s[20:21]
	s_add_i32 m0, s54, 0x2000
	s_nop 0
	global_load_lds_dwordx4 v142, s[20:21]
	s_mov_b32 m0, s34
	s_nop 0
	global_load_lds_dwordx4 v136, s[26:27]
	s_mov_b32 m0, s35
	s_nop 0
	global_load_lds_dwordx4 v140, s[26:27]
	s_waitcnt vmcnt(8)
	s_waitcnt lgkmcnt(0)
	s_barrier
	s_setprio 1
	s_waitcnt lgkmcnt(0)
	v_mfma_f32_16x16x32_bf16 v[92:95], v[128:131], v[176:179], v[92:95]
	v_mfma_f32_16x16x32_bf16 v[92:95], v[132:135], v[180:183], v[92:95]
	v_mfma_f32_16x16x32_bf16 v[84:87], v[132:135], v[194:197], v[84:87]
	v_mfma_f32_16x16x32_bf16 v[84:87], v[128:131], v[184:187], v[84:87]
	v_mfma_f32_16x16x32_bf16 v[76:79], v[128:131], v[198:201], v[76:79]
	v_mfma_f32_16x16x32_bf16 v[76:79], v[132:135], v[202:205], v[76:79]
	v_mfma_f32_16x16x32_bf16 v[68:71], v[132:135], v[210:213], v[68:71]
	v_mfma_f32_16x16x32_bf16 v[68:71], v[128:131], v[206:209], v[68:71]
	v_mfma_f32_16x16x32_bf16 v[88:91], v[152:155], v[176:179], v[88:91]
	v_mfma_f32_16x16x32_bf16 v[88:91], v[156:159], v[180:183], v[88:91]
	v_mfma_f32_16x16x32_bf16 v[80:83], v[156:159], v[194:197], v[80:83]
	v_mfma_f32_16x16x32_bf16 v[80:83], v[152:155], v[184:187], v[80:83]
	v_mfma_f32_16x16x32_bf16 v[72:75], v[152:155], v[198:201], v[72:75]
	v_mfma_f32_16x16x32_bf16 v[72:75], v[156:159], v[202:205], v[72:75]
	v_mfma_f32_16x16x32_bf16 v[64:67], v[156:159], v[210:213], v[64:67]
	v_mfma_f32_16x16x32_bf16 v[64:67], v[152:155], v[206:209], v[64:67]
	s_setprio 0
	s_setprio 1
	v_mfma_f32_16x16x32_bf16 v[28:31], v[160:163], v[176:179], v[28:31]
	v_mfma_f32_16x16x32_bf16 v[28:31], v[164:167], v[180:183], v[28:31]
	v_mfma_f32_16x16x32_bf16 v[20:23], v[164:167], v[194:197], v[20:23]
	v_mfma_f32_16x16x32_bf16 v[20:23], v[160:163], v[184:187], v[20:23]
	v_mfma_f32_16x16x32_bf16 v[12:15], v[160:163], v[198:201], v[12:15]
	v_mfma_f32_16x16x32_bf16 v[12:15], v[164:167], v[202:205], v[12:15]
	v_mfma_f32_16x16x32_bf16 v[4:7], v[164:167], v[210:213], v[4:7]
	v_mfma_f32_16x16x32_bf16 v[4:7], v[160:163], v[206:209], v[4:7]
	v_mfma_f32_16x16x32_bf16 v[24:27], v[168:171], v[176:179], v[24:27]
	v_mfma_f32_16x16x32_bf16 v[24:27], v[172:175], v[180:183], v[24:27]
	v_mfma_f32_16x16x32_bf16 v[16:19], v[172:175], v[194:197], v[16:19]
	v_mfma_f32_16x16x32_bf16 v[16:19], v[168:171], v[184:187], v[16:19]
	v_mfma_f32_16x16x32_bf16 v[8:11], v[168:171], v[198:201], v[8:11]
	v_mfma_f32_16x16x32_bf16 v[8:11], v[172:175], v[202:205], v[8:11]
	v_mfma_f32_16x16x32_bf16 v[0:3], v[172:175], v[210:213], v[0:3]
	v_mfma_f32_16x16x32_bf16 v[0:3], v[168:171], v[206:209], v[0:3]
	s_setprio 0
	s_barrier
; #define PG8_STAGE(bufoff, gbase, voff) do { _Pragma("unroll") for (int _i = 0; _i < 2; ++_i) \
;         __builtin_amdgcn_global_load_lds((const unsigned*)((const char*)(gbase) + (voff)[_i]), (PG8_LAS unsigned*)(lds + (bufoff) + ldsw + _i * 8192), 16, 0, 0); } while (0)
; #define PG8_LDA(dst, b, h) do { _Pragma("unroll") for (int m = 0; m < 4; ++m) _Pragma("unroll") for (int k = 0; k < 2; ++k) dst[m][k] = *(const PG8_LAS bf16x8*)(lds + PG8_SA(b, h) + aoff + m * 2048 + k * 1024); } while (0)
; #define PG8_LDB(dst, b, h) do { _Pragma("unroll") for (int n = 0; n < 2; ++n) _Pragma("unroll") for (int k = 0; k < 2; ++k) dst[n][k] = *(const PG8_LAS bf16x8*)(lds + PG8_SB(b, h) + boff + n * 2048 + k * 1024); } while (0)
; #define PG8_WAIT_V(n) asm volatile("s_waitcnt vmcnt(" #n ")" ::: "memory")
; #define PG8_WAIT_L(n) asm volatile("s_waitcnt lgkmcnt(" #n ")" ::: "memory")
; #define PG8_BAR __builtin_amdgcn_s_barrier()
; #define PG8_SCHED __builtin_amdgcn_sched_barrier(0)
; template <class Epi, class Sched, bool ALIGN_EPI = false, bool SP2 = false>
; __device__ __forceinline__ void gemm_phase(PG8_LAS unsigned char* lds, const Gemm g, const Sched& S, const Epi& E, int tid_in) {
;     ...
;         for (int t = 0; t < nt; t += 2) {
;             const bool last = (t == nt - 2);
;             const char* a1 = cA + (size_t)(t + 1) * kstep;
;             const char* a2 = last ? nA : cA + (size_t)(t + 2) * kstep; const char* b2 = last ? nB : cB + (size_t)(t + 2) * kstep;
;     ...
;             PG8_LDB(B0, 1, 0); PG8_LDB(B1, 1, 1); PG8_SCHED; PG8_LDA(At, 1, 0); PG8_STAGE(PG8_SA(0, 1), a2 + hstepA, voffA);
;             PG8_WAIT_V(8); PG8_WAIT_L(0); PG8_BAR; PG8_MMA(0, 0, At, B0); PG8_MMA(0, 1, At, B1); PG8_BAR; PG8_SCHED;
;             PG8_LDA(At, 1, 1); PG8_STAGE(PG8_SB(1, 0), b3, voffB); PG8_STAGE(PG8_SB(1, 1), b3 + hstep, voffB); PG8_STAGE(PG8_SA(1, 0), a3, voffA);
;             PG8_WAIT_V(8); PG8_WAIT_L(0); PG8_BAR; PG8_MMA(1, 0, At, B0); PG8_MMA(1, 1, At, B1); PG8_BAR; PG8_SCHED;
	s_add_i32 s54, 0, 0x18000
	s_add_i32 s55, 0, 0x1c000
	v_add_u32_e32 v156, s54, v189
	v_add_u32_e32 v172, s55, v189
	ds_read_b128 v[128:131], v156
	ds_read_b128 v[132:135], v156 offset:1024
	ds_read_b128 v[152:155], v156 offset:2048
	ds_read_b128 v[156:159], v156 offset:3072
	ds_read_b128 v[160:163], v172
	ds_read_b128 v[164:167], v172 offset:1024
	ds_read_b128 v[168:171], v172 offset:2048
	ds_read_b128 v[172:175], v172 offset:3072
	s_add_u32 s20, s26, 0x2b0000
	s_addc_u32 s21, s27, 0
	s_mov_b32 m0, s36
	ds_read_b128 v[176:179], v193 offset:32768
	ds_read_b128 v[180:183], v193 offset:33792
	ds_read_b128 v[184:187], v193 offset:34816
	ds_read_b128 v[194:197], v193 offset:35840
	ds_read_b128 v[198:201], v193 offset:36864
	ds_read_b128 v[202:205], v193 offset:37888
	ds_read_b128 v[206:209], v193 offset:38912
	ds_read_b128 v[210:213], v193 offset:39936
	global_load_lds_dwordx4 v136, s[20:21]
	s_mov_b32 m0, s37
	s_nop 0
	global_load_lds_dwordx4 v140, s[20:21]
	s_waitcnt vmcnt(8)
	s_waitcnt lgkmcnt(0)
	s_barrier
	s_setprio 1
	s_waitcnt lgkmcnt(0)
	v_mfma_f32_16x16x32_bf16 v[124:127], v[128:131], v[176:179], v[124:127]
	v_mfma_f32_16x16x32_bf16 v[124:127], v[132:135], v[180:183], v[124:127]
	v_mfma_f32_16x16x32_bf16 v[116:119], v[132:135], v[194:197], v[116:119]
	v_mfma_f32_16x16x32_bf16 v[116:119], v[128:131], v[184:187], v[116:119]
	v_mfma_f32_16x16x32_bf16 v[108:111], v[128:131], v[198:201], v[108:111]
	v_mfma_f32_16x16x32_bf16 v[108:111], v[132:135], v[202:205], v[108:111]
	v_mfma_f32_16x16x32_bf16 v[100:103], v[132:135], v[210:213], v[100:103]
	v_mfma_f32_16x16x32_bf16 v[100:103], v[128:131], v[206:209], v[100:103]
	v_mfma_f32_16x16x32_bf16 v[120:123], v[152:155], v[176:179], v[120:123]
	v_mfma_f32_16x16x32_bf16 v[120:123], v[156:159], v[180:183], v[120:123]
	v_mfma_f32_16x16x32_bf16 v[112:115], v[156:159], v[194:197], v[112:115]
	v_mfma_f32_16x16x32_bf16 v[112:115], v[152:155], v[184:187], v[112:115]
	v_mfma_f32_16x16x32_bf16 v[104:107], v[152:155], v[198:201], v[104:107]
	v_mfma_f32_16x16x32_bf16 v[104:107], v[156:159], v[202:205], v[104:107]
	v_mfma_f32_16x16x32_bf16 v[96:99], v[156:159], v[210:213], v[96:99]
	v_mfma_f32_16x16x32_bf16 v[96:99], v[152:155], v[206:209], v[96:99]
	s_setprio 0
	s_setprio 1
	v_mfma_f32_16x16x32_bf16 v[60:63], v[160:163], v[176:179], v[60:63]
	v_mfma_f32_16x16x32_bf16 v[60:63], v[164:167], v[180:183], v[60:63]
	v_mfma_f32_16x16x32_bf16 v[52:55], v[164:167], v[194:197], v[52:55]
	v_mfma_f32_16x16x32_bf16 v[52:55], v[160:163], v[184:187], v[52:55]
	v_mfma_f32_16x16x32_bf16 v[44:47], v[160:163], v[198:201], v[44:47]
	v_mfma_f32_16x16x32_bf16 v[44:47], v[164:167], v[202:205], v[44:47]
	v_mfma_f32_16x16x32_bf16 v[36:39], v[164:167], v[210:213], v[36:39]
	v_mfma_f32_16x16x32_bf16 v[36:39], v[160:163], v[206:209], v[36:39]
	v_mfma_f32_16x16x32_bf16 v[56:59], v[168:171], v[176:179], v[56:59]
	v_mfma_f32_16x16x32_bf16 v[56:59], v[172:175], v[180:183], v[56:59]
	v_mfma_f32_16x16x32_bf16 v[48:51], v[172:175], v[194:197], v[48:51]
	v_mfma_f32_16x16x32_bf16 v[48:51], v[168:171], v[184:187], v[48:51]
	v_mfma_f32_16x16x32_bf16 v[40:43], v[168:171], v[198:201], v[40:43]
	v_mfma_f32_16x16x32_bf16 v[40:43], v[172:175], v[202:205], v[40:43]
	v_mfma_f32_16x16x32_bf16 v[32:35], v[172:175], v[210:213], v[32:35]
	v_mfma_f32_16x16x32_bf16 v[32:35], v[168:171], v[206:209], v[32:35]
	s_setprio 0
	s_barrier
	s_add_i32 s20, s54, s33
	s_mov_b32 m0, s20
	ds_read_b128 v[176:179], v193 offset:49152
	ds_read_b128 v[180:183], v193 offset:50176
	ds_read_b128 v[184:187], v193 offset:51200
	ds_read_b128 v[194:197], v193 offset:52224
	ds_read_b128 v[198:201], v193 offset:53248
	ds_read_b128 v[202:205], v193 offset:54272
	ds_read_b128 v[206:209], v193 offset:55296
	ds_read_b128 v[210:213], v193 offset:56320
	global_load_lds_dwordx4 v138, s[98:99]
	s_add_i32 m0, s20, 0x2000
	s_add_u32 s20, s24, 0x2b0080
	s_addc_u32 s21, s25, 0
	s_add_i32 s24, s55, s33
	global_load_lds_dwordx4 v142, s[98:99]
	s_mov_b32 m0, s24
	s_nop 0
	global_load_lds_dwordx4 v138, s[20:21]
	s_add_i32 m0, s24, 0x2000
	s_nop 0
	global_load_lds_dwordx4 v142, s[20:21]
	s_mov_b32 m0, s42
	s_nop 0
	global_load_lds_dwordx4 v136, s[100:101]
	s_mov_b32 m0, s43
	s_nop 0
	global_load_lds_dwordx4 v140, s[100:101]
	s_waitcnt vmcnt(8)
	s_waitcnt lgkmcnt(0)
	s_barrier
	s_setprio 1
	s_waitcnt lgkmcnt(0)
	v_mfma_f32_16x16x32_bf16 v[92:95], v[128:131], v[176:179], v[92:95]
	v_mfma_f32_16x16x32_bf16 v[92:95], v[132:135], v[180:183], v[92:95]
	v_mfma_f32_16x16x32_bf16 v[84:87], v[132:135], v[194:197], v[84:87]
	v_mfma_f32_16x16x32_bf16 v[84:87], v[128:131], v[184:187], v[84:87]
	v_mfma_f32_16x16x32_bf16 v[76:79], v[128:131], v[198:201], v[76:79]
	v_mfma_f32_16x16x32_bf16 v[76:79], v[132:135], v[202:205], v[76:79]
	v_mfma_f32_16x16x32_bf16 v[68:71], v[132:135], v[210:213], v[68:71]
	v_mfma_f32_16x16x32_bf16 v[68:71], v[128:131], v[206:209], v[68:71]
	v_mfma_f32_16x16x32_bf16 v[88:91], v[152:155], v[176:179], v[88:91]
	v_mfma_f32_16x16x32_bf16 v[88:91], v[156:159], v[180:183], v[88:91]
	v_mfma_f32_16x16x32_bf16 v[80:83], v[156:159], v[194:197], v[80:83]
	v_mfma_f32_16x16x32_bf16 v[80:83], v[152:155], v[184:187], v[80:83]
	v_mfma_f32_16x16x32_bf16 v[72:75], v[152:155], v[198:201], v[72:75]
	v_mfma_f32_16x16x32_bf16 v[72:75], v[156:159], v[202:205], v[72:75]
	v_mfma_f32_16x16x32_bf16 v[64:67], v[156:159], v[210:213], v[64:67]
	v_mfma_f32_16x16x32_bf16 v[64:67], v[152:155], v[206:209], v[64:67]
	s_setprio 0
	s_setprio 1
	v_mfma_f32_16x16x32_bf16 v[28:31], v[160:163], v[176:179], v[28:31]
	v_mfma_f32_16x16x32_bf16 v[28:31], v[164:167], v[180:183], v[28:31]
	v_mfma_f32_16x16x32_bf16 v[20:23], v[164:167], v[194:197], v[20:23]
	v_mfma_f32_16x16x32_bf16 v[20:23], v[160:163], v[184:187], v[20:23]
	v_mfma_f32_16x16x32_bf16 v[12:15], v[160:163], v[198:201], v[12:15]
	v_mfma_f32_16x16x32_bf16 v[12:15], v[164:167], v[202:205], v[12:15]
	v_mfma_f32_16x16x32_bf16 v[4:7], v[164:167], v[210:213], v[4:7]
	v_mfma_f32_16x16x32_bf16 v[4:7], v[160:163], v[206:209], v[4:7]
	v_mfma_f32_16x16x32_bf16 v[24:27], v[168:171], v[176:179], v[24:27]
	v_mfma_f32_16x16x32_bf16 v[24:27], v[172:175], v[180:183], v[24:27]
	v_mfma_f32_16x16x32_bf16 v[16:19], v[172:175], v[194:197], v[16:19]
	v_mfma_f32_16x16x32_bf16 v[16:19], v[168:171], v[184:187], v[16:19]
	v_mfma_f32_16x16x32_bf16 v[8:11], v[168:171], v[198:201], v[8:11]
	v_mfma_f32_16x16x32_bf16 v[8:11], v[172:175], v[202:205], v[8:11]
	v_mfma_f32_16x16x32_bf16 v[0:3], v[172:175], v[210:213], v[0:3]
	v_mfma_f32_16x16x32_bf16 v[0:3], v[168:171], v[206:209], v[0:3]
	s_setprio 0
	s_barrier
	s_add_i32 s53, s53, 2
	s_add_u32 s51, s51, 0x100
	s_addc_u32 s52, s52, 0
	s_cmpk_gt_u32 s53, 0xa9
	s_mov_b64 s[20:21], s[22:23]
	s_cbranch_scc0 .LBB0_1328
	s_and_b64 vcc, exec, s[14:15]
	s_cbranch_vccz .LBB0_1331
	s_barrier
;     __device__ __forceinline__ void operator()(const f32x4 (&acc)[2][2][4][2], const Unit& u, int wr, int wc, int fr, int fq) const {
;         typedef float f2_ __attribute__((ext_vector_type(2)));
;         const int row0 = u.pm * BM + wr * 64 + fr, col0 = u.pn * BM + wc * 32 + 8 * fq;
;         const float* g = gate + (size_t)(u.pm >> 4) * 24576;
; #pragma unroll
;         for (int bj = 0; bj < 2; ++bj) { const int col = col0 + bj * HALF; const f32x4 g0 = *(const f32x4*)(g + col), g1 = *(const f32x4*)(g + col + 4);
;             const f32x4 a0 = *(const f32x4*)(ln_g + col) * alpha, a1 = *(const f32x4*)(ln_g + col + 4) * alpha, b0 = *(const f32x4*)(ln_b + col) * alpha, b1 = *(const f32x4*)(ln_b + col + 4) * alpha;
; #pragma unroll
;             for (int ai = 0; ai < 2; ++ai)
; #pragma unroll
;                 for (int m = 0; m < 4; ++m) { const size_t row = (size_t)(row0 + ai * HALF + m * 16), off = row * 4096 + col; const f2_ st = *(const f2_*)(stats + 2 * row); const float mean = st.x, rstd = st.y;
;                     const f32x4 x0 = (*(const f32x4*)(r1 + off) - mean) * rstd, x1 = (*(const f32x4*)(r1 + off + 4) - mean) * rstd;
;                     *(f32x4*)(out + off) = x0 * a0 + b0 + g0 * acc[ai][bj][m][0]; *(f32x4*)(out + off + 4) = x1 * a1 + b1 + g1 * acc[ai][bj][m][1]; } }
;     }
.LBB0_1331:
	v_lshl_add_u32 v170, s49, 8, v188
	v_lshl_or_b32 v152, s50, 8, v190
	v_readlane_b32 s52, v254, 32
	v_ashrrev_i32_e32 v153, 31, v152
	v_readlane_b32 s56, v254, 36
	v_readlane_b32 s57, v254, 37
	v_ashrrev_i32_e32 v171, 31, v170
	v_lshlrev_b64 v[128:129], 2, v[152:153]
	v_readlane_b32 s58, v254, 38
	v_readlane_b32 s59, v254, 39
	s_mov_b64 s[20:21], s[56:57]
	v_lshlrev_b64 v[164:165], 12, v[170:171]
	s_mov_b64 s[22:23], s[58:59]
	v_lshl_add_u64 v[158:159], s[20:21], 0, v[128:129]
	v_lshl_add_u64 v[130:131], v[164:165], 0, v[152:153]
	s_ashr_i32 s20, s49, 4
	global_load_dwordx4 v[174:177], v[158:159], off offset:16
	global_load_dwordx4 v[180:183], v[158:159], off
	v_lshl_add_u64 v[160:161], s[22:23], 0, v[128:129]
	v_lshl_add_u64 v[162:163], v[170:171], 3, s[10:11]
	v_lshlrev_b64 v[156:157], 2, v[130:131]
	s_mul_hi_i32 s21, s20, 0x18000
	s_mul_i32 s20, s20, 0x18000
	global_load_dwordx4 v[194:197], v[160:161], off offset:16
	global_load_dwordx4 v[198:201], v[160:161], off
	v_lshl_add_u64 v[130:131], s[8:9], 0, v[156:157]
	global_load_dwordx2 v[210:211], v[162:163], off
	global_load_dwordx4 v[202:205], v[130:131], off
	global_load_dwordx4 v[206:209], v[130:131], off offset:16
	s_add_u32 s20, s40, s20
	s_addc_u32 s21, s41, s21
	v_lshl_add_u64 v[166:167], s[20:21], 0, v[128:129]
	global_load_dwordx4 v[132:135], v[166:167], off
	global_load_dwordx4 v[128:131], v[166:167], off offset:16
	v_or_b32_e32 v154, 16, v170
	v_ashrrev_i32_e32 v155, 31, v154
	v_lshlrev_b64 v[168:169], 12, v[154:155]
	v_lshl_add_u64 v[172:173], v[168:169], 0, v[152:153]
	v_lshlrev_b64 v[212:213], 2, v[172:173]
	v_lshl_add_u64 v[156:157], s[92:93], 0, v[156:157]
	v_lshl_add_u64 v[154:155], v[154:155], 3, s[10:11]
	v_lshl_add_u64 v[214:215], s[8:9], 0, v[212:213]
	s_and_b64 vcc, exec, s[2:3]
	s_mov_b64 s[2:3], -1
	v_readlane_b32 s53, v254, 33
	v_readlane_b32 s54, v254, 34
	v_readlane_b32 s55, v254, 35
	v_readlane_b32 s60, v254, 40
	v_readlane_b32 s61, v254, 41
	v_readlane_b32 s62, v254, 42
	v_readlane_b32 s63, v254, 43
	v_readlane_b32 s64, v254, 44
	v_readlane_b32 s65, v254, 45
	v_readlane_b32 s66, v254, 46
	v_readlane_b32 s67, v254, 47
	s_waitcnt vmcnt(0)
	v_pk_mul_f32 v[172:173], v[176:177], s[16:17] op_sel_hi:[1,0]
	v_pk_mul_f32 v[178:179], v[182:183], s[16:17] op_sel_hi:[1,0]
	v_pk_mul_f32 v[182:183], v[180:181], s[16:17] op_sel_hi:[1,0]
	v_pk_mul_f32 v[174:175], v[174:175], s[16:17] op_sel_hi:[1,0]
	v_pk_mul_f32 v[176:177], v[196:197], s[16:17] op_sel_hi:[1,0]
	v_pk_mul_f32 v[180:181], v[194:195], s[16:17] op_sel_hi:[1,0]
	v_sub_f32_e32 v195, v203, v210
	v_sub_f32_e32 v194, v202, v210
	v_sub_f32_e32 v197, v205, v210
	v_sub_f32_e32 v196, v204, v210
	v_pk_mul_f32 v[184:185], v[200:201], s[16:17] op_sel_hi:[1,0]
	v_pk_mul_f32 v[186:187], v[198:199], s[16:17] op_sel_hi:[1,0]
	v_sub_f32_e32 v199, v207, v210
	v_sub_f32_e32 v198, v206, v210
	v_sub_f32_e32 v201, v209, v210
	v_sub_f32_e32 v200, v208, v210
	v_pk_mul_f32 v[196:197], v[210:211], v[196:197] op_sel:[1,0]
	v_pk_mul_f32 v[194:195], v[210:211], v[194:195] op_sel:[1,0]
	v_pk_mul_f32 v[200:201], v[210:211], v[200:201] op_sel:[1,0]
	v_pk_mul_f32 v[198:199], v[210:211], v[198:199] op_sel:[1,0]
	v_pk_fma_f32 v[194:195], v[182:183], v[194:195], v[186:187]
	v_pk_fma_f32 v[196:197], v[178:179], v[196:197], v[184:185]
	v_pk_fma_f32 v[198:199], v[174:175], v[198:199], v[180:181]
	v_pk_fma_f32 v[200:201], v[172:173], v[200:201], v[176:177]
	v_pk_fma_f32 v[126:127], v[126:127], v[134:135], v[196:197]
	v_pk_fma_f32 v[124:125], v[124:125], v[132:133], v[194:195]
	v_pk_fma_f32 v[122:123], v[122:123], v[130:131], v[200:201]
	v_pk_fma_f32 v[120:121], v[120:121], v[128:129], v[198:199]
	global_store_dwordx4 v[156:157], v[124:127], off
	global_store_dwordx4 v[156:157], v[120:123], off offset:16
	global_load_dwordx2 v[126:127], v[154:155], off
	s_nop 0
	global_load_dwordx4 v[194:197], v[214:215], off
	global_load_dwordx4 v[198:201], v[214:215], off offset:16
	v_or_b32_e32 v120, 32, v170
	v_ashrrev_i32_e32 v121, 31, v120
	v_lshlrev_b64 v[124:125], 12, v[120:121]
	v_lshl_add_u64 v[122:123], v[124:125], 0, v[152:153]
	v_lshlrev_b64 v[202:203], 2, v[122:123]
	v_lshl_add_u64 v[122:123], s[92:93], 0, v[212:213]
	v_lshl_add_u64 v[120:121], v[120:121], 3, s[10:11]
	v_lshl_add_u64 v[204:205], s[8:9], 0, v[202:203]
	s_waitcnt vmcnt(1)
	v_sub_f32_e32 v195, v195, v126
	v_sub_f32_e32 v194, v194, v126
	v_sub_f32_e32 v197, v197, v126
	v_sub_f32_e32 v196, v196, v126
	s_waitcnt vmcnt(0)
	v_sub_f32_e32 v199, v199, v126
	v_sub_f32_e32 v198, v198, v126
	v_sub_f32_e32 v201, v201, v126
	v_sub_f32_e32 v200, v200, v126
	v_pk_mul_f32 v[196:197], v[126:127], v[196:197] op_sel:[1,0]
	v_pk_mul_f32 v[194:195], v[126:127], v[194:195] op_sel:[1,0]
	v_pk_mul_f32 v[200:201], v[126:127], v[200:201] op_sel:[1,0]
	v_pk_mul_f32 v[126:127], v[126:127], v[198:199] op_sel:[1,0]
	v_pk_fma_f32 v[194:195], v[182:183], v[194:195], v[186:187]
	v_pk_fma_f32 v[196:197], v[178:179], v[196:197], v[184:185]
	v_pk_fma_f32 v[126:127], v[174:175], v[126:127], v[180:181]
	v_pk_fma_f32 v[198:199], v[172:173], v[200:201], v[176:177]
	v_pk_fma_f32 v[118:119], v[118:119], v[134:135], v[196:197]
	v_pk_fma_f32 v[116:117], v[116:117], v[132:133], v[194:195]
	v_pk_fma_f32 v[114:115], v[114:115], v[130:131], v[198:199]
	v_pk_fma_f32 v[112:113], v[112:113], v[128:129], v[126:127]
	global_store_dwordx4 v[122:123], v[116:119], off
	global_store_dwordx4 v[122:123], v[112:115], off offset:16
	global_load_dwordx2 v[118:119], v[120:121], off
	s_nop 0
	global_load_dwordx4 v[194:197], v[204:205], off
	global_load_dwordx4 v[198:201], v[204:205], off offset:16
	v_or_b32_e32 v112, 48, v170
	v_ashrrev_i32_e32 v113, 31, v112
	v_lshlrev_b64 v[116:117], 12, v[112:113]
	v_lshl_add_u64 v[114:115], v[116:117], 0, v[152:153]
	v_lshlrev_b64 v[126:127], 2, v[114:115]
	v_lshl_add_u64 v[114:115], s[92:93], 0, v[202:203]
	v_lshl_add_u64 v[112:113], v[112:113], 3, s[10:11]
	v_lshl_add_u64 v[202:203], s[8:9], 0, v[126:127]
	s_waitcnt vmcnt(1)
;     __device__ __forceinline__ void operator()(const f32x4 (&acc)[2][2][4][2], const Unit& u, int wr, int wc, int fr, int fq) const {
;         typedef float f2_ __attribute__((ext_vector_type(2)));
;         const int row0 = u.pm * BM + wr * 64 + fr, col0 = u.pn * BM + wc * 32 + 8 * fq;
;         const float* g = gate + (size_t)(u.pm >> 4) * 24576;
; #pragma unroll
;         for (int bj = 0; bj < 2; ++bj) { const int col = col0 + bj * HALF; const f32x4 g0 = *(const f32x4*)(g + col), g1 = *(const f32x4*)(g + col + 4);
;             const f32x4 a0 = *(const f32x4*)(ln_g + col) * alpha, a1 = *(const f32x4*)(ln_g + col + 4) * alpha, b0 = *(const f32x4*)(ln_b + col) * alpha, b1 = *(const f32x4*)(ln_b + col + 4) * alpha;
; #pragma unroll
;             for (int ai = 0; ai < 2; ++ai)
; #pragma unroll
;                 for (int m = 0; m < 4; ++m) { const size_t row = (size_t)(row0 + ai * HALF + m * 16), off = row * 4096 + col; const f2_ st = *(const f2_*)(stats + 2 * row); const float mean = st.x, rstd = st.y;
;                     const f32x4 x0 = (*(const f32x4*)(r1 + off) - mean) * rstd, x1 = (*(const f32x4*)(r1 + off + 4) - mean) * rstd;
;                     *(f32x4*)(out + off) = x0 * a0 + b0 + g0 * acc[ai][bj][m][0]; *(f32x4*)(out + off + 4) = x1 * a1 + b1 + g1 * acc[ai][bj][m][1]; } }
;     }
	v_sub_f32_e32 v195, v195, v118
	v_sub_f32_e32 v194, v194, v118
	v_sub_f32_e32 v197, v197, v118
	v_sub_f32_e32 v196, v196, v118
	s_waitcnt vmcnt(0)
	v_sub_f32_e32 v199, v199, v118
	v_sub_f32_e32 v198, v198, v118
	v_sub_f32_e32 v201, v201, v118
	v_sub_f32_e32 v200, v200, v118
	v_pk_mul_f32 v[196:197], v[118:119], v[196:197] op_sel:[1,0]
	v_pk_mul_f32 v[194:195], v[118:119], v[194:195] op_sel:[1,0]
	v_pk_mul_f32 v[200:201], v[118:119], v[200:201] op_sel:[1,0]
	v_pk_mul_f32 v[118:119], v[118:119], v[198:199] op_sel:[1,0]
	v_pk_fma_f32 v[194:195], v[182:183], v[194:195], v[186:187]
	v_pk_fma_f32 v[196:197], v[178:179], v[196:197], v[184:185]
	v_pk_fma_f32 v[118:119], v[174:175], v[118:119], v[180:181]
	v_pk_fma_f32 v[198:199], v[172:173], v[200:201], v[176:177]
	v_pk_fma_f32 v[110:111], v[110:111], v[134:135], v[196:197]
	v_pk_fma_f32 v[108:109], v[108:109], v[132:133], v[194:195]
	v_pk_fma_f32 v[106:107], v[106:107], v[130:131], v[198:199]
	v_pk_fma_f32 v[104:105], v[104:105], v[128:129], v[118:119]
	global_store_dwordx4 v[114:115], v[108:111], off
	global_store_dwordx4 v[114:115], v[104:107], off offset:16
	global_load_dwordx2 v[110:111], v[112:113], off
	s_nop 0
	global_load_dwordx4 v[194:197], v[202:203], off
	global_load_dwordx4 v[198:201], v[202:203], off offset:16
	v_add_u32_e32 v106, 0x80, v170
	v_ashrrev_i32_e32 v107, 31, v106
	v_lshlrev_b64 v[104:105], 12, v[106:107]
	v_lshl_add_u64 v[108:109], v[104:105], 0, v[152:153]
	v_lshlrev_b64 v[118:119], 2, v[108:109]
	v_lshl_add_u64 v[108:109], s[92:93], 0, v[126:127]
	v_lshl_add_u64 v[106:107], v[106:107], 3, s[10:11]
	v_lshl_add_u64 v[126:127], s[8:9], 0, v[118:119]
	s_waitcnt vmcnt(1)
	v_sub_f32_e32 v195, v195, v110
	v_sub_f32_e32 v194, v194, v110
	v_sub_f32_e32 v197, v197, v110
	v_sub_f32_e32 v196, v196, v110
	s_waitcnt vmcnt(0)
	v_sub_f32_e32 v199, v199, v110
	v_sub_f32_e32 v198, v198, v110
	v_sub_f32_e32 v201, v201, v110
	v_sub_f32_e32 v200, v200, v110
	v_pk_mul_f32 v[196:197], v[110:111], v[196:197] op_sel:[1,0]
	v_pk_mul_f32 v[194:195], v[110:111], v[194:195] op_sel:[1,0]
	v_pk_mul_f32 v[200:201], v[110:111], v[200:201] op_sel:[1,0]
	v_pk_mul_f32 v[110:111], v[110:111], v[198:199] op_sel:[1,0]
	v_pk_fma_f32 v[194:195], v[182:183], v[194:195], v[186:187]
	v_pk_fma_f32 v[196:197], v[178:179], v[196:197], v[184:185]
	v_pk_fma_f32 v[110:111], v[174:175], v[110:111], v[180:181]
	v_pk_fma_f32 v[198:199], v[172:173], v[200:201], v[176:177]
	v_pk_fma_f32 v[102:103], v[102:103], v[134:135], v[196:197]
	v_pk_fma_f32 v[100:101], v[100:101], v[132:133], v[194:195]
	v_pk_fma_f32 v[98:99], v[98:99], v[130:131], v[198:199]
	v_pk_fma_f32 v[96:97], v[96:97], v[128:129], v[110:111]
	global_store_dwordx4 v[108:109], v[100:103], off
	global_store_dwordx4 v[108:109], v[96:99], off offset:16
	global_load_dwordx2 v[102:103], v[106:107], off
	s_nop 0
	global_load_dwordx4 v[194:197], v[126:127], off
	global_load_dwordx4 v[198:201], v[126:127], off offset:16
	v_add_u32_e32 v96, 0x90, v170
	v_ashrrev_i32_e32 v97, 31, v96
	v_lshlrev_b64 v[100:101], 12, v[96:97]
	v_lshl_add_u64 v[98:99], v[100:101], 0, v[152:153]
	v_lshlrev_b64 v[110:111], 2, v[98:99]
	v_lshl_add_u64 v[98:99], s[92:93], 0, v[118:119]
	v_lshl_add_u64 v[96:97], v[96:97], 3, s[10:11]
	v_lshl_add_u64 v[118:119], s[8:9], 0, v[110:111]
	s_waitcnt vmcnt(1)
	v_sub_f32_e32 v127, v195, v102
	v_sub_f32_e32 v126, v194, v102
	v_sub_f32_e32 v195, v197, v102
	v_sub_f32_e32 v194, v196, v102
	s_waitcnt vmcnt(0)
	v_sub_f32_e32 v197, v199, v102
	v_sub_f32_e32 v196, v198, v102
	v_sub_f32_e32 v199, v201, v102
	v_sub_f32_e32 v198, v200, v102
	v_pk_mul_f32 v[194:195], v[102:103], v[194:195] op_sel:[1,0]
	v_pk_mul_f32 v[126:127], v[102:103], v[126:127] op_sel:[1,0]
	v_pk_mul_f32 v[198:199], v[102:103], v[198:199] op_sel:[1,0]
	v_pk_mul_f32 v[102:103], v[102:103], v[196:197] op_sel:[1,0]
	v_pk_fma_f32 v[126:127], v[182:183], v[126:127], v[186:187]
	v_pk_fma_f32 v[194:195], v[178:179], v[194:195], v[184:185]
	v_pk_fma_f32 v[102:103], v[174:175], v[102:103], v[180:181]
	v_pk_fma_f32 v[196:197], v[172:173], v[198:199], v[176:177]
	v_pk_fma_f32 v[94:95], v[94:95], v[134:135], v[194:195]
	v_pk_fma_f32 v[92:93], v[92:93], v[132:133], v[126:127]
	v_pk_fma_f32 v[90:91], v[90:91], v[130:131], v[196:197]
	v_pk_fma_f32 v[88:89], v[88:89], v[128:129], v[102:103]
	global_store_dwordx4 v[98:99], v[92:95], off
	global_store_dwordx4 v[98:99], v[88:91], off offset:16
	global_load_dwordx2 v[94:95], v[96:97], off
	s_nop 0
	global_load_dwordx4 v[194:197], v[118:119], off
	global_load_dwordx4 v[198:201], v[118:119], off offset:16
	v_add_u32_e32 v88, 0xa0, v170
	v_ashrrev_i32_e32 v89, 31, v88
	v_lshlrev_b64 v[92:93], 12, v[88:89]
	v_lshl_add_u64 v[90:91], v[92:93], 0, v[152:153]
	v_lshlrev_b64 v[102:103], 2, v[90:91]
	v_lshl_add_u64 v[90:91], s[92:93], 0, v[110:111]
	v_lshl_add_u64 v[88:89], v[88:89], 3, s[10:11]
	v_lshl_add_u64 v[110:111], s[8:9], 0, v[102:103]
	s_waitcnt vmcnt(1)
	v_sub_f32_e32 v119, v195, v94
	v_sub_f32_e32 v118, v194, v94
	v_sub_f32_e32 v127, v197, v94
	v_sub_f32_e32 v126, v196, v94
	s_waitcnt vmcnt(0)
;     __device__ __forceinline__ void operator()(const f32x4 (&acc)[2][2][4][2], const Unit& u, int wr, int wc, int fr, int fq) const {
;         typedef float f2_ __attribute__((ext_vector_type(2)));
;         const int row0 = u.pm * BM + wr * 64 + fr, col0 = u.pn * BM + wc * 32 + 8 * fq;
;         const float* g = gate + (size_t)(u.pm >> 4) * 24576;
; #pragma unroll
;         for (int bj = 0; bj < 2; ++bj) { const int col = col0 + bj * HALF; const f32x4 g0 = *(const f32x4*)(g + col), g1 = *(const f32x4*)(g + col + 4);
;             const f32x4 a0 = *(const f32x4*)(ln_g + col) * alpha, a1 = *(const f32x4*)(ln_g + col + 4) * alpha, b0 = *(const f32x4*)(ln_b + col) * alpha, b1 = *(const f32x4*)(ln_b + col + 4) * alpha;
; #pragma unroll
;             for (int ai = 0; ai < 2; ++ai)
; #pragma unroll
;                 for (int m = 0; m < 4; ++m) { const size_t row = (size_t)(row0 + ai * HALF + m * 16), off = row * 4096 + col; const f2_ st = *(const f2_*)(stats + 2 * row); const float mean = st.x, rstd = st.y;
;                     const f32x4 x0 = (*(const f32x4*)(r1 + off) - mean) * rstd, x1 = (*(const f32x4*)(r1 + off + 4) - mean) * rstd;
;                     *(f32x4*)(out + off) = x0 * a0 + b0 + g0 * acc[ai][bj][m][0]; *(f32x4*)(out + off + 4) = x1 * a1 + b1 + g1 * acc[ai][bj][m][1]; } }
;     }
	v_sub_f32_e32 v195, v199, v94
	v_sub_f32_e32 v194, v198, v94
	v_sub_f32_e32 v197, v201, v94
	v_sub_f32_e32 v196, v200, v94
	v_pk_mul_f32 v[126:127], v[94:95], v[126:127] op_sel:[1,0]
	v_pk_mul_f32 v[118:119], v[94:95], v[118:119] op_sel:[1,0]
	v_pk_mul_f32 v[196:197], v[94:95], v[196:197] op_sel:[1,0]
	v_pk_mul_f32 v[94:95], v[94:95], v[194:195] op_sel:[1,0]
	v_pk_fma_f32 v[118:119], v[182:183], v[118:119], v[186:187]
	v_pk_fma_f32 v[126:127], v[178:179], v[126:127], v[184:185]
	v_pk_fma_f32 v[94:95], v[174:175], v[94:95], v[180:181]
	v_pk_fma_f32 v[194:195], v[172:173], v[196:197], v[176:177]
	v_pk_fma_f32 v[86:87], v[86:87], v[134:135], v[126:127]
	v_pk_fma_f32 v[84:85], v[84:85], v[132:133], v[118:119]
	v_pk_fma_f32 v[82:83], v[82:83], v[130:131], v[194:195]
	v_pk_fma_f32 v[80:81], v[80:81], v[128:129], v[94:95]
	global_store_dwordx4 v[90:91], v[84:87], off
	global_store_dwordx4 v[90:91], v[80:83], off offset:16
	global_load_dwordx2 v[86:87], v[88:89], off
	s_nop 0
	global_load_dwordx4 v[194:197], v[110:111], off
	global_load_dwordx4 v[198:201], v[110:111], off offset:16
	v_add_u32_e32 v80, 0xb0, v170
	v_ashrrev_i32_e32 v81, 31, v80
	v_lshlrev_b64 v[84:85], 12, v[80:81]
	v_lshl_add_u64 v[82:83], v[84:85], 0, v[152:153]
	v_lshlrev_b64 v[94:95], 2, v[82:83]
	v_lshl_add_u64 v[82:83], s[92:93], 0, v[102:103]
	v_lshl_add_u64 v[80:81], v[80:81], 3, s[10:11]
	v_lshl_add_u64 v[102:103], s[8:9], 0, v[94:95]
	s_waitcnt vmcnt(1)
	v_sub_f32_e32 v111, v195, v86
	v_sub_f32_e32 v110, v194, v86
	v_sub_f32_e32 v119, v197, v86
	v_sub_f32_e32 v118, v196, v86
	s_waitcnt vmcnt(0)
	v_sub_f32_e32 v127, v199, v86
	v_sub_f32_e32 v126, v198, v86
	v_sub_f32_e32 v171, v201, v86
	v_sub_f32_e32 v170, v200, v86
	v_pk_mul_f32 v[118:119], v[86:87], v[118:119] op_sel:[1,0]
	v_pk_mul_f32 v[110:111], v[86:87], v[110:111] op_sel:[1,0]
	v_pk_mul_f32 v[170:171], v[86:87], v[170:171] op_sel:[1,0]
	v_pk_mul_f32 v[86:87], v[86:87], v[126:127] op_sel:[1,0]
	v_pk_fma_f32 v[110:111], v[182:183], v[110:111], v[186:187]
	v_pk_fma_f32 v[118:119], v[178:179], v[118:119], v[184:185]
	v_pk_fma_f32 v[86:87], v[174:175], v[86:87], v[180:181]
	v_pk_fma_f32 v[126:127], v[172:173], v[170:171], v[176:177]
	v_pk_fma_f32 v[78:79], v[78:79], v[134:135], v[118:119]
	v_pk_fma_f32 v[76:77], v[76:77], v[132:133], v[110:111]
	v_pk_fma_f32 v[74:75], v[74:75], v[130:131], v[126:127]
	v_pk_fma_f32 v[72:73], v[72:73], v[128:129], v[86:87]
	global_store_dwordx4 v[82:83], v[76:79], off
	global_store_dwordx4 v[82:83], v[72:75], off offset:16
	global_load_dwordx2 v[78:79], v[80:81], off
	s_nop 0
	global_load_dwordx4 v[74:77], v[102:103], off
	global_load_dwordx4 v[194:197], v[102:103], off offset:16
	v_lshl_add_u64 v[72:73], s[92:93], 0, v[94:95]
	v_or_b32_e32 v126, 0x80, v152
	v_ashrrev_i32_e32 v127, 31, v126
	v_lshl_add_u64 v[124:125], v[124:125], 0, v[126:127]
	v_lshl_add_u64 v[124:125], v[124:125], 2, s[8:9]
	s_waitcnt vmcnt(1)
	v_sub_f32_e32 v75, v75, v78
	v_sub_f32_e32 v74, v74, v78
	v_sub_f32_e32 v77, v77, v78
	v_sub_f32_e32 v76, v76, v78
	s_waitcnt vmcnt(0)
	v_sub_f32_e32 v87, v195, v78
	v_sub_f32_e32 v86, v194, v78
	v_sub_f32_e32 v95, v197, v78
	v_sub_f32_e32 v94, v196, v78
	v_pk_mul_f32 v[76:77], v[78:79], v[76:77] op_sel:[1,0]
	v_pk_mul_f32 v[74:75], v[78:79], v[74:75] op_sel:[1,0]
	v_pk_mul_f32 v[94:95], v[78:79], v[94:95] op_sel:[1,0]
	v_pk_mul_f32 v[78:79], v[78:79], v[86:87] op_sel:[1,0]
	v_pk_fma_f32 v[74:75], v[182:183], v[74:75], v[186:187]
	v_pk_fma_f32 v[76:77], v[178:179], v[76:77], v[184:185]
	v_pk_fma_f32 v[78:79], v[174:175], v[78:79], v[180:181]
	v_pk_fma_f32 v[86:87], v[172:173], v[94:95], v[176:177]
	v_pk_fma_f32 v[70:71], v[70:71], v[134:135], v[76:77]
	v_pk_fma_f32 v[68:69], v[68:69], v[132:133], v[74:75]
	v_pk_fma_f32 v[66:67], v[66:67], v[130:131], v[86:87]
	v_pk_fma_f32 v[64:65], v[64:65], v[128:129], v[78:79]
	global_store_dwordx4 v[72:73], v[68:71], off
	global_store_dwordx4 v[72:73], v[64:67], off offset:16
	global_load_dwordx4 v[128:131], v[158:159], off offset:528
	global_load_dwordx4 v[76:79], v[158:159], off offset:512
	global_load_dwordx4 v[132:135], v[160:161], off offset:528
	s_nop 0
	global_load_dwordx4 v[158:161], v[160:161], off offset:512
	v_lshl_add_u64 v[64:65], v[164:165], 0, v[126:127]
	v_lshl_add_u64 v[64:65], v[64:65], 2, s[8:9]
	global_load_dwordx2 v[152:153], v[162:163], off
	s_nop 0
	global_load_dwordx4 v[162:165], v[64:65], off
	global_load_dwordx4 v[170:173], v[64:65], off offset:16
	global_load_dwordx4 v[68:71], v[166:167], off offset:512
	s_nop 0
	global_load_dwordx4 v[64:67], v[166:167], off offset:528
	v_lshl_add_u64 v[74:75], v[168:169], 0, v[126:127]
	v_lshl_add_u64 v[166:167], v[74:75], 2, s[8:9]
	s_waitcnt vmcnt(8)
	v_pk_mul_f32 v[86:87], v[128:129], s[16:17] op_sel_hi:[1,0]
	s_waitcnt vmcnt(7)
	v_pk_mul_f32 v[74:75], v[78:79], s[16:17] op_sel_hi:[1,0]
	v_pk_mul_f32 v[78:79], v[76:77], s[16:17] op_sel_hi:[1,0]
	v_pk_mul_f32 v[76:77], v[130:131], s[16:17] op_sel_hi:[1,0]
	s_waitcnt vmcnt(3)
	v_sub_f32_e32 v129, v163, v152
	v_sub_f32_e32 v128, v162, v152
	v_sub_f32_e32 v131, v165, v152
	v_sub_f32_e32 v130, v164, v152
	v_pk_mul_f32 v[94:95], v[160:161], s[16:17] op_sel_hi:[1,0]
	v_pk_mul_f32 v[110:111], v[158:159], s[16:17] op_sel_hi:[1,0]
	v_pk_mul_f32 v[102:103], v[134:135], s[16:17] op_sel_hi:[1,0]
	v_pk_mul_f32 v[118:119], v[132:133], s[16:17] op_sel_hi:[1,0]
	s_waitcnt vmcnt(2)
;     __device__ __forceinline__ void operator()(const f32x4 (&acc)[2][2][4][2], const Unit& u, int wr, int wc, int fr, int fq) const {
;         typedef float f2_ __attribute__((ext_vector_type(2)));
;         const int row0 = u.pm * BM + wr * 64 + fr, col0 = u.pn * BM + wc * 32 + 8 * fq;
;         const float* g = gate + (size_t)(u.pm >> 4) * 24576;
; #pragma unroll
;         for (int bj = 0; bj < 2; ++bj) { const int col = col0 + bj * HALF; const f32x4 g0 = *(const f32x4*)(g + col), g1 = *(const f32x4*)(g + col + 4);
;             const f32x4 a0 = *(const f32x4*)(ln_g + col) * alpha, a1 = *(const f32x4*)(ln_g + col + 4) * alpha, b0 = *(const f32x4*)(ln_b + col) * alpha, b1 = *(const f32x4*)(ln_b + col + 4) * alpha;
; #pragma unroll
;             for (int ai = 0; ai < 2; ++ai)
; #pragma unroll
;                 for (int m = 0; m < 4; ++m) { const size_t row = (size_t)(row0 + ai * HALF + m * 16), off = row * 4096 + col; const f2_ st = *(const f2_*)(stats + 2 * row); const float mean = st.x, rstd = st.y;
;                     const f32x4 x0 = (*(const f32x4*)(r1 + off) - mean) * rstd, x1 = (*(const f32x4*)(r1 + off + 4) - mean) * rstd;
;                     *(f32x4*)(out + off) = x0 * a0 + b0 + g0 * acc[ai][bj][m][0]; *(f32x4*)(out + off + 4) = x1 * a1 + b1 + g1 * acc[ai][bj][m][1]; } }
;     }
	v_sub_f32_e32 v133, v171, v152
	v_sub_f32_e32 v132, v170, v152
	v_sub_f32_e32 v135, v173, v152
	v_sub_f32_e32 v134, v172, v152
	v_pk_mul_f32 v[130:131], v[152:153], v[130:131] op_sel:[1,0]
	v_pk_mul_f32 v[128:129], v[152:153], v[128:129] op_sel:[1,0]
	v_pk_mul_f32 v[134:135], v[152:153], v[134:135] op_sel:[1,0]
	v_pk_mul_f32 v[132:133], v[152:153], v[132:133] op_sel:[1,0]
	v_pk_fma_f32 v[128:129], v[78:79], v[128:129], v[110:111]
	v_pk_fma_f32 v[130:131], v[74:75], v[130:131], v[94:95]
	v_pk_fma_f32 v[132:133], v[86:87], v[132:133], v[118:119]
	v_pk_fma_f32 v[134:135], v[76:77], v[134:135], v[102:103]
	s_waitcnt vmcnt(1)
	v_pk_fma_f32 v[62:63], v[62:63], v[70:71], v[130:131]
	v_pk_fma_f32 v[60:61], v[60:61], v[68:69], v[128:129]
	s_waitcnt vmcnt(0)
	v_pk_fma_f32 v[58:59], v[58:59], v[66:67], v[134:135]
	v_pk_fma_f32 v[56:57], v[56:57], v[64:65], v[132:133]
	global_store_dwordx4 v[156:157], v[60:63], off offset:512
	global_store_dwordx4 v[156:157], v[56:59], off offset:528
	global_load_dwordx2 v[128:129], v[154:155], off
	s_nop 0
	global_load_dwordx4 v[56:59], v[166:167], off
	global_load_dwordx4 v[60:63], v[166:167], off offset:16
	s_waitcnt vmcnt(1)
	v_sub_f32_e32 v57, v57, v128
	v_sub_f32_e32 v56, v56, v128
	v_sub_f32_e32 v59, v59, v128
	v_sub_f32_e32 v58, v58, v128
	s_waitcnt vmcnt(0)
	v_sub_f32_e32 v61, v61, v128
	v_sub_f32_e32 v60, v60, v128
	v_sub_f32_e32 v63, v63, v128
	v_sub_f32_e32 v62, v62, v128
	v_pk_mul_f32 v[58:59], v[128:129], v[58:59] op_sel:[1,0]
	v_pk_mul_f32 v[56:57], v[128:129], v[56:57] op_sel:[1,0]
	v_pk_mul_f32 v[62:63], v[128:129], v[62:63] op_sel:[1,0]
	v_pk_mul_f32 v[60:61], v[128:129], v[60:61] op_sel:[1,0]
	v_pk_fma_f32 v[56:57], v[78:79], v[56:57], v[110:111]
	v_pk_fma_f32 v[58:59], v[74:75], v[58:59], v[94:95]
	v_pk_fma_f32 v[60:61], v[86:87], v[60:61], v[118:119]
	v_pk_fma_f32 v[62:63], v[76:77], v[62:63], v[102:103]
	v_pk_fma_f32 v[54:55], v[54:55], v[70:71], v[58:59]
	v_pk_fma_f32 v[52:53], v[52:53], v[68:69], v[56:57]
	v_pk_fma_f32 v[50:51], v[50:51], v[66:67], v[62:63]
	v_pk_fma_f32 v[48:49], v[48:49], v[64:65], v[60:61]
	global_store_dwordx4 v[122:123], v[52:55], off offset:512
	global_store_dwordx4 v[122:123], v[48:51], off offset:528
	global_load_dwordx2 v[56:57], v[120:121], off
	s_nop 0
	global_load_dwordx4 v[48:51], v[124:125], off
	global_load_dwordx4 v[52:55], v[124:125], off offset:16
	v_lshl_add_u64 v[58:59], v[116:117], 0, v[126:127]
	v_lshl_add_u64 v[58:59], v[58:59], 2, s[8:9]
	s_waitcnt vmcnt(1)
	v_sub_f32_e32 v49, v49, v56
	v_sub_f32_e32 v48, v48, v56
	v_sub_f32_e32 v51, v51, v56
	v_sub_f32_e32 v50, v50, v56
	s_waitcnt vmcnt(0)
	v_sub_f32_e32 v53, v53, v56
	v_sub_f32_e32 v52, v52, v56
	v_sub_f32_e32 v55, v55, v56
	v_sub_f32_e32 v54, v54, v56
	v_pk_mul_f32 v[50:51], v[56:57], v[50:51] op_sel:[1,0]
	v_pk_mul_f32 v[48:49], v[56:57], v[48:49] op_sel:[1,0]
	v_pk_mul_f32 v[54:55], v[56:57], v[54:55] op_sel:[1,0]
	v_pk_mul_f32 v[52:53], v[56:57], v[52:53] op_sel:[1,0]
	v_pk_fma_f32 v[48:49], v[78:79], v[48:49], v[110:111]
	v_pk_fma_f32 v[50:51], v[74:75], v[50:51], v[94:95]
	v_pk_fma_f32 v[52:53], v[86:87], v[52:53], v[118:119]
	v_pk_fma_f32 v[54:55], v[76:77], v[54:55], v[102:103]
	v_pk_fma_f32 v[46:47], v[46:47], v[70:71], v[50:51]
	v_pk_fma_f32 v[44:45], v[44:45], v[68:69], v[48:49]
	v_pk_fma_f32 v[42:43], v[42:43], v[66:67], v[54:55]
	v_pk_fma_f32 v[40:41], v[40:41], v[64:65], v[52:53]
	global_store_dwordx4 v[114:115], v[44:47], off offset:512
	global_store_dwordx4 v[114:115], v[40:43], off offset:528
	global_load_dwordx2 v[48:49], v[112:113], off
	s_nop 0
	global_load_dwordx4 v[40:43], v[58:59], off
	global_load_dwordx4 v[44:47], v[58:59], off offset:16
	v_lshl_add_u64 v[50:51], v[104:105], 0, v[126:127]
	v_lshl_add_u64 v[50:51], v[50:51], 2, s[8:9]
	s_waitcnt vmcnt(1)
	v_sub_f32_e32 v41, v41, v48
	v_sub_f32_e32 v40, v40, v48
	v_sub_f32_e32 v43, v43, v48
	v_sub_f32_e32 v42, v42, v48
	s_waitcnt vmcnt(0)
	v_sub_f32_e32 v45, v45, v48
	v_sub_f32_e32 v44, v44, v48
	v_sub_f32_e32 v47, v47, v48
	v_sub_f32_e32 v46, v46, v48
	v_pk_mul_f32 v[42:43], v[48:49], v[42:43] op_sel:[1,0]
	v_pk_mul_f32 v[40:41], v[48:49], v[40:41] op_sel:[1,0]
	v_pk_mul_f32 v[46:47], v[48:49], v[46:47] op_sel:[1,0]
	v_pk_mul_f32 v[44:45], v[48:49], v[44:45] op_sel:[1,0]
	v_pk_fma_f32 v[40:41], v[78:79], v[40:41], v[110:111]
	v_pk_fma_f32 v[42:43], v[74:75], v[42:43], v[94:95]
	v_pk_fma_f32 v[44:45], v[86:87], v[44:45], v[118:119]
	v_pk_fma_f32 v[46:47], v[76:77], v[46:47], v[102:103]
	v_pk_fma_f32 v[38:39], v[38:39], v[70:71], v[42:43]
	v_pk_fma_f32 v[36:37], v[36:37], v[68:69], v[40:41]
	v_pk_fma_f32 v[34:35], v[34:35], v[66:67], v[46:47]
	v_pk_fma_f32 v[32:33], v[32:33], v[64:65], v[44:45]
	global_store_dwordx4 v[108:109], v[36:39], off offset:512
	global_store_dwordx4 v[108:109], v[32:35], off offset:528
	global_load_dwordx2 v[40:41], v[106:107], off
	s_nop 0
	global_load_dwordx4 v[32:35], v[50:51], off
	global_load_dwordx4 v[36:39], v[50:51], off offset:16
	v_lshl_add_u64 v[42:43], v[100:101], 0, v[126:127]
	v_lshl_add_u64 v[42:43], v[42:43], 2, s[8:9]
	s_waitcnt vmcnt(1)
;     __device__ __forceinline__ void operator()(const f32x4 (&acc)[2][2][4][2], const Unit& u, int wr, int wc, int fr, int fq) const {
;         typedef float f2_ __attribute__((ext_vector_type(2)));
;         const int row0 = u.pm * BM + wr * 64 + fr, col0 = u.pn * BM + wc * 32 + 8 * fq;
;         const float* g = gate + (size_t)(u.pm >> 4) * 24576;
; #pragma unroll
;         for (int bj = 0; bj < 2; ++bj) { const int col = col0 + bj * HALF; const f32x4 g0 = *(const f32x4*)(g + col), g1 = *(const f32x4*)(g + col + 4);
;             const f32x4 a0 = *(const f32x4*)(ln_g + col) * alpha, a1 = *(const f32x4*)(ln_g + col + 4) * alpha, b0 = *(const f32x4*)(ln_b + col) * alpha, b1 = *(const f32x4*)(ln_b + col + 4) * alpha;
; #pragma unroll
;             for (int ai = 0; ai < 2; ++ai)
; #pragma unroll
;                 for (int m = 0; m < 4; ++m) { const size_t row = (size_t)(row0 + ai * HALF + m * 16), off = row * 4096 + col; const f2_ st = *(const f2_*)(stats + 2 * row); const float mean = st.x, rstd = st.y;
;                     const f32x4 x0 = (*(const f32x4*)(r1 + off) - mean) * rstd, x1 = (*(const f32x4*)(r1 + off + 4) - mean) * rstd;
;                     *(f32x4*)(out + off) = x0 * a0 + b0 + g0 * acc[ai][bj][m][0]; *(f32x4*)(out + off + 4) = x1 * a1 + b1 + g1 * acc[ai][bj][m][1]; } }
;     }
	v_sub_f32_e32 v33, v33, v40
	v_sub_f32_e32 v32, v32, v40
	v_sub_f32_e32 v35, v35, v40
	v_sub_f32_e32 v34, v34, v40
	s_waitcnt vmcnt(0)
	v_sub_f32_e32 v37, v37, v40
	v_sub_f32_e32 v36, v36, v40
	v_sub_f32_e32 v39, v39, v40
	v_sub_f32_e32 v38, v38, v40
	v_pk_mul_f32 v[34:35], v[40:41], v[34:35] op_sel:[1,0]
	v_pk_mul_f32 v[32:33], v[40:41], v[32:33] op_sel:[1,0]
	v_pk_mul_f32 v[38:39], v[40:41], v[38:39] op_sel:[1,0]
	v_pk_mul_f32 v[36:37], v[40:41], v[36:37] op_sel:[1,0]
	v_pk_fma_f32 v[32:33], v[78:79], v[32:33], v[110:111]
	v_pk_fma_f32 v[34:35], v[74:75], v[34:35], v[94:95]
	v_pk_fma_f32 v[36:37], v[86:87], v[36:37], v[118:119]
	v_pk_fma_f32 v[38:39], v[76:77], v[38:39], v[102:103]
	v_pk_fma_f32 v[30:31], v[30:31], v[70:71], v[34:35]
	v_pk_fma_f32 v[28:29], v[28:29], v[68:69], v[32:33]
	v_pk_fma_f32 v[26:27], v[26:27], v[66:67], v[38:39]
	v_pk_fma_f32 v[24:25], v[24:25], v[64:65], v[36:37]
	global_store_dwordx4 v[98:99], v[28:31], off offset:512
	global_store_dwordx4 v[98:99], v[24:27], off offset:528
	global_load_dwordx2 v[32:33], v[96:97], off
	s_nop 0
	global_load_dwordx4 v[24:27], v[42:43], off
	global_load_dwordx4 v[28:31], v[42:43], off offset:16
	v_lshl_add_u64 v[34:35], v[92:93], 0, v[126:127]
	v_lshl_add_u64 v[34:35], v[34:35], 2, s[8:9]
	s_waitcnt vmcnt(1)
	v_sub_f32_e32 v25, v25, v32
	v_sub_f32_e32 v24, v24, v32
	v_sub_f32_e32 v27, v27, v32
	v_sub_f32_e32 v26, v26, v32
	s_waitcnt vmcnt(0)
	v_sub_f32_e32 v29, v29, v32
	v_sub_f32_e32 v28, v28, v32
	v_sub_f32_e32 v31, v31, v32
	v_sub_f32_e32 v30, v30, v32
	v_pk_mul_f32 v[26:27], v[32:33], v[26:27] op_sel:[1,0]
	v_pk_mul_f32 v[24:25], v[32:33], v[24:25] op_sel:[1,0]
	v_pk_mul_f32 v[30:31], v[32:33], v[30:31] op_sel:[1,0]
	v_pk_mul_f32 v[28:29], v[32:33], v[28:29] op_sel:[1,0]
	v_pk_fma_f32 v[24:25], v[78:79], v[24:25], v[110:111]
	v_pk_fma_f32 v[26:27], v[74:75], v[26:27], v[94:95]
	v_pk_fma_f32 v[28:29], v[86:87], v[28:29], v[118:119]
	v_pk_fma_f32 v[30:31], v[76:77], v[30:31], v[102:103]
	v_pk_fma_f32 v[22:23], v[22:23], v[70:71], v[26:27]
	v_pk_fma_f32 v[20:21], v[20:21], v[68:69], v[24:25]
	v_pk_fma_f32 v[18:19], v[18:19], v[66:67], v[30:31]
	v_pk_fma_f32 v[16:17], v[16:17], v[64:65], v[28:29]
	global_store_dwordx4 v[90:91], v[20:23], off offset:512
	global_store_dwordx4 v[90:91], v[16:19], off offset:528
	global_load_dwordx2 v[24:25], v[88:89], off
	s_nop 0
	global_load_dwordx4 v[16:19], v[34:35], off
	global_load_dwordx4 v[20:23], v[34:35], off offset:16
	v_lshl_add_u64 v[26:27], v[84:85], 0, v[126:127]
	v_lshl_add_u64 v[26:27], v[26:27], 2, s[8:9]
	s_waitcnt vmcnt(1)
	v_sub_f32_e32 v17, v17, v24
	v_sub_f32_e32 v16, v16, v24
	v_sub_f32_e32 v19, v19, v24
	v_sub_f32_e32 v18, v18, v24
	s_waitcnt vmcnt(0)
	v_sub_f32_e32 v21, v21, v24
	v_sub_f32_e32 v20, v20, v24
	v_sub_f32_e32 v23, v23, v24
	v_sub_f32_e32 v22, v22, v24
	v_pk_mul_f32 v[18:19], v[24:25], v[18:19] op_sel:[1,0]
	v_pk_mul_f32 v[16:17], v[24:25], v[16:17] op_sel:[1,0]
	v_pk_mul_f32 v[22:23], v[24:25], v[22:23] op_sel:[1,0]
	v_pk_mul_f32 v[20:21], v[24:25], v[20:21] op_sel:[1,0]
	v_pk_fma_f32 v[16:17], v[78:79], v[16:17], v[110:111]
	v_pk_fma_f32 v[18:19], v[74:75], v[18:19], v[94:95]
	v_pk_fma_f32 v[20:21], v[86:87], v[20:21], v[118:119]
	v_pk_fma_f32 v[22:23], v[76:77], v[22:23], v[102:103]
	v_pk_fma_f32 v[14:15], v[14:15], v[70:71], v[18:19]
	v_pk_fma_f32 v[12:13], v[12:13], v[68:69], v[16:17]
	v_pk_fma_f32 v[10:11], v[10:11], v[66:67], v[22:23]
	v_pk_fma_f32 v[8:9], v[8:9], v[64:65], v[20:21]
	global_store_dwordx4 v[82:83], v[12:15], off offset:512
	global_store_dwordx4 v[82:83], v[8:11], off offset:528
	global_load_dwordx2 v[16:17], v[80:81], off
	s_nop 0
	global_load_dwordx4 v[8:11], v[26:27], off
	global_load_dwordx4 v[12:15], v[26:27], off offset:16
	s_waitcnt vmcnt(1)
	v_sub_f32_e32 v9, v9, v16
	v_sub_f32_e32 v8, v8, v16
	v_sub_f32_e32 v11, v11, v16
	v_sub_f32_e32 v10, v10, v16
	s_waitcnt vmcnt(0)
	v_sub_f32_e32 v13, v13, v16
	v_sub_f32_e32 v12, v12, v16
	v_sub_f32_e32 v15, v15, v16
	v_sub_f32_e32 v14, v14, v16
	v_pk_mul_f32 v[10:11], v[16:17], v[10:11] op_sel:[1,0]
	v_pk_mul_f32 v[8:9], v[16:17], v[8:9] op_sel:[1,0]
	v_pk_mul_f32 v[14:15], v[16:17], v[14:15] op_sel:[1,0]
	v_pk_mul_f32 v[12:13], v[16:17], v[12:13] op_sel:[1,0]
	v_pk_fma_f32 v[8:9], v[78:79], v[8:9], v[110:111]
	v_pk_fma_f32 v[10:11], v[74:75], v[10:11], v[94:95]
	v_pk_fma_f32 v[12:13], v[86:87], v[12:13], v[118:119]
	v_pk_fma_f32 v[14:15], v[76:77], v[14:15], v[102:103]
	v_pk_fma_f32 v[6:7], v[6:7], v[70:71], v[10:11]
	v_pk_fma_f32 v[4:5], v[4:5], v[68:69], v[8:9]
	v_pk_fma_f32 v[2:3], v[2:3], v[66:67], v[14:15]
	v_pk_fma_f32 v[0:1], v[0:1], v[64:65], v[12:13]
	global_store_dwordx4 v[72:73], v[4:7], off offset:512
	global_store_dwordx4 v[72:73], v[0:3], off offset:528
	s_cbranch_vccnz .LBB0_1316
	s_andn2_b64 vcc, exec, s[6:7]
	s_cbranch_vccnz .LBB0_1315
	s_barrier
	s_branch .LBB0_1315

; __global__ void __launch_bounds__(NWAVES * 64, 2) mk_fwd(Args args) {
;     extern __shared__ __attribute__((aligned(16))) unsigned char lds[];
	.amdhsa_kernel _Z6mk_fwd4Args
		.amdhsa_group_segment_fixed_size 0
		.amdhsa_private_segment_fixed_size 0
		.amdhsa_kernarg_size 488
		.amdhsa_user_sgpr_count 2
		.amdhsa_user_sgpr_dispatch_ptr 0
		.amdhsa_user_sgpr_queue_ptr 0
		.amdhsa_user_sgpr_kernarg_segment_ptr 1
		.amdhsa_user_sgpr_dispatch_id 0
		.amdhsa_user_sgpr_kernarg_preload_length 0
		.amdhsa_user_sgpr_kernarg_preload_offset 0
		.amdhsa_user_sgpr_private_segment_size 0
		.amdhsa_uses_dynamic_stack 0
		.amdhsa_enable_private_segment 0
		.amdhsa_system_sgpr_workgroup_id_x 1
		.amdhsa_system_sgpr_workgroup_id_y 0
		.amdhsa_system_sgpr_workgroup_id_z 0
		.amdhsa_system_sgpr_workgroup_info 0
		.amdhsa_system_vgpr_workitem_id 0
		.amdhsa_next_free_vgpr 256
		.amdhsa_next_free_sgpr 102
		.amdhsa_accum_offset 256
		.amdhsa_reserve_vcc 1
		.amdhsa_float_round_mode_32 0
		.amdhsa_float_round_mode_16_64 0
		.amdhsa_float_denorm_mode_32 3
		.amdhsa_float_denorm_mode_16_64 3
		.amdhsa_dx10_clamp 1
		.amdhsa_ieee_mode 1
		.amdhsa_fp16_overflow 0
		.amdhsa_tg_split 0
		.amdhsa_exception_fp_ieee_invalid_op 0
		.amdhsa_exception_fp_denorm_src 0
		.amdhsa_exception_fp_ieee_div_zero 0
		.amdhsa_exception_fp_ieee_overflow 0
		.amdhsa_exception_fp_ieee_underflow 0
		.amdhsa_exception_fp_ieee_inexact 0
		.amdhsa_exception_int_div_zero 0
	.end_amdhsa_kernel

; __global__ void __launch_bounds__(NWAVES * 64, 2) mk_fwd(Args args) {
;     extern __shared__ __attribute__((aligned(16))) unsigned char lds[];
amdhsa.kernels:
  - .agpr_count:     0
    .args:
      - .offset:         0
        .size:           232
        .value_kind:     by_value
      - .offset:         232
        .size:           4
        .value_kind:     hidden_block_count_x
      - .offset:         236
        .size:           4
        .value_kind:     hidden_block_count_y
      - .offset:         240
        .size:           4
        .value_kind:     hidden_block_count_z
      - .offset:         244
        .size:           2
        .value_kind:     hidden_group_size_x
      - .offset:         246
        .size:           2
        .value_kind:     hidden_group_size_y
      - .offset:         248
        .size:           2
        .value_kind:     hidden_group_size_z
      - .offset:         250
        .size:           2
        .value_kind:     hidden_remainder_x
      - .offset:         252
        .size:           2
        .value_kind:     hidden_remainder_y
      - .offset:         254
        .size:           2
        .value_kind:     hidden_remainder_z
      - .offset:         272
        .size:           8
        .value_kind:     hidden_global_offset_x
      - .offset:         280
        .size:           8
        .value_kind:     hidden_global_offset_y
      - .offset:         288
        .size:           8
        .value_kind:     hidden_global_offset_z
      - .offset:         296
        .size:           2
        .value_kind:     hidden_grid_dims
      - .offset:         352
        .size:           4
        .value_kind:     hidden_dynamic_lds_size
    .group_segment_fixed_size: 0
    .kernarg_segment_align: 8
    .kernarg_segment_size: 488
    .language:       OpenCL C
    .language_version:
      - 2
      - 0
    .max_flat_workgroup_size: 512
    .name:           _Z6mk_fwd4Args
    .private_segment_fixed_size: 0
    .sgpr_count:     108
    .sgpr_spill_count: 84
    .symbol:         _Z6mk_fwd4Args.kd
    .uniform_work_group_size: 1
    .uses_dynamic_stack: false
    .vgpr_count:     256
    .vgpr_spill_count: 0
    .wavefront_size: 64
